# baseline (speedup 1.0000x reference)
; DI int my_tid() { int t = threadIdx.x; asm volatile("" : "+v"(t)); return t; }
; #define PEER_SWAP() do { _Pragma("unroll") for (int q_ = 0; q_ < 8; ++q_) _Pragma("unroll") for (int c_ = 0; c_ < 4; ++c_) { \
;             const auto r_ = __builtin_amdgcn_permlane32_swap(ra[q_][c_], rb[q_][c_], false, false); ucur[q_][c_] = r_[0]; vcur[q_][c_] = r_[1]; } } while (0)
; #define PEER_LOADREC_MEM(ep_) do { \
;         _Pragma("unroll") for (int q_ = 0; q_ < 8; ++q_) { \
;             const int ia_ = __builtin_amdgcn_readfirstlane((ep_)[2 * q_]), ib_ = __builtin_amdgcn_readfirstlane((ep_)[2 * q_ + 1]); \
;             ra[q_] = *(const u32x4*)(REC + (size_t)ia_ * 1024); rb[q_] = *(const u32x4*)(REC + (size_t)ib_ * 1024); } } while (0)
; #define PEER_NEXTOPS(t_) do { const u32x4* xr_ = (const u32x4*)(xb + (size_t)(t_) * PA + 32 * l5); xq[0] = xr_[0]; xq[1] = xr_[1]; xq[2] = xr_[2]; xq[3] = xr_[3]; \
;         ivq0 = eidx[(size_t)(t_) * 128 + lane]; ivq1 = eidx[(size_t)(t_) * 128 + 64 + lane]; gvq0 = gate[(size_t)(t_) * 128 + lane]; gvq1 = gate[(size_t)(t_) * 128 + 64 + lane]; } while (0)
; DI void peer_phase(const Params& p, int layer, bool dry) {
;     unsigned char* ws = p.ws;
;     const int lane = my_tid() & 63, wid = __builtin_amdgcn_readfirstlane(my_tid() >> 6);
;     const int gw = blockIdx.x * NWV + wid, nw = gridDim.x * NWV;
;     const unsigned char* U6 = ws + OFF_U; const float* SU = (const float*)(ws + OFF_U + 16777216);
;     const unsigned char* V6 = ws + OFF_V; const float* SV = (const float*)(ws + OFF_V + 16777216);
;     bf16_t* xb = (bf16_t*)(ws + OFF_R2);
;     const float* x1f = (const float*)(ws + OFF_R3);
;     const int* eidx = (const int*)(ws + OFF_EIDX);
;     const float* gate = (const float*)(ws + OFF_GATE);
;     const float* g2 = p.in[16] + layer * DM;
;     const float* b2 = p.in[17] + layer * DM;
;     const int hi = lane >> 5, l5 = lane & 31, b4 = (lane >> 4) & 1, b3 = (lane >> 3) & 1, esel = 4 * b4 + 2 * b3 + hi;
;     u32x4 ucur[8], vcur[8], ra[8], rb[8];
;     const int b2_ = (lane >> 2) & 1, esel16 = 8 * b4 + 4 * b3 + 2 * b2_ + hi;
;     const unsigned char* REC = ws + OFF_U + 16 * lane;
;     ...
;     if (gw < T_TOK) {
;         PEER_LOADREC_MEM(eidx + (size_t)gw * 128);
;         PEER_SWAP();
;     }
;     u32x4 xq[4]; int ivq0 = 0, ivq1 = 0; float gvq0 = 0.f, gvq1 = 0.f;
;     ...
;     if (gw < T_TOK) PEER_NEXTOPS(gw);
.LBB0_28:
	v_readlane_b32 s0, v252, 34
	s_ashr_i32 s42, s0, 3
	s_and_b32 s28, s0, 7
	s_cmp_lt_u32 s0, 8
	v_readlane_b32 s1, v252, 35
	s_cselect_b64 s[2:3], -1, 0
	s_cmp_gt_u32 s0, 7
	v_writelane_b32 v250, s2, 21
	s_cselect_b64 s[12:13], -1, 0
	s_cmp_lt_i32 s28, 4
	s_mov_b64 s[0:1], -1
	v_writelane_b32 v250, s3, 22
	s_cbranch_scc1 .LBB0_130
	s_lshl_b32 s14, s42, 10
	s_ashr_i32 s15, s14, 31
	s_cmp_lt_i32 s28, 6
	s_cbranch_scc1 .LBB0_85
	s_cmp_gt_i32 s28, 6
	s_cbranch_scc0 .LBB0_51
	v_mov_b32_e32 v80, v192
	v_mov_b32_e32 v0, v192
	v_readlane_b32 s1, v252, 36
	v_readfirstlane_b32 s0, v0
	s_ashr_i32 s0, s0, 6
	s_mul_i32 s32, s0, 0x4100
	s_lshl_b32 s45, s0, 11
	s_add_i32 s45, s45, 0x20800
	v_writelane_b32 v250, s45, 42
	s_add_i32 s10, s0, s1
	s_mov_b32 s43, s28
	s_cmpk_gt_i32 s10, 0x7fff
	s_cbranch_scc1 .LBB0_50
	s_waitcnt vmcnt(0)
	v_and_b32_e32 v96, 63, v80
	v_readlane_b32 s0, v252, 37
	v_readlane_b32 s16, v250, 1
	v_lshlrev_b32_e32 v128, 4, v96
	v_lshlrev_b32_e32 v232, 4, v96
	v_lshrrev_b32_e32 v233, 5, v96
	v_mul_u32_u24_e32 v233, 0x410, v233
	v_and_b32_e32 v196, 31, v96
	v_readlane_b32 s12, v252, 37
	v_lshl_add_u32 v233, v196, 4, v233
	v_readlane_b32 s13, v252, 38
	s_and_b32 s44, s12, 0xffffff
	s_andn2_b32 s12, s12, 0xffffff
	v_add_u32_e32 v232, s44, v232
	v_add_u32_e32 v233, s32, v233
	v_and_b32_e32 v196, 15, v96
	v_mul_u32_u24_e32 v196, 0x410, v196
	v_lshrrev_b32_e32 v210, 4, v96
	v_lshl_add_u32 v196, v210, 4, v196
	v_add_u32_e32 v196, s32, v196
	v_lshlrev_b32_e32 v210, 6, v210
	v_add_u32_e32 v210, s45, v210
	s_mov_b32 s45, s13
	v_readlane_b32 s1, v252, 38
	s_lshl_b64 s[2:3], s[14:15], 2
	v_readlane_b32 s18, v250, 3
	v_lshl_add_u64 v[98:99], s[0:1], 0, v[128:129]
	v_readlane_b32 s19, v250, 4
	s_add_u32 s0, s18, s2
	s_addc_u32 s1, s19, s3
	v_readlane_b32 s17, v250, 2
	s_add_u32 s18, s16, s2
	s_addc_u32 s19, s17, s3
	s_cmp_eq_u32 s42, 1
	s_cselect_b64 s[16:17], -1, 0
	s_ashr_i32 s11, s10, 31
	s_lshl_b64 s[2:3], s[10:11], 9
	v_bfe_u32 v85, v80, 4, 1
	v_bfe_u32 v84, v80, 3, 1
	v_bfe_u32 v83, v80, 2, 1
	s_add_u32 s4, s92, s2
	v_lshlrev_b32_e32 v0, 3, v85
	v_lshlrev_b32_e32 v1, 2, v84
	v_lshlrev_b32_e32 v2, 1, v83
	s_addc_u32 s5, s93, s3
	v_or3_b32 v81, v0, v1, v2
	v_lshlrev_b32_e32 v64, 5, v80
	v_and_b32_e32 v92, 0x3e0, v64
	v_lshl_or_b32 v86, v96, 2, s2
	v_mov_b32_e32 v87, s3
	v_lshlrev_b32_e32 v128, 1, v92
	v_lshl_add_u64 v[88:89], s[92:93], 0, v[86:87]
	v_cmp_lt_i32_e32 vcc, v199, v200
	v_bfe_u32 v82, v80, 5, 1
	v_lshl_add_u64 v[100:101], s[88:89], 0, v[128:129]
	v_and_or_b32 v80, v80, 32, v198
	v_readlane_b32 s20, v250, 5
	v_readlane_b32 s21, v250, 6
	v_lshrrev_b32_e32 v216, 3, v80
	v_cmp_gt_u32_e64 s[8:9], 32, v96
	v_or_b32_e32 v217, 8, v216
	v_or_b32_e32 v219, 16, v216
	v_or_b32_e32 v220, 24, v216
	v_or_b32_e32 v221, 32, v216
	v_or_b32_e32 v222, 40, v216
	v_or_b32_e32 v223, 48, v216
	v_or_b32_e32 v224, 56, v216
	v_readlane_b32 s22, v250, 7
	v_readlane_b32 s23, v250, 8
	global_load_dword v218, v[88:89], off
	v_or_b32_e32 v88, 0x100, v86
	v_mov_b32_e32 v89, s3
	v_lshl_add_u64 v[90:91], s[92:93], 0, v[88:89]
	v_lshl_add_u64 v[86:87], s[76:77], 0, v[86:87]
	global_load_dword v225, v[90:91], off
	global_load_dword v226, v[86:87], off
	v_lshl_add_u64 v[86:87], s[76:77], 0, v[88:89]
	global_load_dword v227, v[86:87], off
	s_waitcnt vmcnt(0)
	v_lshrrev_b32_e32 v64, 11, v218
	v_lshrrev_b32_e32 v65, 11, v225
	s_mov_b32 s36, 0
	v_cmp_eq_u32_e64 s[28:29], 0, v64
	v_cmp_eq_u32_e64 s[30:31], 0, v65
	s_bcnt1_i32_b64 s34, s[28:29]
	s_bcnt1_i32_b64 s35, s[30:31]
	v_mbcnt_lo_u32_b32 v68, s28, 0
	v_mbcnt_hi_u32_b32 v68, s29, v68
	v_mbcnt_lo_u32_b32 v69, s30, 0
	v_mbcnt_hi_u32_b32 v69, s31, v69
	v_add_u32_e32 v68, s36, v68
	s_add_i32 s36, s36, s34
	v_add_u32_e32 v69, s36, v69
	s_add_i32 s36, s36, s35
	v_cndmask_b32_e64 v66, v66, v68, s[28:29]
	v_cndmask_b32_e64 v67, v67, v69, s[30:31]
	v_cmp_eq_u32_e64 s[28:29], 1, v64
	v_cmp_eq_u32_e64 s[30:31], 1, v65
	s_bcnt1_i32_b64 s34, s[28:29]
	s_bcnt1_i32_b64 s35, s[30:31]
	v_mbcnt_lo_u32_b32 v68, s28, 0
	v_mbcnt_hi_u32_b32 v68, s29, v68
	v_mbcnt_lo_u32_b32 v69, s30, 0
	v_mbcnt_hi_u32_b32 v69, s31, v69
	v_add_u32_e32 v68, s36, v68
	s_add_i32 s36, s36, s34
	v_add_u32_e32 v69, s36, v69
	s_add_i32 s36, s36, s35
	v_cndmask_b32_e64 v66, v66, v68, s[28:29]
	v_cndmask_b32_e64 v67, v67, v69, s[30:31]
	v_cmp_eq_u32_e64 s[28:29], 2, v64
	v_cmp_eq_u32_e64 s[30:31], 2, v65
	s_bcnt1_i32_b64 s34, s[28:29]
	s_bcnt1_i32_b64 s35, s[30:31]
	v_mbcnt_lo_u32_b32 v68, s28, 0
	v_mbcnt_hi_u32_b32 v68, s29, v68
	v_mbcnt_lo_u32_b32 v69, s30, 0
	v_mbcnt_hi_u32_b32 v69, s31, v69
	v_add_u32_e32 v68, s36, v68
	s_add_i32 s36, s36, s34
	v_add_u32_e32 v69, s36, v69
	s_add_i32 s36, s36, s35
	v_cndmask_b32_e64 v66, v66, v68, s[28:29]
	v_cndmask_b32_e64 v67, v67, v69, s[30:31]
	v_cmp_eq_u32_e64 s[28:29], 3, v64
	v_cmp_eq_u32_e64 s[30:31], 3, v65
	s_bcnt1_i32_b64 s34, s[28:29]
	s_bcnt1_i32_b64 s35, s[30:31]
	v_mbcnt_lo_u32_b32 v68, s28, 0
	v_mbcnt_hi_u32_b32 v68, s29, v68
	v_mbcnt_lo_u32_b32 v69, s30, 0
	v_mbcnt_hi_u32_b32 v69, s31, v69
	v_add_u32_e32 v68, s36, v68
	s_add_i32 s36, s36, s34
	v_add_u32_e32 v69, s36, v69
	s_add_i32 s36, s36, s35
	v_cndmask_b32_e64 v66, v66, v68, s[28:29]
	v_cndmask_b32_e64 v67, v67, v69, s[30:31]
	v_cmp_eq_u32_e64 s[28:29], 4, v64
	v_cmp_eq_u32_e64 s[30:31], 4, v65
	s_bcnt1_i32_b64 s34, s[28:29]
	s_bcnt1_i32_b64 s35, s[30:31]
	v_mbcnt_lo_u32_b32 v68, s28, 0
	v_mbcnt_hi_u32_b32 v68, s29, v68
	v_mbcnt_lo_u32_b32 v69, s30, 0
	v_mbcnt_hi_u32_b32 v69, s31, v69
	v_add_u32_e32 v68, s36, v68
	s_add_i32 s36, s36, s34
	v_add_u32_e32 v69, s36, v69
	s_add_i32 s36, s36, s35
	v_cndmask_b32_e64 v66, v66, v68, s[28:29]
; #define PEER_SWAP() do { _Pragma("unroll") for (int q_ = 0; q_ < 8; ++q_) _Pragma("unroll") for (int c_ = 0; c_ < 4; ++c_) { \
;             const auto r_ = __builtin_amdgcn_permlane32_swap(ra[q_][c_], rb[q_][c_], false, false); ucur[q_][c_] = r_[0]; vcur[q_][c_] = r_[1]; } } while (0)
; #define PEER_LOADREC_MEM(ep_) do { \
;         _Pragma("unroll") for (int q_ = 0; q_ < 8; ++q_) { \
;             const int ia_ = __builtin_amdgcn_readfirstlane((ep_)[2 * q_]), ib_ = __builtin_amdgcn_readfirstlane((ep_)[2 * q_ + 1]); \
;             ra[q_] = *(const u32x4*)(REC + (size_t)ia_ * 1024); rb[q_] = *(const u32x4*)(REC + (size_t)ib_ * 1024); } } while (0)
; #define PEER_NEXTOPS(t_) do { const u32x4* xr_ = (const u32x4*)(xb + (size_t)(t_) * PA + 32 * l5); xq[0] = xr_[0]; xq[1] = xr_[1]; xq[2] = xr_[2]; xq[3] = xr_[3]; \
;         ivq0 = eidx[(size_t)(t_) * 128 + lane]; ivq1 = eidx[(size_t)(t_) * 128 + 64 + lane]; gvq0 = gate[(size_t)(t_) * 128 + lane]; gvq1 = gate[(size_t)(t_) * 128 + 64 + lane]; } while (0)
; DI void peer_phase(const Params& p, int layer, bool dry) {
;     ...
;     if (gw < T_TOK) {
;         PEER_LOADREC_MEM(eidx + (size_t)gw * 128);
;         PEER_SWAP();
;     }
;     u32x4 xq[4]; int ivq0 = 0, ivq1 = 0; float gvq0 = 0.f, gvq1 = 0.f;
;     ...
;     if (gw < T_TOK) PEER_NEXTOPS(gw);
	v_cndmask_b32_e64 v67, v67, v69, s[30:31]
	v_cmp_eq_u32_e64 s[28:29], 5, v64
	v_cmp_eq_u32_e64 s[30:31], 5, v65
	s_bcnt1_i32_b64 s34, s[28:29]
	s_bcnt1_i32_b64 s35, s[30:31]
	v_mbcnt_lo_u32_b32 v68, s28, 0
	v_mbcnt_hi_u32_b32 v68, s29, v68
	v_mbcnt_lo_u32_b32 v69, s30, 0
	v_mbcnt_hi_u32_b32 v69, s31, v69
	v_add_u32_e32 v68, s36, v68
	s_add_i32 s36, s36, s34
	v_add_u32_e32 v69, s36, v69
	s_add_i32 s36, s36, s35
	v_cndmask_b32_e64 v66, v66, v68, s[28:29]
	v_cndmask_b32_e64 v67, v67, v69, s[30:31]
	v_cmp_eq_u32_e64 s[28:29], 6, v64
	v_cmp_eq_u32_e64 s[30:31], 6, v65
	s_bcnt1_i32_b64 s34, s[28:29]
	s_bcnt1_i32_b64 s35, s[30:31]
	v_mbcnt_lo_u32_b32 v68, s28, 0
	v_mbcnt_hi_u32_b32 v68, s29, v68
	v_mbcnt_lo_u32_b32 v69, s30, 0
	v_mbcnt_hi_u32_b32 v69, s31, v69
	v_add_u32_e32 v68, s36, v68
	s_add_i32 s36, s36, s34
	v_add_u32_e32 v69, s36, v69
	s_add_i32 s36, s36, s35
	v_cndmask_b32_e64 v66, v66, v68, s[28:29]
	v_cndmask_b32_e64 v67, v67, v69, s[30:31]
	v_cmp_eq_u32_e64 s[28:29], 7, v64
	v_cmp_eq_u32_e64 s[30:31], 7, v65
	s_bcnt1_i32_b64 s34, s[28:29]
	s_bcnt1_i32_b64 s35, s[30:31]
	v_mbcnt_lo_u32_b32 v68, s28, 0
	v_mbcnt_hi_u32_b32 v68, s29, v68
	v_mbcnt_lo_u32_b32 v69, s30, 0
	v_mbcnt_hi_u32_b32 v69, s31, v69
	v_add_u32_e32 v68, s36, v68
	s_add_i32 s36, s36, s34
	v_add_u32_e32 v69, s36, v69
	s_add_i32 s36, s36, s35
	v_cndmask_b32_e64 v66, v66, v68, s[28:29]
	v_cndmask_b32_e64 v67, v67, v69, s[30:31]
	v_lshl_add_u32 v71, v66, 2, s32
	v_lshl_add_u32 v72, v67, 2, s32
	v_lshl_add_u32 v70, v96, 2, s32
	ds_write_b32 v71, v218
	ds_write_b32 v72, v225
	ds_write_b32 v71, v226 offset:512
	ds_write_b32 v72, v227 offset:512
	s_waitcnt lgkmcnt(0)
	ds_read_b32 v218, v70
	ds_read_b32 v225, v70 offset:256
	ds_read_b32 v226, v70 offset:512
	ds_read_b32 v227, v70 offset:768
	s_waitcnt lgkmcnt(0)
	v_readlane_b32 s44, v218, 0
	s_mov_b32 m0, s32
	s_lshl_b32 s44, s44, 10
	s_or_b32 s44, s12, s44
	global_load_lds_dwordx4 v232, s[44:45] sc1
	v_readlane_b32 s44, v218, 1
	s_add_i32 m0, s32, 0x410
	s_lshl_b32 s44, s44, 10
	s_or_b32 s44, s12, s44
	global_load_lds_dwordx4 v232, s[44:45] sc1
	v_readlane_b32 s44, v218, 2
	s_add_i32 m0, s32, 0x820
	s_lshl_b32 s44, s44, 10
	s_or_b32 s44, s12, s44
	global_load_lds_dwordx4 v232, s[44:45] sc1
	v_readlane_b32 s44, v218, 3
	s_add_i32 m0, s32, 0xc30
	s_lshl_b32 s44, s44, 10
	s_or_b32 s44, s12, s44
	global_load_lds_dwordx4 v232, s[44:45] sc1
	v_readlane_b32 s44, v218, 4
	s_add_i32 m0, s32, 0x1040
	s_lshl_b32 s44, s44, 10
	s_or_b32 s44, s12, s44
	global_load_lds_dwordx4 v232, s[44:45] sc1
	v_readlane_b32 s44, v218, 5
	s_add_i32 m0, s32, 0x1450
	s_lshl_b32 s44, s44, 10
	s_or_b32 s44, s12, s44
	global_load_lds_dwordx4 v232, s[44:45] sc1
	v_readlane_b32 s44, v218, 6
	s_add_i32 m0, s32, 0x1860
	s_lshl_b32 s44, s44, 10
	s_or_b32 s44, s12, s44
	global_load_lds_dwordx4 v232, s[44:45] sc1
	v_readlane_b32 s44, v218, 7
	s_add_i32 m0, s32, 0x1c70
	s_lshl_b32 s44, s44, 10
	s_or_b32 s44, s12, s44
	global_load_lds_dwordx4 v232, s[44:45] sc1
	v_readlane_b32 s44, v218, 8
	s_add_i32 m0, s32, 0x2080
	s_lshl_b32 s44, s44, 10
	s_or_b32 s44, s12, s44
	global_load_lds_dwordx4 v232, s[44:45] sc1
	v_readlane_b32 s44, v218, 9
	s_add_i32 m0, s32, 0x2490
	s_lshl_b32 s44, s44, 10
	s_or_b32 s44, s12, s44
	global_load_lds_dwordx4 v232, s[44:45] sc1
	v_readlane_b32 s44, v218, 10
	s_add_i32 m0, s32, 0x28a0
	s_lshl_b32 s44, s44, 10
	s_or_b32 s44, s12, s44
	global_load_lds_dwordx4 v232, s[44:45] sc1
	v_readlane_b32 s44, v218, 11
	s_add_i32 m0, s32, 0x2cb0
	s_lshl_b32 s44, s44, 10
	s_or_b32 s44, s12, s44
	global_load_lds_dwordx4 v232, s[44:45] sc1
	v_readlane_b32 s44, v218, 12
	s_add_i32 m0, s32, 0x30c0
	s_lshl_b32 s44, s44, 10
	s_or_b32 s44, s12, s44
	global_load_lds_dwordx4 v232, s[44:45] sc1
	v_readlane_b32 s44, v218, 13
	s_add_i32 m0, s32, 0x34d0
	s_lshl_b32 s44, s44, 10
	s_or_b32 s44, s12, s44
	global_load_lds_dwordx4 v232, s[44:45] sc1
	v_readlane_b32 s44, v218, 14
	s_add_i32 m0, s32, 0x38e0
	s_lshl_b32 s44, s44, 10
	s_or_b32 s44, s12, s44
	global_load_lds_dwordx4 v232, s[44:45] sc1
	v_readlane_b32 s44, v218, 15
	s_add_i32 m0, s32, 0x3cf0
	s_lshl_b32 s44, s44, 10
	s_or_b32 s44, s12, s44
	global_load_lds_dwordx4 v232, s[44:45] sc1
	s_lshl_b64 s[4:5], s[10:11], 11
	s_add_u32 s4, s88, s4
	s_addc_u32 s5, s89, s5
	global_load_dwordx4 v[64:67], v128, s[4:5] offset:48
	global_load_dwordx4 v[72:75], v128, s[4:5] offset:32
	global_load_dwordx4 v[68:71], v128, s[4:5] offset:16
	global_load_dwordx4 v[76:79], v128, s[4:5]
	v_cmp_eq_u32_e64 s[2:3], 0, v85
	v_cndmask_b32_e32 v85, v197, v199, vcc
	v_cmp_lt_i32_e32 vcc, v201, v200
	v_cmp_eq_u32_e64 s[4:5], 0, v84
	v_cmp_eq_u32_e64 s[6:7], 0, v83
	v_cndmask_b32_e32 v84, v197, v201, vcc
	v_cmp_lt_i32_e32 vcc, v202, v200
	v_lshlrev_b32_e32 v97, 2, v85
	v_lshlrev_b32_e32 v211, 2, v84
	v_cndmask_b32_e32 v83, v197, v202, vcc
	v_cmp_lt_i32_e32 vcc, v203, v200
	v_lshlrev_b32_e32 v212, 2, v83
	v_mov_b32_e32 v85, v129
	v_cndmask_b32_e32 v83, v197, v203, vcc
	v_cmp_lt_i32_e32 vcc, v204, v200
	v_lshlrev_b32_e32 v213, 2, v83
	v_cndmask_b32_e32 v83, v197, v204, vcc
	v_cmp_lt_i32_e32 vcc, v205, v200
	v_lshlrev_b32_e32 v214, 2, v83
	v_cndmask_b32_e32 v83, v197, v205, vcc
	v_lshlrev_b32_e32 v215, 2, v83
	v_lshl_or_b32 v83, v82, 4, v92
	v_lshlrev_b32_e32 v128, 2, v83
	v_lshl_add_u64 v[104:105], s[0:1], 0, v[128:129]
	v_readlane_b32 s0, v252, 39
	v_lshlrev_b32_e32 v84, 1, v83
	v_readlane_b32 s1, v252, 40
	v_lshl_add_u64 v[102:103], s[18:19], 0, v[128:129]
	v_lshl_add_u64 v[106:107], s[88:89], 0, v[84:85]
	v_lshl_add_u64 v[108:109], s[0:1], 0, v[84:85]
	v_lshl_add_u64 v[110:111], s[20:21], 0, v[128:129]
	v_and_b32_e32 v128, 15, v96
	s_waitcnt vmcnt(4)
	ds_read_b128 v[60:63], v196
	ds_read_b128 v[28:31], v233 offset:512
	ds_read_b128 v[56:59], v196 offset:64
	ds_read_b128 v[24:27], v233 offset:2592
	ds_read_b128 v[52:55], v196 offset:128
	ds_read_b128 v[20:23], v233 offset:4672
	ds_read_b128 v[48:51], v196 offset:192
	ds_read_b128 v[16:19], v233 offset:6752
	ds_read_b128 v[44:47], v196 offset:256
	ds_read_b128 v[12:15], v233 offset:8832
	ds_read_b128 v[40:43], v196 offset:320
	ds_read_b128 v[8:11], v233 offset:10912
	ds_read_b128 v[36:39], v196 offset:384
	ds_read_b128 v[4:7], v233 offset:12992
	ds_read_b128 v[32:35], v196 offset:448
	ds_read_b128 v[0:3], v233 offset:15072
	s_waitcnt lgkmcnt(0)
	global_load_dwordx4 v[234:237], v[102:103], off
	global_load_dwordx4 v[238:241], v[102:103], off offset:16
	global_load_dwordx4 v[242:245], v[102:103], off offset:32
	global_load_dwordx4 v[246:249], v[102:103], off offset:48
	global_load_dwordx4 v[130:133], v[104:105], off
	global_load_dwordx4 v[134:137], v[104:105], off offset:16
	global_load_dwordx4 v[138:141], v[104:105], off offset:32
	global_load_dwordx4 v[206:209], v[104:105], off offset:48
	s_branch .LBB0_34

; DI float dotU(const URow& q, const f32x2 (&x2)[16]) { return dot32r(dec6(q), x2); }
; #define PEER_LOADREC_FROM(isrc_, lb_) do { \
;         _Pragma("unroll") for (int q_ = 0; q_ < 8; ++q_) { \
;             const int ia_ = __builtin_amdgcn_readlane(isrc_, (lb_) + 2 * q_), ib_ = __builtin_amdgcn_readlane(isrc_, (lb_) + 2 * q_ + 1); \
;             ra[q_] = *(const u32x4*)(REC + (size_t)ia_ * 1024); rb[q_] = *(const u32x4*)(REC + (size_t)ib_ * 1024); } } while (0)
; #define PEER_LOADREC_MEM(ep_) do { \
;         _Pragma("unroll") for (int q_ = 0; q_ < 8; ++q_) { \
;             const int ia_ = __builtin_amdgcn_readfirstlane((ep_)[2 * q_]), ib_ = __builtin_amdgcn_readfirstlane((ep_)[2 * q_ + 1]); \
;             ra[q_] = *(const u32x4*)(REC + (size_t)ia_ * 1024); rb[q_] = *(const u32x4*)(REC + (size_t)ib_ * 1024); } } while (0)
; DI float dotU(const URow& q, const f32x2 (&x2)[16]) {
;     f32x2 a0 = {0.f, 0.f}, a1 = {0.f, 0.f};
; #pragma unroll
;     for (int d = 0; d < 4; ++d) {
;         a0 += __builtin_amdgcn_cvt_scalef32_pk_f32_fp4(q[d], 1.0f, 0) * x2[4 * d];     a1 += __builtin_amdgcn_cvt_scalef32_pk_f32_fp4(q[d], 1.0f, 1) * x2[4 * d + 1];
;         a0 += __builtin_amdgcn_cvt_scalef32_pk_f32_fp4(q[d], 1.0f, 2) * x2[4 * d + 2]; a1 += __builtin_amdgcn_cvt_scalef32_pk_f32_fp4(q[d], 1.0f, 3) * x2[4 * d + 3];
;     }
;     a0 += a1;
;     return a0.x + a0.y;
; }
; DI void peer_phase(const Params& p, int layer, bool dry) {
;     ...
;         for (int bt = 0; bt < 8; ++bt) {
;             if (bt < 7) { const int nb = bt + 1; const int isrc = (nb < 4) ? iv0 : iv1; const int lb = (nb & 3) * 16; PEER_LOADREC_FROM(isrc, lb); }
;             else PEER_LOADREC_MEM(eidx + (size_t)tn * 128);
;             const int myidx = __shfl((bt < 4) ? iv0 : iv1, (bt & 3) * 16 + esel16);
;             const float gsc = __shfl((bt < 4) ? gv0 : gv1, (bt & 3) * 16 + esel16) * SV[myidx], usc = SU[myidx];
;             float d[8];
; #pragma unroll
;             for (int q = 0; q < 8; ++q) d[q] = dotU(ucur[q], x2);
.LBB0_35:
	s_cmp_lt_u32 s11, 4
	s_cselect_b64 vcc, -1, 0
	v_or_b32_e32 v83, s60, v128
	s_waitcnt vmcnt(6)
	v_cndmask_b32_e32 v82, v225, v218, vcc
	v_lshlrev_b32_e32 v228, 2, v83
	ds_bpermute_b32 v90, v228, v82
	s_waitcnt lgkmcnt(0)
	v_ashrrev_i32_e32 v91, 31, v90
	v_lshlrev_b64 v[90:91], 2, v[90:91]
	v_lshl_add_u64 v[92:93], s[96:97], 0, v[90:91]
	v_lshl_add_u64 v[90:91], s[94:95], 0, v[90:91]
	global_load_dword v92, v[92:93], off
	s_nop 0
	global_load_dword v93, v[90:91], off
	s_mov_b32 m0, s32
	s_or_b32 s44, s12, s28
	global_load_lds_dwordx4 v232, s[44:45] sc1
	s_add_i32 m0, s32, 0x410
	s_or_b32 s44, s12, s26
	global_load_lds_dwordx4 v232, s[44:45] sc1
	s_add_i32 m0, s32, 0x820
	s_or_b32 s44, s12, s30
	global_load_lds_dwordx4 v232, s[44:45] sc1
	s_add_i32 m0, s32, 0xc30
	s_or_b32 s44, s12, s40
	global_load_lds_dwordx4 v232, s[44:45] sc1
	s_add_i32 m0, s32, 0x1040
	s_or_b32 s44, s12, s34
	global_load_lds_dwordx4 v232, s[44:45] sc1
	s_add_i32 m0, s32, 0x1450
	s_or_b32 s44, s12, s38
	global_load_lds_dwordx4 v232, s[44:45] sc1
	s_add_i32 m0, s32, 0x1860
	s_or_b32 s44, s12, s50
	global_load_lds_dwordx4 v232, s[44:45] sc1
	s_add_i32 m0, s32, 0x1c70
	s_or_b32 s44, s12, s48
	global_load_lds_dwordx4 v232, s[44:45] sc1
	s_add_i32 m0, s32, 0x2080
	s_or_b32 s44, s12, s54
	global_load_lds_dwordx4 v232, s[44:45] sc1
	s_add_i32 m0, s32, 0x2490
	s_or_b32 s44, s12, s46
	global_load_lds_dwordx4 v232, s[44:45] sc1
	s_add_i32 m0, s32, 0x28a0
	s_or_b32 s44, s12, s58
	global_load_lds_dwordx4 v232, s[44:45] sc1
	s_add_i32 m0, s32, 0x2cb0
	s_or_b32 s44, s12, s36
	global_load_lds_dwordx4 v232, s[44:45] sc1
	s_add_i32 m0, s32, 0x30c0
	s_or_b32 s44, s12, s62
	global_load_lds_dwordx4 v232, s[44:45] sc1
	s_add_i32 m0, s32, 0x34d0
	s_or_b32 s44, s12, s52
	global_load_lds_dwordx4 v232, s[44:45] sc1
	s_add_i32 m0, s32, 0x38e0
	s_or_b32 s44, s12, s64
	global_load_lds_dwordx4 v232, s[44:45] sc1
	s_add_i32 m0, s32, 0x3cf0
	s_or_b32 s44, s12, s56
	global_load_lds_dwordx4 v232, s[44:45] sc1
	ds_read_b128 v[64:67], v210
	ds_read_b128 v[68:71], v210 offset:16
	ds_read_b128 v[72:75], v210 offset:32
	ds_read_b128 v[76:79], v210 offset:48
	v_cvt_scalef32_pk_bf16_fp4 v84, v60, 1.0
	v_cvt_scalef32_pk_bf16_fp4 v85, v60, 1.0 op_sel:[1,0,0]
	v_cvt_scalef32_pk_bf16_fp4 v86, v60, 1.0 op_sel:[0,1,0]
	v_cvt_scalef32_pk_bf16_fp4 v87, v60, 1.0 op_sel:[1,1,0]
	v_cvt_scalef32_pk_bf16_fp4 v88, v61, 1.0
	v_cvt_scalef32_pk_bf16_fp4 v89, v61, 1.0 op_sel:[1,0,0]
	v_cvt_scalef32_pk_bf16_fp4 v90, v61, 1.0 op_sel:[0,1,0]
	v_cvt_scalef32_pk_bf16_fp4 v91, v61, 1.0 op_sel:[1,1,0]
	s_waitcnt lgkmcnt(2)
	v_mfma_f32_16x16x32_bf16 v[80:83], v[64:67], v[84:87], 0
	ds_read_b128 v[64:67], v210 offset:256
	v_cvt_scalef32_pk_bf16_fp4 v84, v62, 1.0
	v_cvt_scalef32_pk_bf16_fp4 v85, v62, 1.0 op_sel:[1,0,0]
	v_cvt_scalef32_pk_bf16_fp4 v86, v62, 1.0 op_sel:[0,1,0]
	v_cvt_scalef32_pk_bf16_fp4 v87, v62, 1.0 op_sel:[1,1,0]
	v_mfma_f32_16x16x32_bf16 v[80:83], v[68:71], v[88:91], v[80:83]
	ds_read_b128 v[68:71], v210 offset:272
	v_cvt_scalef32_pk_bf16_fp4 v88, v63, 1.0
	v_cvt_scalef32_pk_bf16_fp4 v89, v63, 1.0 op_sel:[1,0,0]
	v_cvt_scalef32_pk_bf16_fp4 v90, v63, 1.0 op_sel:[0,1,0]
	v_cvt_scalef32_pk_bf16_fp4 v91, v63, 1.0 op_sel:[1,1,0]
	s_waitcnt lgkmcnt(2)
	v_mfma_f32_16x16x32_bf16 v[80:83], v[72:75], v[84:87], v[80:83]
	ds_read_b128 v[72:75], v210 offset:288
	v_cvt_scalef32_pk_bf16_fp4 v84, v56, 1.0
	v_cvt_scalef32_pk_bf16_fp4 v85, v56, 1.0 op_sel:[1,0,0]
	v_cvt_scalef32_pk_bf16_fp4 v86, v56, 1.0 op_sel:[0,1,0]
	v_cvt_scalef32_pk_bf16_fp4 v87, v56, 1.0 op_sel:[1,1,0]
	v_mfma_f32_16x16x32_bf16 v[80:83], v[76:79], v[88:91], v[80:83]
	ds_read_b128 v[76:79], v210 offset:304
	v_cvt_scalef32_pk_bf16_fp4 v88, v57, 1.0
	v_cvt_scalef32_pk_bf16_fp4 v89, v57, 1.0 op_sel:[1,0,0]
	v_cvt_scalef32_pk_bf16_fp4 v90, v57, 1.0 op_sel:[0,1,0]
	v_cvt_scalef32_pk_bf16_fp4 v91, v57, 1.0 op_sel:[1,1,0]
	s_waitcnt lgkmcnt(2)
	v_mfma_f32_16x16x32_bf16 v[80:83], v[64:67], v[84:87], v[80:83]
	ds_read_b128 v[64:67], v210 offset:512
	v_cvt_scalef32_pk_bf16_fp4 v84, v58, 1.0
	v_cvt_scalef32_pk_bf16_fp4 v85, v58, 1.0 op_sel:[1,0,0]
	v_cvt_scalef32_pk_bf16_fp4 v86, v58, 1.0 op_sel:[0,1,0]
	v_cvt_scalef32_pk_bf16_fp4 v87, v58, 1.0 op_sel:[1,1,0]
	v_mfma_f32_16x16x32_bf16 v[80:83], v[68:71], v[88:91], v[80:83]
	ds_read_b128 v[68:71], v210 offset:528
	v_cvt_scalef32_pk_bf16_fp4 v88, v59, 1.0
	v_cvt_scalef32_pk_bf16_fp4 v89, v59, 1.0 op_sel:[1,0,0]
	v_cvt_scalef32_pk_bf16_fp4 v90, v59, 1.0 op_sel:[0,1,0]
	v_cvt_scalef32_pk_bf16_fp4 v91, v59, 1.0 op_sel:[1,1,0]
	s_waitcnt lgkmcnt(2)
	v_mfma_f32_16x16x32_bf16 v[80:83], v[72:75], v[84:87], v[80:83]
	ds_read_b128 v[72:75], v210 offset:544
	v_cvt_scalef32_pk_bf16_fp4 v84, v52, 1.0
	v_cvt_scalef32_pk_bf16_fp4 v85, v52, 1.0 op_sel:[1,0,0]
	v_cvt_scalef32_pk_bf16_fp4 v86, v52, 1.0 op_sel:[0,1,0]
	v_cvt_scalef32_pk_bf16_fp4 v87, v52, 1.0 op_sel:[1,1,0]
	v_mfma_f32_16x16x32_bf16 v[80:83], v[76:79], v[88:91], v[80:83]
	ds_read_b128 v[76:79], v210 offset:560
	v_cvt_scalef32_pk_bf16_fp4 v88, v53, 1.0
	v_cvt_scalef32_pk_bf16_fp4 v89, v53, 1.0 op_sel:[1,0,0]
	v_cvt_scalef32_pk_bf16_fp4 v90, v53, 1.0 op_sel:[0,1,0]
	v_cvt_scalef32_pk_bf16_fp4 v91, v53, 1.0 op_sel:[1,1,0]
	s_waitcnt lgkmcnt(2)
	v_mfma_f32_16x16x32_bf16 v[80:83], v[64:67], v[84:87], v[80:83]
	ds_read_b128 v[64:67], v210 offset:768
	v_cvt_scalef32_pk_bf16_fp4 v84, v54, 1.0
	v_cvt_scalef32_pk_bf16_fp4 v85, v54, 1.0 op_sel:[1,0,0]
	v_cvt_scalef32_pk_bf16_fp4 v86, v54, 1.0 op_sel:[0,1,0]
	v_cvt_scalef32_pk_bf16_fp4 v87, v54, 1.0 op_sel:[1,1,0]
	v_mfma_f32_16x16x32_bf16 v[80:83], v[68:71], v[88:91], v[80:83]
	ds_read_b128 v[68:71], v210 offset:784
	v_cvt_scalef32_pk_bf16_fp4 v88, v55, 1.0
	v_cvt_scalef32_pk_bf16_fp4 v89, v55, 1.0 op_sel:[1,0,0]
	v_cvt_scalef32_pk_bf16_fp4 v90, v55, 1.0 op_sel:[0,1,0]
	v_cvt_scalef32_pk_bf16_fp4 v91, v55, 1.0 op_sel:[1,1,0]
	s_waitcnt lgkmcnt(2)
; DI float dotU(const URow& q, const f32x2 (&x2)[16]) { return dot32r(dec6(q), x2); }
; DI float dotU(const URow& q, const f32x2 (&x2)[16]) {
;     f32x2 a0 = {0.f, 0.f}, a1 = {0.f, 0.f};
; #pragma unroll
;     for (int d = 0; d < 4; ++d) {
;         a0 += __builtin_amdgcn_cvt_scalef32_pk_f32_fp4(q[d], 1.0f, 0) * x2[4 * d];     a1 += __builtin_amdgcn_cvt_scalef32_pk_f32_fp4(q[d], 1.0f, 1) * x2[4 * d + 1];
;         a0 += __builtin_amdgcn_cvt_scalef32_pk_f32_fp4(q[d], 1.0f, 2) * x2[4 * d + 2]; a1 += __builtin_amdgcn_cvt_scalef32_pk_f32_fp4(q[d], 1.0f, 3) * x2[4 * d + 3];
;     }
;     a0 += a1;
;     return a0.x + a0.y;
; }
; DI void peer_phase(const Params& p, int layer, bool dry) {
;     ...
;             for (int q = 0; q < 8; ++q) d[q] = dotU(ucur[q], x2);
	v_mfma_f32_16x16x32_bf16 v[80:83], v[72:75], v[84:87], v[80:83]
	ds_read_b128 v[72:75], v210 offset:800
	v_cvt_scalef32_pk_bf16_fp4 v84, v48, 1.0
	v_cvt_scalef32_pk_bf16_fp4 v85, v48, 1.0 op_sel:[1,0,0]
	v_cvt_scalef32_pk_bf16_fp4 v86, v48, 1.0 op_sel:[0,1,0]
	v_cvt_scalef32_pk_bf16_fp4 v87, v48, 1.0 op_sel:[1,1,0]
	v_mfma_f32_16x16x32_bf16 v[80:83], v[76:79], v[88:91], v[80:83]
	ds_read_b128 v[76:79], v210 offset:816
	v_cvt_scalef32_pk_bf16_fp4 v88, v49, 1.0
	v_cvt_scalef32_pk_bf16_fp4 v89, v49, 1.0 op_sel:[1,0,0]
	v_cvt_scalef32_pk_bf16_fp4 v90, v49, 1.0 op_sel:[0,1,0]
	v_cvt_scalef32_pk_bf16_fp4 v91, v49, 1.0 op_sel:[1,1,0]
	s_waitcnt lgkmcnt(2)
	v_mfma_f32_16x16x32_bf16 v[80:83], v[64:67], v[84:87], v[80:83]
	ds_read_b128 v[64:67], v210 offset:1024
	v_cvt_scalef32_pk_bf16_fp4 v84, v50, 1.0
	v_cvt_scalef32_pk_bf16_fp4 v85, v50, 1.0 op_sel:[1,0,0]
	v_cvt_scalef32_pk_bf16_fp4 v86, v50, 1.0 op_sel:[0,1,0]
	v_cvt_scalef32_pk_bf16_fp4 v87, v50, 1.0 op_sel:[1,1,0]
	v_mfma_f32_16x16x32_bf16 v[80:83], v[68:71], v[88:91], v[80:83]
	ds_read_b128 v[68:71], v210 offset:1040
	v_cvt_scalef32_pk_bf16_fp4 v88, v51, 1.0
	v_cvt_scalef32_pk_bf16_fp4 v89, v51, 1.0 op_sel:[1,0,0]
	v_cvt_scalef32_pk_bf16_fp4 v90, v51, 1.0 op_sel:[0,1,0]
	v_cvt_scalef32_pk_bf16_fp4 v91, v51, 1.0 op_sel:[1,1,0]
	s_waitcnt lgkmcnt(2)
	v_mfma_f32_16x16x32_bf16 v[80:83], v[72:75], v[84:87], v[80:83]
	ds_read_b128 v[72:75], v210 offset:1056
	v_cvt_scalef32_pk_bf16_fp4 v84, v44, 1.0
	v_cvt_scalef32_pk_bf16_fp4 v85, v44, 1.0 op_sel:[1,0,0]
	v_cvt_scalef32_pk_bf16_fp4 v86, v44, 1.0 op_sel:[0,1,0]
	v_cvt_scalef32_pk_bf16_fp4 v87, v44, 1.0 op_sel:[1,1,0]
	v_mfma_f32_16x16x32_bf16 v[80:83], v[76:79], v[88:91], v[80:83]
	ds_read_b128 v[76:79], v210 offset:1072
	v_cvt_scalef32_pk_bf16_fp4 v88, v45, 1.0
	v_cvt_scalef32_pk_bf16_fp4 v89, v45, 1.0 op_sel:[1,0,0]
	v_cvt_scalef32_pk_bf16_fp4 v90, v45, 1.0 op_sel:[0,1,0]
	v_cvt_scalef32_pk_bf16_fp4 v91, v45, 1.0 op_sel:[1,1,0]
	s_waitcnt lgkmcnt(2)
	v_mfma_f32_16x16x32_bf16 v[80:83], v[64:67], v[84:87], v[80:83]
	ds_read_b128 v[64:67], v210 offset:1280
	v_cvt_scalef32_pk_bf16_fp4 v84, v46, 1.0
	v_cvt_scalef32_pk_bf16_fp4 v85, v46, 1.0 op_sel:[1,0,0]
	v_cvt_scalef32_pk_bf16_fp4 v86, v46, 1.0 op_sel:[0,1,0]
	v_cvt_scalef32_pk_bf16_fp4 v87, v46, 1.0 op_sel:[1,1,0]
	v_mfma_f32_16x16x32_bf16 v[80:83], v[68:71], v[88:91], v[80:83]
	ds_read_b128 v[68:71], v210 offset:1296
	v_cvt_scalef32_pk_bf16_fp4 v88, v47, 1.0
	v_cvt_scalef32_pk_bf16_fp4 v89, v47, 1.0 op_sel:[1,0,0]
	v_cvt_scalef32_pk_bf16_fp4 v90, v47, 1.0 op_sel:[0,1,0]
	v_cvt_scalef32_pk_bf16_fp4 v91, v47, 1.0 op_sel:[1,1,0]
	s_waitcnt lgkmcnt(2)
	v_mfma_f32_16x16x32_bf16 v[80:83], v[72:75], v[84:87], v[80:83]
	ds_read_b128 v[72:75], v210 offset:1312
	v_cvt_scalef32_pk_bf16_fp4 v84, v40, 1.0
	v_cvt_scalef32_pk_bf16_fp4 v85, v40, 1.0 op_sel:[1,0,0]
	v_cvt_scalef32_pk_bf16_fp4 v86, v40, 1.0 op_sel:[0,1,0]
	v_cvt_scalef32_pk_bf16_fp4 v87, v40, 1.0 op_sel:[1,1,0]
	v_mfma_f32_16x16x32_bf16 v[80:83], v[76:79], v[88:91], v[80:83]
	ds_read_b128 v[76:79], v210 offset:1328
	v_cvt_scalef32_pk_bf16_fp4 v88, v41, 1.0
	v_cvt_scalef32_pk_bf16_fp4 v89, v41, 1.0 op_sel:[1,0,0]
	v_cvt_scalef32_pk_bf16_fp4 v90, v41, 1.0 op_sel:[0,1,0]
	v_cvt_scalef32_pk_bf16_fp4 v91, v41, 1.0 op_sel:[1,1,0]
	s_waitcnt lgkmcnt(2)
	v_mfma_f32_16x16x32_bf16 v[80:83], v[64:67], v[84:87], v[80:83]
	ds_read_b128 v[64:67], v210 offset:1536
	v_cvt_scalef32_pk_bf16_fp4 v84, v42, 1.0
	v_cvt_scalef32_pk_bf16_fp4 v85, v42, 1.0 op_sel:[1,0,0]
	v_cvt_scalef32_pk_bf16_fp4 v86, v42, 1.0 op_sel:[0,1,0]
	v_cvt_scalef32_pk_bf16_fp4 v87, v42, 1.0 op_sel:[1,1,0]
	v_mfma_f32_16x16x32_bf16 v[80:83], v[68:71], v[88:91], v[80:83]
	ds_read_b128 v[68:71], v210 offset:1552
	v_cvt_scalef32_pk_bf16_fp4 v88, v43, 1.0
	v_cvt_scalef32_pk_bf16_fp4 v89, v43, 1.0 op_sel:[1,0,0]
	v_cvt_scalef32_pk_bf16_fp4 v90, v43, 1.0 op_sel:[0,1,0]
	v_cvt_scalef32_pk_bf16_fp4 v91, v43, 1.0 op_sel:[1,1,0]
	s_waitcnt lgkmcnt(2)
	v_mfma_f32_16x16x32_bf16 v[80:83], v[72:75], v[84:87], v[80:83]
	ds_read_b128 v[72:75], v210 offset:1568
	v_cvt_scalef32_pk_bf16_fp4 v84, v36, 1.0
	v_cvt_scalef32_pk_bf16_fp4 v85, v36, 1.0 op_sel:[1,0,0]
	v_cvt_scalef32_pk_bf16_fp4 v86, v36, 1.0 op_sel:[0,1,0]
	v_cvt_scalef32_pk_bf16_fp4 v87, v36, 1.0 op_sel:[1,1,0]
	v_mfma_f32_16x16x32_bf16 v[80:83], v[76:79], v[88:91], v[80:83]
	ds_read_b128 v[76:79], v210 offset:1584
	v_cvt_scalef32_pk_bf16_fp4 v88, v37, 1.0
	v_cvt_scalef32_pk_bf16_fp4 v89, v37, 1.0 op_sel:[1,0,0]
	v_cvt_scalef32_pk_bf16_fp4 v90, v37, 1.0 op_sel:[0,1,0]
	v_cvt_scalef32_pk_bf16_fp4 v91, v37, 1.0 op_sel:[1,1,0]
	s_waitcnt lgkmcnt(2)
	v_mfma_f32_16x16x32_bf16 v[80:83], v[64:67], v[84:87], v[80:83]
	ds_read_b128 v[64:67], v210 offset:1792
	v_cvt_scalef32_pk_bf16_fp4 v84, v38, 1.0
	v_cvt_scalef32_pk_bf16_fp4 v85, v38, 1.0 op_sel:[1,0,0]
	v_cvt_scalef32_pk_bf16_fp4 v86, v38, 1.0 op_sel:[0,1,0]
	v_cvt_scalef32_pk_bf16_fp4 v87, v38, 1.0 op_sel:[1,1,0]
	v_mfma_f32_16x16x32_bf16 v[80:83], v[68:71], v[88:91], v[80:83]
	ds_read_b128 v[68:71], v210 offset:1808
	v_cvt_scalef32_pk_bf16_fp4 v88, v39, 1.0
	v_cvt_scalef32_pk_bf16_fp4 v89, v39, 1.0 op_sel:[1,0,0]
	v_cvt_scalef32_pk_bf16_fp4 v90, v39, 1.0 op_sel:[0,1,0]
	v_cvt_scalef32_pk_bf16_fp4 v91, v39, 1.0 op_sel:[1,1,0]
	s_waitcnt lgkmcnt(2)
	v_mfma_f32_16x16x32_bf16 v[80:83], v[72:75], v[84:87], v[80:83]
	ds_read_b128 v[72:75], v210 offset:1824
	v_cvt_scalef32_pk_bf16_fp4 v84, v32, 1.0
	v_cvt_scalef32_pk_bf16_fp4 v85, v32, 1.0 op_sel:[1,0,0]
	v_cvt_scalef32_pk_bf16_fp4 v86, v32, 1.0 op_sel:[0,1,0]
	v_cvt_scalef32_pk_bf16_fp4 v87, v32, 1.0 op_sel:[1,1,0]
	v_mfma_f32_16x16x32_bf16 v[80:83], v[76:79], v[88:91], v[80:83]
	ds_read_b128 v[76:79], v210 offset:1840
	v_cvt_scalef32_pk_bf16_fp4 v88, v33, 1.0
	v_cvt_scalef32_pk_bf16_fp4 v89, v33, 1.0 op_sel:[1,0,0]
	v_cvt_scalef32_pk_bf16_fp4 v90, v33, 1.0 op_sel:[0,1,0]
	v_cvt_scalef32_pk_bf16_fp4 v91, v33, 1.0 op_sel:[1,1,0]
	s_waitcnt lgkmcnt(2)
; DI float dotU(const URow& q, const f32x2 (&x2)[16]) { return dot32r(dec6(q), x2); }
; DI void axpyV(f32x2 (&f2)[16], float a, const VRow& q) { axpy32r(f2, a, dec6(q)); }
; DI float gelu_tanh(float x) {
;     const float u = 0.7978845608f * (x + 0.044715f * x * x * x);
;     const float th = 1.f - 2.f / (__expf(2.f * u) + 1.f);
;     return 0.5f * x * (1.f + th);
; }
; DI void axpyV(f32x2 (&f2)[16], float a, const VRow& q) {
;     const f32x2 aa = {a, a};
; #pragma unroll
;     for (int d = 0; d < 4; ++d) {
;         f2[4 * d] += aa * __builtin_amdgcn_cvt_scalef32_pk_f32_fp4(q[d], 1.0f, 0);     f2[4 * d + 1] += aa * __builtin_amdgcn_cvt_scalef32_pk_f32_fp4(q[d], 1.0f, 1);
;         f2[4 * d + 2] += aa * __builtin_amdgcn_cvt_scalef32_pk_f32_fp4(q[d], 1.0f, 2); f2[4 * d + 3] += aa * __builtin_amdgcn_cvt_scalef32_pk_f32_fp4(q[d], 1.0f, 3);
;     }
; }
; DI void peer_phase(const Params& p, int layer, bool dry) {
;     ...
;             for (int q = 0; q < 8; ++q) d[q] = dotU(ucur[q], x2);
;     ...
;             const float act = gelu_tanh(r1 * usc) * gsc;
; #pragma unroll
;             for (int q = 0; q < 8; ++q) { const float a = __shfl(act, (lane & 32) | ((q >> 2) << 4) | (((q >> 1) & 1) << 3) | ((q & 1) << 2)); axpyV(f2, a, vcur[q]); }
	v_mfma_f32_16x16x32_bf16 v[80:83], v[64:67], v[84:87], v[80:83]
	v_cvt_scalef32_pk_bf16_fp4 v84, v34, 1.0
	v_cvt_scalef32_pk_bf16_fp4 v85, v34, 1.0 op_sel:[1,0,0]
	v_cvt_scalef32_pk_bf16_fp4 v86, v34, 1.0 op_sel:[0,1,0]
	v_cvt_scalef32_pk_bf16_fp4 v87, v34, 1.0 op_sel:[1,1,0]
	v_mfma_f32_16x16x32_bf16 v[80:83], v[68:71], v[88:91], v[80:83]
	v_cvt_scalef32_pk_bf16_fp4 v88, v35, 1.0
	v_cvt_scalef32_pk_bf16_fp4 v89, v35, 1.0 op_sel:[1,0,0]
	v_cvt_scalef32_pk_bf16_fp4 v90, v35, 1.0 op_sel:[0,1,0]
	v_cvt_scalef32_pk_bf16_fp4 v91, v35, 1.0 op_sel:[1,1,0]
	s_waitcnt lgkmcnt(0)
	v_mfma_f32_16x16x32_bf16 v[80:83], v[72:75], v[84:87], v[80:83]
	v_mfma_f32_16x16x32_bf16 v[80:83], v[76:79], v[88:91], v[80:83]
	s_waitcnt vmcnt(22)
	v_cndmask_b32_e32 v54, v227, v226, vcc
	ds_bpermute_b32 v54, v228, v54
	v_cvt_scalef32_pk_f32_fp4 v[230:231], v28, 1.0
	s_nop 7
	s_waitcnt lgkmcnt(0)
	s_waitcnt vmcnt(16)
	v_mul_f32_e32 v55, v93, v80
	v_mul_f32_e32 v46, 0x3d372713, v55
	v_mul_f32_e32 v46, v55, v46
	v_fma_f32 v46, v55, v46, v55
	v_mul_f32_e32 v46, 0x3f4c422a, v46
	v_add_f32_e32 v46, v46, v46
	v_mul_f32_e32 v46, 0x3fb8aa3b, v46
	v_exp_f32_e32 v52, v46
	s_nop 0
	v_add_f32_e32 v93, 1.0, v52
	v_div_scale_f32 v94, s[28:29], v93, v93, 2.0
	v_rcp_f32_e32 v95, v94
	s_add_i32 s11, s11, 1
	s_cmpk_eq_i32 s21, 0x80
	v_fma_f32 v190, -v94, v95, 1.0
	v_fmac_f32_e32 v95, v190, v95
	v_div_scale_f32 v190, vcc, 2.0, v93, 2.0
	v_mul_f32_e32 v191, v190, v95
	v_fma_f32 v228, -v94, v191, v190
	v_fmac_f32_e32 v191, v228, v95
	v_fma_f32 v94, -v94, v191, v190
	v_div_fmas_f32 v94, v94, v95, v191
	v_div_fixup_f32 v93, v94, v93, 2.0
	v_sub_f32_e32 v94, 1.0, v93
	v_mul_f32_e32 v93, 0.5, v55
	v_add_f32_e32 v55, 1.0, v94
	v_pk_mul_f32 v[54:55], v[92:93], v[54:55]
	v_pk_mul_f32 v[190:191], v[54:55], v[54:55] op_sel:[0,1] op_sel_hi:[1,0]
	ds_bpermute_b32 v228, v216, v190
	s_waitcnt lgkmcnt(0)
	v_pk_fma_f32 v[188:189], v[230:231], v[228:229], v[188:189] op_sel_hi:[1,0,1]
	v_cvt_scalef32_pk_f32_fp4 v[230:231], v28, 1.0 op_sel:[1,0,0]
	v_pk_fma_f32 v[164:165], v[228:229], v[230:231], v[164:165] op_sel_hi:[0,1,1]
	v_cvt_scalef32_pk_f32_fp4 v[230:231], v28, 1.0 op_sel:[0,1,0]
	v_pk_fma_f32 v[168:169], v[228:229], v[230:231], v[168:169] op_sel_hi:[0,1,1]
	v_cvt_scalef32_pk_f32_fp4 v[230:231], v28, 1.0 op_sel:[1,1,0]
	v_pk_fma_f32 v[172:173], v[228:229], v[230:231], v[172:173] op_sel_hi:[0,1,1]
	v_cvt_scalef32_pk_f32_fp4 v[230:231], v29, 1.0
	v_pk_fma_f32 v[176:177], v[228:229], v[230:231], v[176:177] op_sel_hi:[0,1,1]
	v_cvt_scalef32_pk_f32_fp4 v[230:231], v29, 1.0 op_sel:[1,0,0]
	v_pk_fma_f32 v[180:181], v[228:229], v[230:231], v[180:181] op_sel_hi:[0,1,1]
	v_cvt_scalef32_pk_f32_fp4 v[230:231], v29, 1.0 op_sel:[0,1,0]
	v_cvt_scalef32_pk_f32_fp4 v[28:29], v29, 1.0 op_sel:[1,1,0]
	v_pk_fma_f32 v[28:29], v[228:229], v[28:29], v[186:187] op_sel_hi:[0,1,1]
	v_cvt_scalef32_pk_f32_fp4 v[186:187], v30, 1.0
	v_pk_fma_f32 v[158:159], v[228:229], v[186:187], v[158:159] op_sel_hi:[0,1,1]
	v_cvt_scalef32_pk_f32_fp4 v[186:187], v30, 1.0 op_sel:[1,0,0]
	v_pk_fma_f32 v[162:163], v[228:229], v[186:187], v[162:163] op_sel_hi:[0,1,1]
	v_cvt_scalef32_pk_f32_fp4 v[186:187], v30, 1.0 op_sel:[0,1,0]
	v_pk_fma_f32 v[166:167], v[228:229], v[186:187], v[166:167] op_sel_hi:[0,1,1]
	v_cvt_scalef32_pk_f32_fp4 v[186:187], v30, 1.0 op_sel:[1,1,0]
	v_pk_fma_f32 v[170:171], v[228:229], v[186:187], v[170:171] op_sel_hi:[0,1,1]
	v_cvt_scalef32_pk_f32_fp4 v[186:187], v31, 1.0
	ds_bpermute_b32 v30, v217, v190
	v_pk_fma_f32 v[174:175], v[228:229], v[186:187], v[174:175] op_sel_hi:[0,1,1]
	v_cvt_scalef32_pk_f32_fp4 v[186:187], v31, 1.0 op_sel:[1,0,0]
	v_pk_fma_f32 v[178:179], v[228:229], v[186:187], v[178:179] op_sel_hi:[0,1,1]
	v_cvt_scalef32_pk_f32_fp4 v[186:187], v31, 1.0 op_sel:[0,1,0]
	v_pk_fma_f32 v[182:183], v[228:229], v[186:187], v[182:183] op_sel_hi:[0,1,1]
	v_cvt_scalef32_pk_f32_fp4 v[186:187], v31, 1.0 op_sel:[1,1,0]
	v_pk_fma_f32 v[160:161], v[228:229], v[186:187], v[160:161] op_sel_hi:[0,1,1]
	v_cvt_scalef32_pk_f32_fp4 v[186:187], v24, 1.0
	s_waitcnt lgkmcnt(0)
	v_pk_fma_f32 v[186:187], v[186:187], v[30:31], v[188:189] op_sel_hi:[1,0,1]
	v_cvt_scalef32_pk_f32_fp4 v[188:189], v24, 1.0 op_sel:[1,0,0]
	v_pk_fma_f32 v[164:165], v[30:31], v[188:189], v[164:165] op_sel_hi:[0,1,1]
	v_cvt_scalef32_pk_f32_fp4 v[188:189], v24, 1.0 op_sel:[0,1,0]
	v_pk_fma_f32 v[168:169], v[30:31], v[188:189], v[168:169] op_sel_hi:[0,1,1]
	v_cvt_scalef32_pk_f32_fp4 v[188:189], v24, 1.0 op_sel:[1,1,0]
	v_pk_fma_f32 v[172:173], v[30:31], v[188:189], v[172:173] op_sel_hi:[0,1,1]
	v_cvt_scalef32_pk_f32_fp4 v[188:189], v25, 1.0
	v_pk_fma_f32 v[176:177], v[30:31], v[188:189], v[176:177] op_sel_hi:[0,1,1]
	v_cvt_scalef32_pk_f32_fp4 v[188:189], v25, 1.0 op_sel:[1,0,0]
	v_pk_fma_f32 v[180:181], v[30:31], v[188:189], v[180:181] op_sel_hi:[0,1,1]
	v_cvt_scalef32_pk_f32_fp4 v[188:189], v25, 1.0 op_sel:[0,1,0]
	v_cvt_scalef32_pk_f32_fp4 v[24:25], v25, 1.0 op_sel:[1,1,0]
	v_pk_fma_f32 v[24:25], v[30:31], v[24:25], v[28:29] op_sel_hi:[0,1,1]
	v_cvt_scalef32_pk_f32_fp4 v[28:29], v26, 1.0
	v_pk_fma_f32 v[28:29], v[30:31], v[28:29], v[158:159] op_sel_hi:[0,1,1]
	v_cvt_scalef32_pk_f32_fp4 v[158:159], v26, 1.0 op_sel:[1,0,0]
	v_pk_fma_f32 v[158:159], v[30:31], v[158:159], v[162:163] op_sel_hi:[0,1,1]
	v_cvt_scalef32_pk_f32_fp4 v[162:163], v26, 1.0 op_sel:[0,1,0]
	v_pk_fma_f32 v[162:163], v[30:31], v[162:163], v[166:167] op_sel_hi:[0,1,1]
	v_cvt_scalef32_pk_f32_fp4 v[166:167], v26, 1.0 op_sel:[1,1,0]
	v_pk_fma_f32 v[166:167], v[30:31], v[166:167], v[170:171] op_sel_hi:[0,1,1]
	v_cvt_scalef32_pk_f32_fp4 v[170:171], v27, 1.0
	ds_bpermute_b32 v26, v219, v190
	v_pk_fma_f32 v[170:171], v[30:31], v[170:171], v[174:175] op_sel_hi:[0,1,1]
	v_cvt_scalef32_pk_f32_fp4 v[174:175], v27, 1.0 op_sel:[1,0,0]
	v_pk_fma_f32 v[174:175], v[30:31], v[174:175], v[178:179] op_sel_hi:[0,1,1]
	v_cvt_scalef32_pk_f32_fp4 v[178:179], v27, 1.0 op_sel:[0,1,0]
	v_pk_fma_f32 v[184:185], v[228:229], v[230:231], v[184:185] op_sel_hi:[0,1,1]
	v_pk_fma_f32 v[178:179], v[30:31], v[178:179], v[182:183] op_sel_hi:[0,1,1]
	v_cvt_scalef32_pk_f32_fp4 v[182:183], v27, 1.0 op_sel:[1,1,0]
	v_pk_fma_f32 v[184:185], v[30:31], v[188:189], v[184:185] op_sel_hi:[0,1,1]
	v_pk_fma_f32 v[30:31], v[30:31], v[182:183], v[160:161] op_sel_hi:[0,1,1]
	v_cvt_scalef32_pk_f32_fp4 v[182:183], v20, 1.0 op_sel:[1,0,0]
	s_waitcnt lgkmcnt(0)
; DI void axpyV(f32x2 (&f2)[16], float a, const VRow& q) { axpy32r(f2, a, dec6(q)); }
; DI void axpyV(f32x2 (&f2)[16], float a, const VRow& q) {
;     const f32x2 aa = {a, a};
; #pragma unroll
;     for (int d = 0; d < 4; ++d) {
;         f2[4 * d] += aa * __builtin_amdgcn_cvt_scalef32_pk_f32_fp4(q[d], 1.0f, 0);     f2[4 * d + 1] += aa * __builtin_amdgcn_cvt_scalef32_pk_f32_fp4(q[d], 1.0f, 1);
;         f2[4 * d + 2] += aa * __builtin_amdgcn_cvt_scalef32_pk_f32_fp4(q[d], 1.0f, 2); f2[4 * d + 3] += aa * __builtin_amdgcn_cvt_scalef32_pk_f32_fp4(q[d], 1.0f, 3);
;     }
; }
; DI void peer_phase(const Params& p, int layer, bool dry) {
;     ...
;             for (int q = 0; q < 8; ++q) { const float a = __shfl(act, (lane & 32) | ((q >> 2) << 4) | (((q >> 1) & 1) << 3) | ((q & 1) << 2)); axpyV(f2, a, vcur[q]); }
	v_pk_fma_f32 v[164:165], v[26:27], v[182:183], v[164:165] op_sel_hi:[0,1,1]
	v_cvt_scalef32_pk_f32_fp4 v[182:183], v20, 1.0 op_sel:[0,1,0]
	v_pk_fma_f32 v[168:169], v[26:27], v[182:183], v[168:169] op_sel_hi:[0,1,1]
	v_cvt_scalef32_pk_f32_fp4 v[182:183], v20, 1.0 op_sel:[1,1,0]
	v_pk_fma_f32 v[172:173], v[26:27], v[182:183], v[172:173] op_sel_hi:[0,1,1]
	v_cvt_scalef32_pk_f32_fp4 v[182:183], v21, 1.0
	v_pk_fma_f32 v[176:177], v[26:27], v[182:183], v[176:177] op_sel_hi:[0,1,1]
	v_cvt_scalef32_pk_f32_fp4 v[182:183], v21, 1.0 op_sel:[1,0,0]
	v_cvt_scalef32_pk_f32_fp4 v[160:161], v20, 1.0
	v_pk_fma_f32 v[180:181], v[26:27], v[182:183], v[180:181] op_sel_hi:[0,1,1]
	v_cvt_scalef32_pk_f32_fp4 v[182:183], v21, 1.0 op_sel:[0,1,0]
	v_cvt_scalef32_pk_f32_fp4 v[20:21], v21, 1.0 op_sel:[1,1,0]
	v_pk_fma_f32 v[20:21], v[26:27], v[20:21], v[24:25] op_sel_hi:[0,1,1]
	v_cvt_scalef32_pk_f32_fp4 v[24:25], v22, 1.0
	v_pk_fma_f32 v[24:25], v[26:27], v[24:25], v[28:29] op_sel_hi:[0,1,1]
	v_cvt_scalef32_pk_f32_fp4 v[28:29], v22, 1.0 op_sel:[1,0,0]
	v_pk_fma_f32 v[28:29], v[26:27], v[28:29], v[158:159] op_sel_hi:[0,1,1]
	v_cvt_scalef32_pk_f32_fp4 v[158:159], v22, 1.0 op_sel:[0,1,0]
	v_pk_fma_f32 v[158:159], v[26:27], v[158:159], v[162:163] op_sel_hi:[0,1,1]
	v_cvt_scalef32_pk_f32_fp4 v[162:163], v22, 1.0 op_sel:[1,1,0]
	v_pk_fma_f32 v[162:163], v[26:27], v[162:163], v[166:167] op_sel_hi:[0,1,1]
	v_cvt_scalef32_pk_f32_fp4 v[166:167], v23, 1.0
	ds_bpermute_b32 v22, v220, v190
	v_pk_fma_f32 v[166:167], v[26:27], v[166:167], v[170:171] op_sel_hi:[0,1,1]
	v_cvt_scalef32_pk_f32_fp4 v[170:171], v23, 1.0 op_sel:[1,0,0]
	v_pk_fma_f32 v[170:171], v[26:27], v[170:171], v[174:175] op_sel_hi:[0,1,1]
	v_cvt_scalef32_pk_f32_fp4 v[174:175], v23, 1.0 op_sel:[0,1,0]
	v_pk_fma_f32 v[174:175], v[26:27], v[174:175], v[178:179] op_sel_hi:[0,1,1]
	v_cvt_scalef32_pk_f32_fp4 v[178:179], v23, 1.0 op_sel:[1,1,0]
	v_pk_fma_f32 v[160:161], v[160:161], v[26:27], v[186:187] op_sel_hi:[1,0,1]
	v_pk_fma_f32 v[182:183], v[26:27], v[182:183], v[184:185] op_sel_hi:[0,1,1]
	v_pk_fma_f32 v[26:27], v[26:27], v[178:179], v[30:31] op_sel_hi:[0,1,1]
	v_cvt_scalef32_pk_f32_fp4 v[30:31], v16, 1.0
	s_waitcnt lgkmcnt(0)
	v_pk_fma_f32 v[30:31], v[30:31], v[22:23], v[160:161] op_sel_hi:[1,0,1]
	v_cvt_scalef32_pk_f32_fp4 v[160:161], v16, 1.0 op_sel:[1,0,0]
	v_pk_fma_f32 v[160:161], v[22:23], v[160:161], v[164:165] op_sel_hi:[0,1,1]
	v_cvt_scalef32_pk_f32_fp4 v[164:165], v16, 1.0 op_sel:[0,1,0]
	v_pk_fma_f32 v[164:165], v[22:23], v[164:165], v[168:169] op_sel_hi:[0,1,1]
	v_cvt_scalef32_pk_f32_fp4 v[168:169], v16, 1.0 op_sel:[1,1,0]
	v_pk_fma_f32 v[168:169], v[22:23], v[168:169], v[172:173] op_sel_hi:[0,1,1]
	v_cvt_scalef32_pk_f32_fp4 v[172:173], v17, 1.0
	v_pk_fma_f32 v[172:173], v[22:23], v[172:173], v[176:177] op_sel_hi:[0,1,1]
	v_cvt_scalef32_pk_f32_fp4 v[176:177], v17, 1.0 op_sel:[1,0,0]
	v_cvt_scalef32_pk_f32_fp4 v[178:179], v17, 1.0 op_sel:[0,1,0]
	v_cvt_scalef32_pk_f32_fp4 v[16:17], v17, 1.0 op_sel:[1,1,0]
	v_pk_fma_f32 v[16:17], v[22:23], v[16:17], v[20:21] op_sel_hi:[0,1,1]
	v_cvt_scalef32_pk_f32_fp4 v[20:21], v18, 1.0
	v_pk_fma_f32 v[20:21], v[22:23], v[20:21], v[24:25] op_sel_hi:[0,1,1]
	v_cvt_scalef32_pk_f32_fp4 v[24:25], v18, 1.0 op_sel:[1,0,0]
	v_pk_fma_f32 v[24:25], v[22:23], v[24:25], v[28:29] op_sel_hi:[0,1,1]
	v_cvt_scalef32_pk_f32_fp4 v[28:29], v18, 1.0 op_sel:[0,1,0]
	v_pk_fma_f32 v[28:29], v[22:23], v[28:29], v[158:159] op_sel_hi:[0,1,1]
	v_cvt_scalef32_pk_f32_fp4 v[158:159], v18, 1.0 op_sel:[1,1,0]
	v_pk_fma_f32 v[158:159], v[22:23], v[158:159], v[162:163] op_sel_hi:[0,1,1]
	v_cvt_scalef32_pk_f32_fp4 v[162:163], v19, 1.0
	ds_bpermute_b32 v18, v221, v190
	v_pk_fma_f32 v[162:163], v[22:23], v[162:163], v[166:167] op_sel_hi:[0,1,1]
	v_cvt_scalef32_pk_f32_fp4 v[166:167], v19, 1.0 op_sel:[1,0,0]
	v_pk_fma_f32 v[166:167], v[22:23], v[166:167], v[170:171] op_sel_hi:[0,1,1]
	v_cvt_scalef32_pk_f32_fp4 v[170:171], v19, 1.0 op_sel:[0,1,0]
	v_pk_fma_f32 v[170:171], v[22:23], v[170:171], v[174:175] op_sel_hi:[0,1,1]
	v_cvt_scalef32_pk_f32_fp4 v[174:175], v19, 1.0 op_sel:[1,1,0]
	v_pk_fma_f32 v[176:177], v[22:23], v[176:177], v[180:181] op_sel_hi:[0,1,1]
	v_pk_fma_f32 v[178:179], v[22:23], v[178:179], v[182:183] op_sel_hi:[0,1,1]
	v_pk_fma_f32 v[22:23], v[22:23], v[174:175], v[26:27] op_sel_hi:[0,1,1]
	v_cvt_scalef32_pk_f32_fp4 v[26:27], v12, 1.0
	s_waitcnt lgkmcnt(0)
	v_pk_fma_f32 v[26:27], v[26:27], v[18:19], v[30:31] op_sel_hi:[1,0,1]
	v_cvt_scalef32_pk_f32_fp4 v[30:31], v12, 1.0 op_sel:[1,0,0]
	v_pk_fma_f32 v[30:31], v[18:19], v[30:31], v[160:161] op_sel_hi:[0,1,1]
	v_cvt_scalef32_pk_f32_fp4 v[160:161], v12, 1.0 op_sel:[0,1,0]
	v_pk_fma_f32 v[160:161], v[18:19], v[160:161], v[164:165] op_sel_hi:[0,1,1]
	v_cvt_scalef32_pk_f32_fp4 v[164:165], v12, 1.0 op_sel:[1,1,0]
	v_pk_fma_f32 v[164:165], v[18:19], v[164:165], v[168:169] op_sel_hi:[0,1,1]
	v_cvt_scalef32_pk_f32_fp4 v[168:169], v13, 1.0
	v_pk_fma_f32 v[168:169], v[18:19], v[168:169], v[172:173] op_sel_hi:[0,1,1]
	v_cvt_scalef32_pk_f32_fp4 v[172:173], v13, 1.0 op_sel:[1,0,0]
	v_cvt_scalef32_pk_f32_fp4 v[174:175], v13, 1.0 op_sel:[0,1,0]
	v_cvt_scalef32_pk_f32_fp4 v[12:13], v13, 1.0 op_sel:[1,1,0]
	v_pk_fma_f32 v[12:13], v[18:19], v[12:13], v[16:17] op_sel_hi:[0,1,1]
	v_cvt_scalef32_pk_f32_fp4 v[16:17], v14, 1.0
	v_pk_fma_f32 v[16:17], v[18:19], v[16:17], v[20:21] op_sel_hi:[0,1,1]
	v_cvt_scalef32_pk_f32_fp4 v[20:21], v14, 1.0 op_sel:[1,0,0]
	v_pk_fma_f32 v[20:21], v[18:19], v[20:21], v[24:25] op_sel_hi:[0,1,1]
	v_cvt_scalef32_pk_f32_fp4 v[24:25], v14, 1.0 op_sel:[0,1,0]
	v_pk_fma_f32 v[24:25], v[18:19], v[24:25], v[28:29] op_sel_hi:[0,1,1]
	v_cvt_scalef32_pk_f32_fp4 v[28:29], v14, 1.0 op_sel:[1,1,0]
	v_pk_fma_f32 v[28:29], v[18:19], v[28:29], v[158:159] op_sel_hi:[0,1,1]
	v_cvt_scalef32_pk_f32_fp4 v[158:159], v15, 1.0
	ds_bpermute_b32 v14, v222, v190
	v_pk_fma_f32 v[158:159], v[18:19], v[158:159], v[162:163] op_sel_hi:[0,1,1]
	v_cvt_scalef32_pk_f32_fp4 v[162:163], v15, 1.0 op_sel:[1,0,0]
	v_pk_fma_f32 v[162:163], v[18:19], v[162:163], v[166:167] op_sel_hi:[0,1,1]
	v_cvt_scalef32_pk_f32_fp4 v[166:167], v15, 1.0 op_sel:[0,1,0]
	v_pk_fma_f32 v[166:167], v[18:19], v[166:167], v[170:171] op_sel_hi:[0,1,1]
	v_cvt_scalef32_pk_f32_fp4 v[170:171], v15, 1.0 op_sel:[1,1,0]
	v_pk_fma_f32 v[172:173], v[18:19], v[172:173], v[176:177] op_sel_hi:[0,1,1]
	v_pk_fma_f32 v[174:175], v[18:19], v[174:175], v[178:179] op_sel_hi:[0,1,1]
	v_pk_fma_f32 v[18:19], v[18:19], v[170:171], v[22:23] op_sel_hi:[0,1,1]
	v_cvt_scalef32_pk_f32_fp4 v[22:23], v8, 1.0
	s_waitcnt lgkmcnt(0)
; DI void axpyV(f32x2 (&f2)[16], float a, const VRow& q) { axpy32r(f2, a, dec6(q)); }
; #define PEER_SWAP() do { _Pragma("unroll") for (int q_ = 0; q_ < 8; ++q_) _Pragma("unroll") for (int c_ = 0; c_ < 4; ++c_) { \
;             const auto r_ = __builtin_amdgcn_permlane32_swap(ra[q_][c_], rb[q_][c_], false, false); ucur[q_][c_] = r_[0]; vcur[q_][c_] = r_[1]; } } while (0)
; DI void axpyV(f32x2 (&f2)[16], float a, const VRow& q) {
;     const f32x2 aa = {a, a};
; #pragma unroll
;     for (int d = 0; d < 4; ++d) {
;         f2[4 * d] += aa * __builtin_amdgcn_cvt_scalef32_pk_f32_fp4(q[d], 1.0f, 0);     f2[4 * d + 1] += aa * __builtin_amdgcn_cvt_scalef32_pk_f32_fp4(q[d], 1.0f, 1);
;         f2[4 * d + 2] += aa * __builtin_amdgcn_cvt_scalef32_pk_f32_fp4(q[d], 1.0f, 2); f2[4 * d + 3] += aa * __builtin_amdgcn_cvt_scalef32_pk_f32_fp4(q[d], 1.0f, 3);
;     }
; }
; DI void peer_phase(const Params& p, int layer, bool dry) {
;     ...
;             for (int q = 0; q < 8; ++q) { const float a = __shfl(act, (lane & 32) | ((q >> 2) << 4) | (((q >> 1) & 1) << 3) | ((q & 1) << 2)); axpyV(f2, a, vcur[q]); }
;             PEER_SWAP();
	v_pk_fma_f32 v[22:23], v[22:23], v[14:15], v[26:27] op_sel_hi:[1,0,1]
	v_cvt_scalef32_pk_f32_fp4 v[26:27], v8, 1.0 op_sel:[1,0,0]
	v_pk_fma_f32 v[26:27], v[14:15], v[26:27], v[30:31] op_sel_hi:[0,1,1]
	v_cvt_scalef32_pk_f32_fp4 v[30:31], v8, 1.0 op_sel:[0,1,0]
	v_pk_fma_f32 v[30:31], v[14:15], v[30:31], v[160:161] op_sel_hi:[0,1,1]
	v_cvt_scalef32_pk_f32_fp4 v[160:161], v8, 1.0 op_sel:[1,1,0]
	v_pk_fma_f32 v[160:161], v[14:15], v[160:161], v[164:165] op_sel_hi:[0,1,1]
	v_cvt_scalef32_pk_f32_fp4 v[164:165], v9, 1.0
	v_pk_fma_f32 v[164:165], v[14:15], v[164:165], v[168:169] op_sel_hi:[0,1,1]
	v_cvt_scalef32_pk_f32_fp4 v[168:169], v9, 1.0 op_sel:[1,0,0]
	v_cvt_scalef32_pk_f32_fp4 v[170:171], v9, 1.0 op_sel:[0,1,0]
	v_cvt_scalef32_pk_f32_fp4 v[8:9], v9, 1.0 op_sel:[1,1,0]
	v_pk_fma_f32 v[8:9], v[14:15], v[8:9], v[12:13] op_sel_hi:[0,1,1]
	v_cvt_scalef32_pk_f32_fp4 v[12:13], v10, 1.0
	v_pk_fma_f32 v[12:13], v[14:15], v[12:13], v[16:17] op_sel_hi:[0,1,1]
	v_cvt_scalef32_pk_f32_fp4 v[16:17], v10, 1.0 op_sel:[1,0,0]
	v_pk_fma_f32 v[16:17], v[14:15], v[16:17], v[20:21] op_sel_hi:[0,1,1]
	v_cvt_scalef32_pk_f32_fp4 v[20:21], v10, 1.0 op_sel:[0,1,0]
	v_pk_fma_f32 v[20:21], v[14:15], v[20:21], v[24:25] op_sel_hi:[0,1,1]
	v_cvt_scalef32_pk_f32_fp4 v[24:25], v10, 1.0 op_sel:[1,1,0]
	v_pk_fma_f32 v[24:25], v[14:15], v[24:25], v[28:29] op_sel_hi:[0,1,1]
	v_cvt_scalef32_pk_f32_fp4 v[28:29], v11, 1.0
	ds_bpermute_b32 v10, v223, v190
	v_pk_fma_f32 v[28:29], v[14:15], v[28:29], v[158:159] op_sel_hi:[0,1,1]
	v_cvt_scalef32_pk_f32_fp4 v[158:159], v11, 1.0 op_sel:[1,0,0]
	v_pk_fma_f32 v[158:159], v[14:15], v[158:159], v[162:163] op_sel_hi:[0,1,1]
	v_cvt_scalef32_pk_f32_fp4 v[162:163], v11, 1.0 op_sel:[0,1,0]
	v_pk_fma_f32 v[162:163], v[14:15], v[162:163], v[166:167] op_sel_hi:[0,1,1]
	v_cvt_scalef32_pk_f32_fp4 v[166:167], v11, 1.0 op_sel:[1,1,0]
	v_pk_fma_f32 v[168:169], v[14:15], v[168:169], v[172:173] op_sel_hi:[0,1,1]
	v_pk_fma_f32 v[170:171], v[14:15], v[170:171], v[174:175] op_sel_hi:[0,1,1]
	v_pk_fma_f32 v[14:15], v[14:15], v[166:167], v[18:19] op_sel_hi:[0,1,1]
	v_cvt_scalef32_pk_f32_fp4 v[18:19], v4, 1.0
	s_waitcnt lgkmcnt(0)
	v_pk_fma_f32 v[188:189], v[18:19], v[10:11], v[22:23] op_sel_hi:[1,0,1]
	v_cvt_scalef32_pk_f32_fp4 v[18:19], v4, 1.0 op_sel:[1,0,0]
	v_cvt_scalef32_pk_f32_fp4 v[22:23], v4, 1.0 op_sel:[0,1,0]
	v_pk_fma_f32 v[18:19], v[10:11], v[18:19], v[26:27] op_sel_hi:[0,1,1]
	v_pk_fma_f32 v[22:23], v[10:11], v[22:23], v[30:31] op_sel_hi:[0,1,1]
	v_cvt_scalef32_pk_f32_fp4 v[26:27], v4, 1.0 op_sel:[1,1,0]
	v_cvt_scalef32_pk_f32_fp4 v[30:31], v5, 1.0
	v_pk_fma_f32 v[26:27], v[10:11], v[26:27], v[160:161] op_sel_hi:[0,1,1]
	v_pk_fma_f32 v[30:31], v[10:11], v[30:31], v[164:165] op_sel_hi:[0,1,1]
	v_cvt_scalef32_pk_f32_fp4 v[160:161], v5, 1.0 op_sel:[1,0,0]
	v_cvt_scalef32_pk_f32_fp4 v[164:165], v5, 1.0 op_sel:[0,1,0]
	v_cvt_scalef32_pk_f32_fp4 v[4:5], v5, 1.0 op_sel:[1,1,0]
	v_pk_fma_f32 v[4:5], v[10:11], v[4:5], v[8:9] op_sel_hi:[0,1,1]
	v_cvt_scalef32_pk_f32_fp4 v[8:9], v6, 1.0
	v_pk_fma_f32 v[8:9], v[10:11], v[8:9], v[12:13] op_sel_hi:[0,1,1]
	v_cvt_scalef32_pk_f32_fp4 v[12:13], v6, 1.0 op_sel:[1,0,0]
	v_pk_fma_f32 v[12:13], v[10:11], v[12:13], v[16:17] op_sel_hi:[0,1,1]
	v_cvt_scalef32_pk_f32_fp4 v[16:17], v6, 1.0 op_sel:[0,1,0]
	v_pk_fma_f32 v[16:17], v[10:11], v[16:17], v[20:21] op_sel_hi:[0,1,1]
	v_cvt_scalef32_pk_f32_fp4 v[20:21], v6, 1.0 op_sel:[1,1,0]
	ds_bpermute_b32 v190, v224, v190
	v_pk_fma_f32 v[20:21], v[10:11], v[20:21], v[24:25] op_sel_hi:[0,1,1]
	v_cvt_scalef32_pk_f32_fp4 v[24:25], v7, 1.0
	v_pk_fma_f32 v[24:25], v[10:11], v[24:25], v[28:29] op_sel_hi:[0,1,1]
	v_cvt_scalef32_pk_f32_fp4 v[28:29], v7, 1.0 op_sel:[1,0,0]
	v_pk_fma_f32 v[28:29], v[10:11], v[28:29], v[158:159] op_sel_hi:[0,1,1]
	v_cvt_scalef32_pk_f32_fp4 v[158:159], v7, 1.0 op_sel:[0,1,0]
	v_cvt_scalef32_pk_f32_fp4 v[6:7], v7, 1.0 op_sel:[1,1,0]
	v_pk_fma_f32 v[160:161], v[10:11], v[160:161], v[168:169] op_sel_hi:[0,1,1]
	v_pk_fma_f32 v[166:167], v[10:11], v[164:165], v[170:171] op_sel_hi:[0,1,1]
	v_pk_fma_f32 v[182:183], v[10:11], v[158:159], v[162:163] op_sel_hi:[0,1,1]
	v_pk_fma_f32 v[6:7], v[10:11], v[6:7], v[14:15] op_sel_hi:[0,1,1]
	v_cvt_scalef32_pk_f32_fp4 v[10:11], v0, 1.0 op_sel:[1,0,0]
	s_waitcnt lgkmcnt(0)
	v_pk_fma_f32 v[164:165], v[190:191], v[10:11], v[18:19] op_sel_hi:[0,1,1]
	v_cvt_scalef32_pk_f32_fp4 v[10:11], v0, 1.0 op_sel:[0,1,0]
	v_pk_fma_f32 v[168:169], v[190:191], v[10:11], v[22:23] op_sel_hi:[0,1,1]
	v_cvt_scalef32_pk_f32_fp4 v[10:11], v0, 1.0 op_sel:[1,1,0]
	v_pk_fma_f32 v[172:173], v[190:191], v[10:11], v[26:27] op_sel_hi:[0,1,1]
	v_cvt_scalef32_pk_f32_fp4 v[10:11], v1, 1.0
	v_pk_fma_f32 v[176:177], v[190:191], v[10:11], v[30:31] op_sel_hi:[0,1,1]
	v_cvt_scalef32_pk_f32_fp4 v[10:11], v1, 1.0 op_sel:[1,0,0]
	v_cvt_scalef32_pk_f32_fp4 v[228:229], v0, 1.0
	v_pk_fma_f32 v[180:181], v[190:191], v[10:11], v[160:161] op_sel_hi:[0,1,1]
	v_cvt_scalef32_pk_f32_fp4 v[10:11], v1, 1.0 op_sel:[0,1,0]
	v_cvt_scalef32_pk_f32_fp4 v[0:1], v1, 1.0 op_sel:[1,1,0]
	v_pk_fma_f32 v[186:187], v[190:191], v[0:1], v[4:5] op_sel_hi:[0,1,1]
	v_cvt_scalef32_pk_f32_fp4 v[0:1], v2, 1.0
	v_pk_fma_f32 v[158:159], v[190:191], v[0:1], v[8:9] op_sel_hi:[0,1,1]
	v_cvt_scalef32_pk_f32_fp4 v[0:1], v2, 1.0 op_sel:[1,0,0]
	v_pk_fma_f32 v[162:163], v[190:191], v[0:1], v[12:13] op_sel_hi:[0,1,1]
	v_cvt_scalef32_pk_f32_fp4 v[0:1], v2, 1.0 op_sel:[0,1,0]
	v_pk_fma_f32 v[184:185], v[190:191], v[10:11], v[166:167] op_sel_hi:[0,1,1]
	v_pk_fma_f32 v[166:167], v[190:191], v[0:1], v[16:17] op_sel_hi:[0,1,1]
	v_cvt_scalef32_pk_f32_fp4 v[0:1], v2, 1.0 op_sel:[1,1,0]
	v_pk_fma_f32 v[170:171], v[190:191], v[0:1], v[20:21] op_sel_hi:[0,1,1]
	v_cvt_scalef32_pk_f32_fp4 v[0:1], v3, 1.0
	v_pk_fma_f32 v[174:175], v[190:191], v[0:1], v[24:25] op_sel_hi:[0,1,1]
	v_cvt_scalef32_pk_f32_fp4 v[0:1], v3, 1.0 op_sel:[1,0,0]
	v_pk_fma_f32 v[178:179], v[190:191], v[0:1], v[28:29] op_sel_hi:[0,1,1]
	v_cvt_scalef32_pk_f32_fp4 v[0:1], v3, 1.0 op_sel:[0,1,0]
	v_pk_fma_f32 v[182:183], v[190:191], v[0:1], v[182:183] op_sel_hi:[0,1,1]
	v_cvt_scalef32_pk_f32_fp4 v[0:1], v3, 1.0 op_sel:[1,1,0]
	v_pk_fma_f32 v[160:161], v[190:191], v[0:1], v[6:7] op_sel_hi:[0,1,1]
	s_waitcnt vmcnt(0)
	ds_read_b128 v[60:63], v196
	ds_read_b128 v[28:31], v233 offset:512
	ds_read_b128 v[56:59], v196 offset:64
	ds_read_b128 v[24:27], v233 offset:2592
	ds_read_b128 v[52:55], v196 offset:128
	ds_read_b128 v[20:23], v233 offset:4672
	ds_read_b128 v[48:51], v196 offset:192
	ds_read_b128 v[16:19], v233 offset:6752
	ds_read_b128 v[44:47], v196 offset:256
	ds_read_b128 v[12:15], v233 offset:8832
	ds_read_b128 v[40:43], v196 offset:320
	ds_read_b128 v[8:11], v233 offset:10912
	ds_read_b128 v[36:39], v196 offset:384
	ds_read_b128 v[4:7], v233 offset:12992
	ds_read_b128 v[32:35], v196 offset:448
	ds_read_b128 v[0:3], v233 offset:15072
	s_waitcnt lgkmcnt(0)
	v_pk_fma_f32 v[188:189], v[228:229], v[190:191], v[188:189] op_sel_hi:[1,0,1]
	s_cbranch_scc1 .LBB0_40
; #define PEER_LOADREC_FROM(isrc_, lb_) do { \
;         _Pragma("unroll") for (int q_ = 0; q_ < 8; ++q_) { \
;             const int ia_ = __builtin_amdgcn_readlane(isrc_, (lb_) + 2 * q_), ib_ = __builtin_amdgcn_readlane(isrc_, (lb_) + 2 * q_ + 1); \
;             ra[q_] = *(const u32x4*)(REC + (size_t)ia_ * 1024); rb[q_] = *(const u32x4*)(REC + (size_t)ib_ * 1024); } } while (0)
; #define PEER_LOADREC_MEM(ep_) do { \
;         _Pragma("unroll") for (int q_ = 0; q_ < 8; ++q_) { \
;             const int ia_ = __builtin_amdgcn_readfirstlane((ep_)[2 * q_]), ib_ = __builtin_amdgcn_readfirstlane((ep_)[2 * q_ + 1]); \
;             ra[q_] = *(const u32x4*)(REC + (size_t)ia_ * 1024); rb[q_] = *(const u32x4*)(REC + (size_t)ib_ * 1024); } } while (0)
; DI void peer_phase(const Params& p, int layer, bool dry) {
;     ...
;             if (bt < 7) { const int nb = bt + 1; const int isrc = (nb < 4) ? iv0 : iv1; const int lb = (nb & 3) * 16; PEER_LOADREC_FROM(isrc, lb); }
;             else PEER_LOADREC_MEM(eidx + (size_t)tn * 128);
.LBB0_36:
	s_cmpk_lg_i32 s21, 0x70
	s_mov_b64 s[72:73], -1
	s_cbranch_scc0 .LBB0_38
	s_cmp_lt_u32 s11, 3
	s_cselect_b64 vcc, -1, 0
	s_waitcnt vmcnt(6)
	v_cndmask_b32_e32 v64, v225, v218, vcc
	v_lshlrev_b32_e32 v64, 10, v64
	s_add_i32 s29, s21, 18
	v_readlane_b32 s30, v64, s29
	s_add_i32 s29, s21, 19
	v_readlane_b32 s40, v64, s29
	s_add_i32 s29, s21, 20
	v_readlane_b32 s34, v64, s29
	s_add_i32 s29, s21, 21
	v_readlane_b32 s38, v64, s29
	s_add_i32 s29, s21, 22
	v_readlane_b32 s50, v64, s29
	s_add_i32 s29, s21, 23
	v_readlane_b32 s48, v64, s29
	s_add_i32 s29, s21, 24
	v_readlane_b32 s54, v64, s29
	s_add_i32 s29, s21, 25
	v_readlane_b32 s46, v64, s29
	s_add_i32 s29, s21, 26
	v_readlane_b32 s58, v64, s29
	s_add_i32 s29, s21, 27
	v_readlane_b32 s36, v64, s29
	s_add_i32 s29, s21, 28
	v_readlane_b32 s62, v64, s29
	s_add_i32 s29, s21, 29
	v_readlane_b32 s52, v64, s29
	s_add_i32 s29, s21, 30
	s_add_i32 s27, s21, 16
	s_add_i32 s26, s21, 17
	v_readlane_b32 s64, v64, s29
	s_add_i32 s29, s21, 31
	v_readlane_b32 s28, v64, s27
	v_readlane_b32 s26, v64, s26
	v_readlane_b32 s56, v64, s29
	s_and_b32 s60, s21, 48
	s_mov_b64 s[72:73], 0
	s_mov_b32 s21, s27
.LBB0_38:
	s_andn2_b64 vcc, exec, s[72:73]
	s_cbranch_vccnz .LBB0_35
	v_lshlrev_b32_e32 v70, 2, v96
	s_add_u32 s40, s76, s0
	s_addc_u32 s41, s77, s1
	global_load_dword v218, v70, s[24:25]
	global_load_dword v98, v70, s[24:25] offset:256
	global_load_dword v226, v70, s[40:41]
	global_load_dword v99, v70, s[40:41] offset:256
	s_mov_b32 s60, 48
	s_movk_i32 s21, 0x80
	s_waitcnt vmcnt(0)
	v_lshrrev_b32_e32 v64, 11, v218
	v_lshrrev_b32_e32 v65, 11, v98
	s_mov_b32 s36, 0
	v_cmp_eq_u32_e64 s[28:29], 0, v64
	v_cmp_eq_u32_e64 s[30:31], 0, v65
	s_bcnt1_i32_b64 s34, s[28:29]
	s_bcnt1_i32_b64 s35, s[30:31]
	v_mbcnt_lo_u32_b32 v68, s28, 0
	v_mbcnt_hi_u32_b32 v68, s29, v68
	v_mbcnt_lo_u32_b32 v69, s30, 0
	v_mbcnt_hi_u32_b32 v69, s31, v69
	v_add_u32_e32 v68, s36, v68
	s_add_i32 s36, s36, s34
	v_add_u32_e32 v69, s36, v69
	s_add_i32 s36, s36, s35
	v_cndmask_b32_e64 v66, v66, v68, s[28:29]
	v_cndmask_b32_e64 v67, v67, v69, s[30:31]
	v_cmp_eq_u32_e64 s[28:29], 1, v64
	v_cmp_eq_u32_e64 s[30:31], 1, v65
	s_bcnt1_i32_b64 s34, s[28:29]
	s_bcnt1_i32_b64 s35, s[30:31]
	v_mbcnt_lo_u32_b32 v68, s28, 0
	v_mbcnt_hi_u32_b32 v68, s29, v68
	v_mbcnt_lo_u32_b32 v69, s30, 0
	v_mbcnt_hi_u32_b32 v69, s31, v69
	v_add_u32_e32 v68, s36, v68
	s_add_i32 s36, s36, s34
	v_add_u32_e32 v69, s36, v69
	s_add_i32 s36, s36, s35
	v_cndmask_b32_e64 v66, v66, v68, s[28:29]
	v_cndmask_b32_e64 v67, v67, v69, s[30:31]
	v_cmp_eq_u32_e64 s[28:29], 2, v64
	v_cmp_eq_u32_e64 s[30:31], 2, v65
	s_bcnt1_i32_b64 s34, s[28:29]
	s_bcnt1_i32_b64 s35, s[30:31]
	v_mbcnt_lo_u32_b32 v68, s28, 0
	v_mbcnt_hi_u32_b32 v68, s29, v68
	v_mbcnt_lo_u32_b32 v69, s30, 0
	v_mbcnt_hi_u32_b32 v69, s31, v69
	v_add_u32_e32 v68, s36, v68
	s_add_i32 s36, s36, s34
	v_add_u32_e32 v69, s36, v69
	s_add_i32 s36, s36, s35
	v_cndmask_b32_e64 v66, v66, v68, s[28:29]
	v_cndmask_b32_e64 v67, v67, v69, s[30:31]
	v_cmp_eq_u32_e64 s[28:29], 3, v64
	v_cmp_eq_u32_e64 s[30:31], 3, v65
	s_bcnt1_i32_b64 s34, s[28:29]
	s_bcnt1_i32_b64 s35, s[30:31]
	v_mbcnt_lo_u32_b32 v68, s28, 0
	v_mbcnt_hi_u32_b32 v68, s29, v68
	v_mbcnt_lo_u32_b32 v69, s30, 0
	v_mbcnt_hi_u32_b32 v69, s31, v69
	v_add_u32_e32 v68, s36, v68
	s_add_i32 s36, s36, s34
	v_add_u32_e32 v69, s36, v69
	s_add_i32 s36, s36, s35
	v_cndmask_b32_e64 v66, v66, v68, s[28:29]
	v_cndmask_b32_e64 v67, v67, v69, s[30:31]
	v_cmp_eq_u32_e64 s[28:29], 4, v64
	v_cmp_eq_u32_e64 s[30:31], 4, v65
	s_bcnt1_i32_b64 s34, s[28:29]
	s_bcnt1_i32_b64 s35, s[30:31]
	v_mbcnt_lo_u32_b32 v68, s28, 0
	v_mbcnt_hi_u32_b32 v68, s29, v68
	v_mbcnt_lo_u32_b32 v69, s30, 0
	v_mbcnt_hi_u32_b32 v69, s31, v69
	v_add_u32_e32 v68, s36, v68
	s_add_i32 s36, s36, s34
	v_add_u32_e32 v69, s36, v69
	s_add_i32 s36, s36, s35
	v_cndmask_b32_e64 v66, v66, v68, s[28:29]
	v_cndmask_b32_e64 v67, v67, v69, s[30:31]
	v_cmp_eq_u32_e64 s[28:29], 5, v64
	v_cmp_eq_u32_e64 s[30:31], 5, v65
	s_bcnt1_i32_b64 s34, s[28:29]
	s_bcnt1_i32_b64 s35, s[30:31]
	v_mbcnt_lo_u32_b32 v68, s28, 0
	v_mbcnt_hi_u32_b32 v68, s29, v68
	v_mbcnt_lo_u32_b32 v69, s30, 0
	v_mbcnt_hi_u32_b32 v69, s31, v69
	v_add_u32_e32 v68, s36, v68
	s_add_i32 s36, s36, s34
	v_add_u32_e32 v69, s36, v69
	s_add_i32 s36, s36, s35
	v_cndmask_b32_e64 v66, v66, v68, s[28:29]
	v_cndmask_b32_e64 v67, v67, v69, s[30:31]
	v_cmp_eq_u32_e64 s[28:29], 6, v64
	v_cmp_eq_u32_e64 s[30:31], 6, v65
	s_bcnt1_i32_b64 s34, s[28:29]
	s_bcnt1_i32_b64 s35, s[30:31]
	v_mbcnt_lo_u32_b32 v68, s28, 0
	v_mbcnt_hi_u32_b32 v68, s29, v68
	v_mbcnt_lo_u32_b32 v69, s30, 0
	v_mbcnt_hi_u32_b32 v69, s31, v69
	v_add_u32_e32 v68, s36, v68
	s_add_i32 s36, s36, s34
	v_add_u32_e32 v69, s36, v69
	s_add_i32 s36, s36, s35
	v_cndmask_b32_e64 v66, v66, v68, s[28:29]
	v_cndmask_b32_e64 v67, v67, v69, s[30:31]
	v_cmp_eq_u32_e64 s[28:29], 7, v64
	v_cmp_eq_u32_e64 s[30:31], 7, v65
	s_bcnt1_i32_b64 s34, s[28:29]
	s_bcnt1_i32_b64 s35, s[30:31]
	v_mbcnt_lo_u32_b32 v68, s28, 0
	v_mbcnt_hi_u32_b32 v68, s29, v68
	v_mbcnt_lo_u32_b32 v69, s30, 0
	v_mbcnt_hi_u32_b32 v69, s31, v69
	v_add_u32_e32 v68, s36, v68
	s_add_i32 s36, s36, s34
	v_add_u32_e32 v69, s36, v69
	s_add_i32 s36, s36, s35
	v_cndmask_b32_e64 v66, v66, v68, s[28:29]
	v_cndmask_b32_e64 v67, v67, v69, s[30:31]
	v_lshl_add_u32 v71, v66, 2, s32
	v_lshl_add_u32 v72, v67, 2, s32
	v_lshl_add_u32 v70, v96, 2, s32
	ds_write_b32 v71, v218
	ds_write_b32 v72, v98
	ds_write_b32 v71, v226 offset:512
	ds_write_b32 v72, v99 offset:512
	s_waitcnt lgkmcnt(0)
	ds_read_b32 v218, v70
	ds_read_b32 v98, v70 offset:256
	ds_read_b32 v226, v70 offset:512
	ds_read_b32 v99, v70 offset:768
	s_waitcnt lgkmcnt(0)
	v_lshlrev_b32_e32 v64, 10, v218
	s_nop 0
	v_readlane_b32 s28, v64, 0
	v_readlane_b32 s26, v64, 1
	v_readlane_b32 s30, v64, 2
	v_readlane_b32 s40, v64, 3
	v_readlane_b32 s34, v64, 4
	v_readlane_b32 s38, v64, 5
	v_readlane_b32 s50, v64, 6
	v_readlane_b32 s48, v64, 7
	v_readlane_b32 s54, v64, 8
	v_readlane_b32 s46, v64, 9
	v_readlane_b32 s58, v64, 10
	v_readlane_b32 s36, v64, 11
	v_readlane_b32 s62, v64, 12
	v_readlane_b32 s52, v64, 13
	v_readlane_b32 s64, v64, 14
	v_readlane_b32 s56, v64, 15
	s_branch .LBB0_35

; #define MFMA32(a, b, c) __builtin_amdgcn_mfma_f32_32x32x16_bf16((a), (b), (c), 0, 0, 0)
; DI unsigned fkey(float f) { const unsigned u = __float_as_uint(f); return (u & 0x80000000u) ? ~u : (u | 0x80000000u); }
; #define TK_PREFETCH(t_, p_) do { const int tk0_ = ((t_) >> 3) * 64, hp_ = ((t_) & 7) * 2 + (p_); \
;         _Pragma("unroll") for (int i_ = 0; i_ < 4; ++i_) { const int c_ = tid + 256 * i_; pre[i_] = *(const u32x4*)(qp + (size_t)(tk0_ + (c_ >> 4)) * 2048 + hp_ * 128 + (c_ & 15) * 8); } } while (0)
; DI void topk_phase(unsigned char* smem_, const bf16_t* __restrict__ qp, const bf16_t* __restrict__ keys, int* __restrict__ eidx, float* __restrict__ gate) {
;     ...
;     for (int p = 0; p < 2; ++p) {
; #pragma unroll
;         for (int i = 0; i < 4; ++i) { const int c = tid + 256 * i; *(u32x4*)(As + (c >> 4) * LDA + (c & 15) * 8) = pre[i]; }
;         __syncthreads();
;         f32x16 acc[2];
; #pragma unroll
;         for (int i = 0; i < 16; ++i) { acc[0][i] = 0.f; acc[1][i] = 0.f; }
; #pragma unroll
;         for (int ks = 0; ks < 8; ++ks) {
; #pragma unroll
;             for (int th = 0; th < 2; ++th) { const bf16x8 qf = *(const bf16x8*)(As + (32 * th + l31) * LDA + ks * 16 + hi * 8); acc[th] = MFMA32(kf[p][ks], qf, acc[th]); }
;         }
; #pragma unroll
;         for (int th = 0; th < 2; ++th)
; #pragma unroll
;             for (int g = 0; g < 4; ++g) { f32x4 o; o.x = acc[th][4 * g]; o.y = acc[th][4 * g + 1]; o.z = acc[th][4 * g + 2]; o.w = acc[th][4 * g + 3]; *(f32x4*)(S + (32 * th + l31) * LDS_ + 32 * wid + 8 * g + 4 * hi) = o; }
;         __syncthreads();
;         if (p == 0) TK_PREFETCH(t, 1); else if (t + G < NT) TK_PREFETCH(t + G, 0);
;         unsigned v[32];
; #pragma unroll
;         for (int i = 0; i < 8; ++i) {
;             const f32x4 sv4 = *(const f32x4*)(S + row * LDS_ + 32 * q + 4 * i);
;             const int ib = 127 - (32 * q + 4 * i);
;             v[4 * i] = (fkey(sv4.x) & ~127u) | (unsigned)ib; v[4 * i + 1] = (fkey(sv4.y) & ~127u) | (unsigned)(ib - 1);
;             v[4 * i + 2] = (fkey(sv4.z) & ~127u) | (unsigned)(ib - 2); v[4 * i + 3] = (fkey(sv4.w) & ~127u) | (unsigned)(ib - 3);
.LBB0_57:
	s_waitcnt vmcnt(0)
	ds_write_b128 v234, v[96:99]
	ds_write_b128 v234, v[100:103] offset:4352
	ds_write_b128 v234, v[104:107] offset:8704
	ds_write_b128 v234, v[108:111] offset:13056
	s_waitcnt lgkmcnt(0)
	s_barrier
	ds_read_b128 v[0:3], v235
	ds_read_b128 v[96:99], v235 offset:32
	s_waitcnt lgkmcnt(1)
	v_mfma_f32_32x32x16_bf16 v[16:31], v[32:35], v[0:3], 0
	ds_read_b128 v[0:3], v235 offset:8704
	s_and_b32 s24, s22, 0xffffffc0
	s_lshl_b32 s0, s0, 1
	s_add_u32 s0, s86, s0
	s_addc_u32 s1, s87, 0
	s_waitcnt lgkmcnt(1)
	v_mfma_f32_32x32x16_bf16 v[16:31], v[36:39], v[96:99], v[16:31]
	ds_read_b128 v[96:99], v235 offset:8736
	s_waitcnt lgkmcnt(1)
	v_mfma_f32_32x32x16_bf16 v[0:15], v[32:35], v[0:3], 0
	s_waitcnt lgkmcnt(0)
	v_mfma_f32_32x32x16_bf16 v[0:15], v[36:39], v[96:99], v[0:15]
	ds_read_b128 v[96:99], v235 offset:64
	s_waitcnt lgkmcnt(0)
	v_mfma_f32_32x32x16_bf16 v[16:31], v[40:43], v[96:99], v[16:31]
	ds_read_b128 v[96:99], v235 offset:8768
	s_waitcnt lgkmcnt(0)
	v_mfma_f32_32x32x16_bf16 v[0:15], v[40:43], v[96:99], v[0:15]
	ds_read_b128 v[96:99], v235 offset:96
	s_waitcnt lgkmcnt(0)
	v_mfma_f32_32x32x16_bf16 v[16:31], v[44:47], v[96:99], v[16:31]
	ds_read_b128 v[96:99], v235 offset:8800
	s_waitcnt lgkmcnt(0)
	v_mfma_f32_32x32x16_bf16 v[0:15], v[44:47], v[96:99], v[0:15]
	ds_read_b128 v[96:99], v235 offset:128
	s_waitcnt lgkmcnt(0)
	v_mfma_f32_32x32x16_bf16 v[16:31], v[48:51], v[96:99], v[16:31]
	ds_read_b128 v[96:99], v235 offset:8832
	s_waitcnt lgkmcnt(0)
	v_mfma_f32_32x32x16_bf16 v[0:15], v[48:51], v[96:99], v[0:15]
	ds_read_b128 v[96:99], v235 offset:160
	s_waitcnt lgkmcnt(0)
	v_mfma_f32_32x32x16_bf16 v[16:31], v[52:55], v[96:99], v[16:31]
	ds_read_b128 v[96:99], v235 offset:8864
	s_waitcnt lgkmcnt(0)
	v_mfma_f32_32x32x16_bf16 v[0:15], v[52:55], v[96:99], v[0:15]
	ds_read_b128 v[96:99], v235 offset:192
	s_waitcnt lgkmcnt(0)
	v_mfma_f32_32x32x16_bf16 v[16:31], v[56:59], v[96:99], v[16:31]
	ds_read_b128 v[96:99], v235 offset:8896
	s_waitcnt lgkmcnt(0)
	v_mfma_f32_32x32x16_bf16 v[0:15], v[56:59], v[96:99], v[0:15]
	ds_read_b128 v[96:99], v235 offset:224
	s_waitcnt lgkmcnt(0)
	v_mfma_f32_32x32x16_bf16 v[16:31], v[60:63], v[96:99], v[16:31]
	ds_read_b128 v[96:99], v235 offset:8928
	s_nop 10
	ds_write_b128 v236, v[16:19] offset:17408
	ds_write_b128 v236, v[20:23] offset:17440
	ds_write_b128 v236, v[24:27] offset:17472
	ds_write_b128 v236, v[28:31] offset:17504
	s_waitcnt lgkmcnt(4)
	v_mfma_f32_32x32x16_bf16 v[0:15], v[60:63], v[96:99], v[0:15]
	s_nop 11
	ds_write_b128 v236, v[0:3] offset:34304
	ds_write_b128 v236, v[4:7] offset:34336
	ds_write_b128 v236, v[8:11] offset:34368
	ds_write_b128 v236, v[12:15] offset:34400
	v_or_b32_e32 v0, s24, v165
	v_ashrrev_i32_e32 v1, 31, v0
	v_lshlrev_b64 v[0:1], 12, v[0:1]
	v_lshl_add_u64 v[0:1], s[0:1], 0, v[0:1]
	v_lshl_add_u64 v[0:1], v[0:1], 0, v[128:129]
	s_waitcnt lgkmcnt(0)
	s_barrier
	global_load_dwordx4 v[96:99], v[0:1], off offset:256
	v_or_b32_e32 v0, s24, v166
	v_ashrrev_i32_e32 v1, 31, v0
	v_lshlrev_b64 v[0:1], 12, v[0:1]
	v_lshl_add_u64 v[0:1], s[0:1], 0, v[0:1]
	v_lshl_add_u64 v[0:1], v[0:1], 0, v[128:129]
	global_load_dwordx4 v[100:103], v[0:1], off offset:256
	v_or_b32_e32 v0, s24, v167
	v_ashrrev_i32_e32 v1, 31, v0
	v_lshlrev_b64 v[0:1], 12, v[0:1]
	v_lshl_add_u64 v[0:1], s[0:1], 0, v[0:1]
	v_lshl_add_u64 v[0:1], v[0:1], 0, v[128:129]
	global_load_dwordx4 v[104:107], v[0:1], off offset:256
	v_or_b32_e32 v0, s24, v168
	v_ashrrev_i32_e32 v1, 31, v0
	v_lshlrev_b64 v[0:1], 12, v[0:1]
	v_lshl_add_u64 v[0:1], s[0:1], 0, v[0:1]
	v_lshl_add_u64 v[4:5], v[0:1], 0, v[128:129]
	ds_read_b128 v[0:3], v171 offset:17408
	global_load_dwordx4 v[108:111], v[4:5], off offset:256
	ds_read_b128 v[4:7], v171 offset:17424
	ds_read_b128 v[8:11], v171 offset:17440
	ds_read_b128 v[12:15], v171 offset:17456
	s_waitcnt lgkmcnt(3)
	v_not_b32_e32 v16, v0
	v_or_b32_e32 v17, 0x80000000, v0
	v_cmp_gt_i32_e32 vcc, 0, v0
	s_waitcnt lgkmcnt(0)
	v_not_b32_e32 v20, v15
	v_or_b32_e32 v21, 0x80000000, v15
	v_cndmask_b32_e32 v0, v17, v16, vcc
	v_not_b32_e32 v16, v1
	v_or_b32_e32 v17, 0x80000000, v1
	v_cmp_gt_i32_e32 vcc, 0, v1
	v_and_b32_e32 v0, 0xffffff80, v0
	v_sub_u32_e32 v0, v0, v170
	v_cndmask_b32_e32 v1, v17, v16, vcc
	v_not_b32_e32 v16, v2
	v_or_b32_e32 v17, 0x80000000, v2
	v_cmp_gt_i32_e32 vcc, 0, v2
	v_and_b32_e32 v1, 0xffffff80, v1
	v_sub_u32_e32 v1, v1, v170
	v_cndmask_b32_e32 v2, v17, v16, vcc
	v_not_b32_e32 v16, v3
	v_or_b32_e32 v17, 0x80000000, v3
	v_cmp_gt_i32_e32 vcc, 0, v3
	v_and_b32_e32 v2, 0xffffff80, v2
	v_sub_u32_e32 v2, v2, v170
	v_cndmask_b32_e32 v3, v17, v16, vcc
	v_not_b32_e32 v16, v4
	v_or_b32_e32 v17, 0x80000000, v4
	v_cmp_gt_i32_e32 vcc, 0, v4
	v_and_b32_e32 v3, 0xffffff80, v3
	v_sub_u32_e32 v3, v3, v170
	v_cndmask_b32_e32 v4, v17, v16, vcc
	v_not_b32_e32 v16, v5
	v_or_b32_e32 v17, 0x80000000, v5
	v_cmp_gt_i32_e32 vcc, 0, v5
	v_and_b32_e32 v4, 0xffffff80, v4
	v_sub_u32_e32 v4, v4, v177
	v_cndmask_b32_e32 v5, v17, v16, vcc
	v_not_b32_e32 v16, v6
	v_or_b32_e32 v17, 0x80000000, v6
	v_cmp_gt_i32_e32 vcc, 0, v6
	v_and_b32_e32 v5, 0xffffff80, v5
	v_sub_u32_e32 v5, v5, v177
	v_cndmask_b32_e32 v6, v17, v16, vcc
	v_not_b32_e32 v16, v7
	v_or_b32_e32 v17, 0x80000000, v7
	v_cmp_gt_i32_e32 vcc, 0, v7
	v_and_b32_e32 v6, 0xffffff80, v6
	v_sub_u32_e32 v6, v6, v177
	v_cndmask_b32_e32 v7, v17, v16, vcc
	v_not_b32_e32 v16, v8
	v_or_b32_e32 v17, 0x80000000, v8
	v_cmp_gt_i32_e32 vcc, 0, v8
	v_and_b32_e32 v7, 0xffffff80, v7
	v_sub_u32_e32 v7, v7, v177
	v_cndmask_b32_e32 v8, v17, v16, vcc
	v_not_b32_e32 v16, v9
	v_or_b32_e32 v17, 0x80000000, v9
	v_cmp_gt_i32_e32 vcc, 0, v9
	v_and_b32_e32 v8, 0xffffff80, v8
; DI unsigned fkey(float f) { const unsigned u = __float_as_uint(f); return (u & 0x80000000u) ? ~u : (u | 0x80000000u); }
; DI void topk_phase(unsigned char* smem_, const bf16_t* __restrict__ qp, const bf16_t* __restrict__ keys, int* __restrict__ eidx, float* __restrict__ gate) {
;     ...
;             const f32x4 sv4 = *(const f32x4*)(S + row * LDS_ + 32 * q + 4 * i);
;             const int ib = 127 - (32 * q + 4 * i);
;             v[4 * i] = (fkey(sv4.x) & ~127u) | (unsigned)ib; v[4 * i + 1] = (fkey(sv4.y) & ~127u) | (unsigned)(ib - 1);
;             v[4 * i + 2] = (fkey(sv4.z) & ~127u) | (unsigned)(ib - 2); v[4 * i + 3] = (fkey(sv4.w) & ~127u) | (unsigned)(ib - 3);
	v_sub_u32_e32 v8, v8, v178
	v_cndmask_b32_e32 v9, v17, v16, vcc
	v_not_b32_e32 v16, v10
	v_or_b32_e32 v17, 0x80000000, v10
	v_cmp_gt_i32_e32 vcc, 0, v10
	v_and_b32_e32 v9, 0xffffff80, v9
	v_sub_u32_e32 v9, v9, v178
	v_cndmask_b32_e32 v10, v17, v16, vcc
	v_and_b32_e32 v10, 0xffffff80, v10
	v_sub_u32_e32 v10, v10, v178
	v_add_u32_e32 v16, 0x7d, v10
	v_not_b32_e32 v10, v11
	v_or_b32_e32 v17, 0x80000000, v11
	v_cmp_gt_i32_e32 vcc, 0, v11
	v_or_b32_e32 v11, 0x80000000, v12
	v_add_u32_e32 v0, 0x7f, v0
	v_cndmask_b32_e32 v10, v17, v10, vcc
	v_and_b32_e32 v10, 0xffffff80, v10
	v_sub_u32_e32 v10, v10, v178
	v_add_u32_e32 v17, 0x7c, v10
	v_not_b32_e32 v10, v12
	v_cmp_gt_i32_e32 vcc, 0, v12
	v_add_u32_e32 v1, 0x7e, v1
	v_add_u32_e32 v2, 0x7d, v2
	v_cndmask_b32_e32 v10, v11, v10, vcc
	v_and_b32_e32 v10, 0xffffff80, v10
	v_sub_u32_e32 v10, v10, v179
	v_add_u32_e32 v18, 0x7f, v10
	v_not_b32_e32 v10, v13
	v_or_b32_e32 v11, 0x80000000, v13
	v_cmp_gt_i32_e32 vcc, 0, v13
	v_add_u32_e32 v3, 0x7c, v3
	v_add_u32_e32 v4, 0x7f, v4
	v_cndmask_b32_e32 v10, v11, v10, vcc
	v_and_b32_e32 v10, 0xffffff80, v10
	v_sub_u32_e32 v10, v10, v179
	v_add_u32_e32 v19, 0x7e, v10
	v_not_b32_e32 v10, v14
	v_or_b32_e32 v11, 0x80000000, v14
	v_cmp_gt_i32_e32 vcc, 0, v14
	v_add_u32_e32 v5, 0x7e, v5
	v_add_u32_e32 v6, 0x7d, v6
	v_cndmask_b32_e32 v10, v11, v10, vcc
	v_and_b32_e32 v10, 0xffffff80, v10
	v_sub_u32_e32 v10, v10, v179
	v_add_u32_e32 v14, 0x7d, v10
	ds_read_b128 v[10:13], v171 offset:17472
	v_cmp_gt_i32_e32 vcc, 0, v15
	v_add_u32_e32 v7, 0x7c, v7
	v_add_u32_e32 v8, 0x7f, v8
	v_cndmask_b32_e32 v15, v21, v20, vcc
	s_waitcnt lgkmcnt(0)
	v_not_b32_e32 v20, v10
	v_or_b32_e32 v21, 0x80000000, v10
	v_cmp_gt_i32_e32 vcc, 0, v10
	v_not_b32_e32 v23, v13
	v_or_b32_e32 v24, 0x80000000, v13
	v_cndmask_b32_e32 v10, v21, v20, vcc
	v_and_b32_e32 v10, 0xffffff80, v10
	v_sub_u32_e32 v10, v10, v180
	v_add_u32_e32 v20, 0x7f, v10
	v_not_b32_e32 v10, v11
	v_or_b32_e32 v21, 0x80000000, v11
	v_cmp_gt_i32_e32 vcc, 0, v11
	v_or_b32_e32 v11, 0x80000000, v12
	v_and_b32_e32 v15, 0xffffff80, v15
	v_cndmask_b32_e32 v10, v21, v10, vcc
	v_and_b32_e32 v10, 0xffffff80, v10
	v_sub_u32_e32 v10, v10, v180
	v_add_u32_e32 v21, 0x7e, v10
	v_not_b32_e32 v10, v12
	v_cmp_gt_i32_e32 vcc, 0, v12
	v_sub_u32_e32 v15, v15, v179
	v_add_u32_e32 v9, 0x7e, v9
	v_cndmask_b32_e32 v10, v11, v10, vcc
	v_and_b32_e32 v10, 0xffffff80, v10
	v_sub_u32_e32 v10, v10, v180
	v_add_u32_e32 v22, 0x7d, v10
	v_cmp_gt_i32_e32 vcc, 0, v13
	ds_read_b128 v[10:13], v171 offset:17488
	v_add_u32_e32 v15, 0x7c, v15
	v_cndmask_b32_e32 v23, v24, v23, vcc
	v_and_b32_e32 v23, 0xffffff80, v23
	v_sub_u32_e32 v23, v23, v180
	s_waitcnt lgkmcnt(0)
	v_not_b32_e32 v24, v10
	v_or_b32_e32 v25, 0x80000000, v10
	v_cmp_gt_i32_e32 vcc, 0, v10
	v_not_b32_e32 v27, v13
	v_or_b32_e32 v28, 0x80000000, v13
	v_cndmask_b32_e32 v10, v25, v24, vcc
	v_and_b32_e32 v10, 0xffffff80, v10
	v_sub_u32_e32 v10, v10, v181
	v_add_u32_e32 v24, 0x7f, v10
	v_not_b32_e32 v10, v11
	v_or_b32_e32 v25, 0x80000000, v11
	v_cmp_gt_i32_e32 vcc, 0, v11
	v_or_b32_e32 v11, 0x80000000, v12
	v_add_u32_e32 v23, 0x7c, v23
	v_cndmask_b32_e32 v10, v25, v10, vcc
	v_and_b32_e32 v10, 0xffffff80, v10
	v_sub_u32_e32 v10, v10, v181
	v_add_u32_e32 v25, 0x7e, v10
	v_not_b32_e32 v10, v12
	v_cmp_gt_i32_e32 vcc, 0, v12
	s_nop 1
	v_cndmask_b32_e32 v10, v11, v10, vcc
	v_and_b32_e32 v10, 0xffffff80, v10
	v_sub_u32_e32 v10, v10, v181
	v_add_u32_e32 v26, 0x7d, v10
	v_cmp_gt_i32_e32 vcc, 0, v13
	ds_read_b128 v[10:13], v171 offset:17504
	s_waitcnt lgkmcnt(0)
	v_or_b32_e32 v29, 0x80000000, v10
	v_cndmask_b32_e32 v27, v28, v27, vcc
	v_not_b32_e32 v28, v10
	v_cmp_gt_i32_e32 vcc, 0, v10
	v_not_b32_e32 v31, v13
	v_or_b32_e32 v116, 0x80000000, v13
	v_cndmask_b32_e32 v10, v29, v28, vcc
	v_and_b32_e32 v10, 0xffffff80, v10
	v_sub_u32_e32 v10, v10, v182
	v_add_u32_e32 v28, 0x7f, v10
	v_not_b32_e32 v10, v11
	v_or_b32_e32 v29, 0x80000000, v11
	v_cmp_gt_i32_e32 vcc, 0, v11
	v_or_b32_e32 v11, 0x80000000, v12
	v_and_b32_e32 v27, 0xffffff80, v27
	v_cndmask_b32_e32 v10, v29, v10, vcc
	v_and_b32_e32 v10, 0xffffff80, v10
	v_sub_u32_e32 v10, v10, v182
	v_add_u32_e32 v29, 0x7e, v10
	v_not_b32_e32 v10, v12
	v_cmp_gt_i32_e32 vcc, 0, v12
	v_sub_u32_e32 v27, v27, v181
	v_add_u32_e32 v27, 0x7c, v27
	v_cndmask_b32_e32 v10, v11, v10, vcc
	v_and_b32_e32 v10, 0xffffff80, v10
	v_sub_u32_e32 v10, v10, v182
	v_add_u32_e32 v30, 0x7d, v10
	v_cmp_gt_i32_e32 vcc, 0, v13
	ds_read_b128 v[10:13], v171 offset:17520
	s_waitcnt lgkmcnt(0)
; DI unsigned fkey(float f) { const unsigned u = __float_as_uint(f); return (u & 0x80000000u) ? ~u : (u | 0x80000000u); }
; template <int N> DI void bitonic_sort_desc(unsigned (&v)[N]) {
; #pragma unroll
;     for (int k = 2; k <= N; k <<= 1)
; #pragma unroll
;         for (int j = k >> 1; j > 0; j >>= 1)
; #pragma unroll
;             for (int i = 0; i < N; ++i) { const int l = i ^ j; if (l > i) { if ((i & k) == 0) cswap(v[i], v[l]); else cswap(v[l], v[i]); } }
; }
; DI void topk_phase(unsigned char* smem_, const bf16_t* __restrict__ qp, const bf16_t* __restrict__ keys, int* __restrict__ eidx, float* __restrict__ gate) {
;     ...
;             v[4 * i] = (fkey(sv4.x) & ~127u) | (unsigned)ib; v[4 * i + 1] = (fkey(sv4.y) & ~127u) | (unsigned)(ib - 1);
;             v[4 * i + 2] = (fkey(sv4.z) & ~127u) | (unsigned)(ib - 2); v[4 * i + 3] = (fkey(sv4.w) & ~127u) | (unsigned)(ib - 3);
;         }
;         bitonic_sort_desc<32>(v);
	v_or_b32_e32 v117, 0x80000000, v10
	v_cndmask_b32_e32 v31, v116, v31, vcc
	v_not_b32_e32 v116, v10
	v_cmp_gt_i32_e32 vcc, 0, v10
	v_and_b32_e32 v31, 0xffffff80, v31
	v_sub_u32_e32 v31, v31, v182
	v_cndmask_b32_e32 v10, v117, v116, vcc
	v_not_b32_e32 v116, v11
	v_or_b32_e32 v117, 0x80000000, v11
	v_cmp_gt_i32_e32 vcc, 0, v11
	v_and_b32_e32 v10, 0xffffff80, v10
	v_sub_u32_e32 v10, v10, v183
	v_cndmask_b32_e32 v11, v117, v116, vcc
	v_not_b32_e32 v116, v12
	v_or_b32_e32 v117, 0x80000000, v12
	v_cmp_gt_i32_e32 vcc, 0, v12
	v_and_b32_e32 v11, 0xffffff80, v11
	v_sub_u32_e32 v11, v11, v183
	v_cndmask_b32_e32 v12, v117, v116, vcc
	v_not_b32_e32 v116, v13
	v_or_b32_e32 v117, 0x80000000, v13
	v_cmp_gt_i32_e32 vcc, 0, v13
	v_and_b32_e32 v12, 0xffffff80, v12
	v_sub_u32_e32 v12, v12, v183
	v_cndmask_b32_e32 v13, v117, v116, vcc
	v_and_b32_e32 v13, 0xffffff80, v13
	v_sub_u32_e32 v13, v13, v183
	v_add_u32_e32 v31, 0x7c, v31
	v_add_u32_e32 v10, 0x7f, v10
	v_add_u32_e32 v11, 0x7e, v11
	v_add_u32_e32 v12, 0x7d, v12
	v_add_u32_e32 v13, 0x7c, v13
	v_max_u32_e32 v116, v0, v1
	v_min_u32_e32 v0, v0, v1
	v_max_u32_e32 v1, v3, v2
	v_min_u32_e32 v2, v3, v2
	v_max_u32_e32 v3, v4, v5
	v_min_u32_e32 v4, v4, v5
	v_max_u32_e32 v5, v7, v6
	v_min_u32_e32 v6, v7, v6
	v_max_u32_e32 v7, v8, v9
	v_min_u32_e32 v8, v8, v9
	v_max_u32_e32 v9, v17, v16
	v_min_u32_e32 v16, v17, v16
	v_max_u32_e32 v17, v18, v19
	v_min_u32_e32 v18, v18, v19
	v_max_u32_e32 v19, v15, v14
	v_min_u32_e32 v14, v15, v14
	v_max_u32_e32 v15, v20, v21
	v_min_u32_e32 v20, v20, v21
	v_max_u32_e32 v21, v23, v22
	v_min_u32_e32 v22, v23, v22
	v_max_u32_e32 v23, v24, v25
	v_min_u32_e32 v24, v24, v25
	v_max_u32_e32 v25, v27, v26
	v_min_u32_e32 v26, v27, v26
	v_max_u32_e32 v27, v28, v29
	v_min_u32_e32 v28, v28, v29
	v_max_u32_e32 v29, v31, v30
	v_min_u32_e32 v30, v31, v30
	v_max_u32_e32 v31, v10, v11
	v_min_u32_e32 v10, v10, v11
	v_max_u32_e32 v11, v13, v12
	v_min_u32_e32 v12, v13, v12
	v_max_u32_e32 v13, v116, v2
	v_min_u32_e32 v2, v116, v2
	v_max_u32_e32 v116, v0, v1
	v_min_u32_e32 v0, v0, v1
	v_max_u32_e32 v1, v6, v3
	v_min_u32_e32 v3, v6, v3
	v_max_u32_e32 v6, v5, v4
	v_min_u32_e32 v4, v5, v4
	v_max_u32_e32 v5, v7, v16
	v_min_u32_e32 v7, v7, v16
	v_max_u32_e32 v16, v8, v9
	v_min_u32_e32 v8, v8, v9
	v_max_u32_e32 v9, v14, v17
	v_min_u32_e32 v14, v14, v17
	v_max_u32_e32 v17, v19, v18
	v_min_u32_e32 v18, v19, v18
	v_max_u32_e32 v19, v15, v22
	v_min_u32_e32 v15, v15, v22
	v_max_u32_e32 v22, v20, v21
	v_min_u32_e32 v20, v20, v21
	v_max_u32_e32 v21, v26, v23
	v_min_u32_e32 v23, v26, v23
	v_max_u32_e32 v26, v25, v24
	v_min_u32_e32 v24, v25, v24
	v_max_u32_e32 v25, v27, v30
	v_min_u32_e32 v27, v27, v30
	v_max_u32_e32 v30, v28, v29
	v_min_u32_e32 v28, v28, v29
	v_max_u32_e32 v29, v12, v31
	v_min_u32_e32 v12, v12, v31
	v_max_u32_e32 v31, v11, v10
	v_min_u32_e32 v10, v11, v10
	v_max_u32_e32 v11, v13, v116
	v_min_u32_e32 v13, v13, v116
	v_max_u32_e32 v116, v2, v0
	v_min_u32_e32 v0, v2, v0
	v_max_u32_e32 v2, v4, v3
	v_min_u32_e32 v3, v4, v3
	v_max_u32_e32 v4, v6, v1
	v_min_u32_e32 v1, v6, v1
	v_max_u32_e32 v6, v5, v16
	v_min_u32_e32 v5, v5, v16
	v_max_u32_e32 v16, v7, v8
	v_min_u32_e32 v7, v7, v8
	v_max_u32_e32 v8, v18, v14
	v_min_u32_e32 v14, v18, v14
	v_max_u32_e32 v18, v17, v9
	v_min_u32_e32 v9, v17, v9
	v_max_u32_e32 v17, v19, v22
	v_min_u32_e32 v19, v19, v22
	v_max_u32_e32 v22, v15, v20
	v_min_u32_e32 v15, v15, v20
	v_max_u32_e32 v20, v24, v23
	v_min_u32_e32 v23, v24, v23
	v_max_u32_e32 v24, v26, v21
	v_min_u32_e32 v21, v26, v21
	v_max_u32_e32 v26, v25, v30
	v_min_u32_e32 v25, v25, v30
	v_max_u32_e32 v30, v27, v28
	v_min_u32_e32 v27, v27, v28
	v_max_u32_e32 v28, v10, v12
	v_min_u32_e32 v10, v10, v12
	v_max_u32_e32 v12, v31, v29
	v_min_u32_e32 v29, v31, v29
	v_max_u32_e32 v31, v11, v3
	v_min_u32_e32 v3, v11, v3
	v_max_u32_e32 v11, v13, v2
	v_min_u32_e32 v2, v13, v2
	v_max_u32_e32 v13, v116, v1
	v_min_u32_e32 v1, v116, v1
	v_max_u32_e32 v116, v0, v4
	v_min_u32_e32 v0, v0, v4
	v_max_u32_e32 v4, v14, v6
	v_min_u32_e32 v6, v14, v6
	v_max_u32_e32 v14, v8, v5
	v_min_u32_e32 v5, v8, v5
	v_max_u32_e32 v8, v9, v16
	v_min_u32_e32 v9, v9, v16
	v_max_u32_e32 v16, v18, v7
	v_min_u32_e32 v7, v18, v7
	v_max_u32_e32 v18, v17, v23
	v_min_u32_e32 v17, v17, v23
	v_max_u32_e32 v23, v19, v20
	v_min_u32_e32 v19, v19, v20
	v_max_u32_e32 v20, v22, v21
	v_min_u32_e32 v21, v22, v21
	v_max_u32_e32 v22, v15, v24
	v_min_u32_e32 v15, v15, v24
	v_max_u32_e32 v24, v10, v26
	v_min_u32_e32 v10, v10, v26
	v_max_u32_e32 v26, v28, v25
	v_min_u32_e32 v25, v28, v25
	v_max_u32_e32 v28, v29, v30
	v_min_u32_e32 v29, v29, v30
	v_max_u32_e32 v30, v12, v27
	v_min_u32_e32 v12, v12, v27
	v_max_u32_e32 v27, v31, v13
	v_min_u32_e32 v13, v31, v13
	v_max_u32_e32 v31, v11, v116
	v_min_u32_e32 v11, v11, v116
	v_max_u32_e32 v116, v3, v1
	v_min_u32_e32 v1, v3, v1
	v_max_u32_e32 v3, v2, v0
	v_min_u32_e32 v0, v2, v0
	v_max_u32_e32 v2, v9, v6
	v_min_u32_e32 v6, v9, v6
	v_max_u32_e32 v9, v7, v5
	v_min_u32_e32 v5, v7, v5
	v_max_u32_e32 v7, v8, v4
	v_min_u32_e32 v4, v8, v4
	v_max_u32_e32 v8, v16, v14
	v_min_u32_e32 v14, v16, v14
	v_max_u32_e32 v16, v18, v20
	v_min_u32_e32 v18, v18, v20
	v_max_u32_e32 v20, v23, v22
	v_min_u32_e32 v22, v23, v22
	v_max_u32_e32 v23, v17, v21
	v_min_u32_e32 v17, v17, v21
	v_max_u32_e32 v21, v19, v15
	v_min_u32_e32 v15, v19, v15
	v_max_u32_e32 v19, v29, v10
	v_min_u32_e32 v10, v29, v10
	v_max_u32_e32 v29, v12, v25
	v_min_u32_e32 v12, v12, v25
	v_max_u32_e32 v25, v28, v24
	v_min_u32_e32 v24, v28, v24
	v_max_u32_e32 v28, v30, v26
	v_min_u32_e32 v26, v30, v26
	v_max_u32_e32 v30, v27, v31
	v_min_u32_e32 v27, v27, v31
	v_max_u32_e32 v31, v13, v11
; template <int N> DI void bitonic_sort_desc(unsigned (&v)[N]) {
; #pragma unroll
;     for (int k = 2; k <= N; k <<= 1)
; #pragma unroll
;         for (int j = k >> 1; j > 0; j >>= 1)
; #pragma unroll
;             for (int i = 0; i < N; ++i) { const int l = i ^ j; if (l > i) { if ((i & k) == 0) cswap(v[i], v[l]); else cswap(v[l], v[i]); } }
; }
; DI void topk_phase(unsigned char* smem_, const bf16_t* __restrict__ qp, const bf16_t* __restrict__ keys, int* __restrict__ eidx, float* __restrict__ gate) {
;     ...
;         for (int i = 0; i < 16; ++i) t16[i] = v[i];
;         merge_top16(t16, 1);
	v_min_u32_e32 v11, v13, v11
	v_max_u32_e32 v13, v116, v3
	v_min_u32_e32 v3, v116, v3
	v_max_u32_e32 v116, v1, v0
	v_min_u32_e32 v0, v1, v0
	v_max_u32_e32 v1, v5, v6
	v_min_u32_e32 v5, v5, v6
	v_max_u32_e32 v6, v9, v2
	v_min_u32_e32 v2, v9, v2
	v_max_u32_e32 v9, v14, v4
	v_min_u32_e32 v4, v14, v4
	v_max_u32_e32 v14, v8, v7
	v_min_u32_e32 v7, v8, v7
	v_max_u32_e32 v8, v16, v20
	v_min_u32_e32 v16, v16, v20
	v_max_u32_e32 v20, v18, v22
	v_min_u32_e32 v18, v18, v22
	v_max_u32_e32 v22, v23, v21
	v_min_u32_e32 v21, v23, v21
	v_max_u32_e32 v23, v17, v15
	v_min_u32_e32 v15, v17, v15
	v_max_u32_e32 v17, v12, v10
	v_min_u32_e32 v10, v12, v10
	v_max_u32_e32 v12, v29, v19
	v_min_u32_e32 v19, v29, v19
	v_max_u32_e32 v29, v26, v24
	v_min_u32_e32 v24, v26, v24
	v_max_u32_e32 v26, v28, v25
	v_min_u32_e32 v25, v28, v25
	v_max_u32_e32 v28, v30, v5
	v_min_u32_e32 v5, v30, v5
	v_max_u32_e32 v30, v27, v1
	v_min_u32_e32 v1, v27, v1
	v_max_u32_e32 v27, v31, v2
	v_min_u32_e32 v2, v31, v2
	v_max_u32_e32 v31, v11, v6
	v_min_u32_e32 v6, v11, v6
	v_max_u32_e32 v11, v13, v4
	v_min_u32_e32 v4, v13, v4
	v_max_u32_e32 v13, v3, v9
	v_min_u32_e32 v3, v3, v9
	v_max_u32_e32 v9, v116, v7
	v_min_u32_e32 v7, v116, v7
	v_max_u32_e32 v116, v0, v14
	v_min_u32_e32 v0, v0, v14
	v_max_u32_e32 v14, v10, v8
	v_min_u32_e32 v8, v10, v8
	v_max_u32_e32 v10, v17, v16
	v_min_u32_e32 v16, v17, v16
	v_max_u32_e32 v17, v19, v20
	v_min_u32_e32 v19, v19, v20
	v_max_u32_e32 v20, v12, v18
	v_min_u32_e32 v12, v12, v18
	v_max_u32_e32 v18, v24, v22
	v_min_u32_e32 v22, v24, v22
	v_max_u32_e32 v24, v29, v21
	v_min_u32_e32 v21, v29, v21
	v_max_u32_e32 v29, v25, v23
	v_min_u32_e32 v23, v25, v23
	v_max_u32_e32 v25, v26, v15
	v_min_u32_e32 v15, v26, v15
	v_max_u32_e32 v26, v28, v11
	v_min_u32_e32 v11, v28, v11
	v_max_u32_e32 v28, v30, v13
	v_min_u32_e32 v13, v30, v13
	v_max_u32_e32 v30, v27, v9
	v_min_u32_e32 v9, v27, v9
	v_max_u32_e32 v27, v31, v116
	v_min_u32_e32 v31, v31, v116
	v_max_u32_e32 v116, v5, v4
	v_min_u32_e32 v4, v5, v4
	v_max_u32_e32 v5, v1, v3
	v_min_u32_e32 v1, v1, v3
	v_max_u32_e32 v3, v2, v7
	v_min_u32_e32 v2, v2, v7
	v_max_u32_e32 v7, v6, v0
	v_min_u32_e32 v0, v6, v0
	v_max_u32_e32 v6, v22, v8
	v_min_u32_e32 v8, v22, v8
	v_max_u32_e32 v22, v21, v16
	v_min_u32_e32 v16, v21, v16
	v_max_u32_e32 v21, v23, v19
	v_min_u32_e32 v19, v23, v19
	v_max_u32_e32 v23, v15, v12
	v_min_u32_e32 v12, v15, v12
	v_max_u32_e32 v15, v18, v14
	v_min_u32_e32 v14, v18, v14
	v_max_u32_e32 v18, v24, v10
	v_min_u32_e32 v10, v24, v10
	v_max_u32_e32 v24, v29, v17
	v_min_u32_e32 v17, v29, v17
	v_max_u32_e32 v29, v25, v20
	v_min_u32_e32 v20, v25, v20
	v_max_u32_e32 v25, v26, v30
	v_min_u32_e32 v26, v26, v30
	v_max_u32_e32 v30, v28, v27
	v_min_u32_e32 v27, v28, v27
	v_max_u32_e32 v28, v11, v9
	v_min_u32_e32 v9, v11, v9
	v_max_u32_e32 v11, v13, v31
	v_min_u32_e32 v13, v13, v31
	v_max_u32_e32 v31, v116, v3
	v_min_u32_e32 v3, v116, v3
	v_max_u32_e32 v116, v5, v7
	v_min_u32_e32 v5, v5, v7
	v_max_u32_e32 v7, v4, v2
	v_min_u32_e32 v2, v4, v2
	v_max_u32_e32 v4, v1, v0
	v_min_u32_e32 v0, v1, v0
	v_max_u32_e32 v1, v19, v8
	v_min_u32_e32 v8, v19, v8
	v_max_u32_e32 v19, v12, v16
	v_min_u32_e32 v12, v12, v16
	v_max_u32_e32 v16, v21, v6
	v_min_u32_e32 v6, v21, v6
	v_max_u32_e32 v21, v23, v22
	v_min_u32_e32 v22, v23, v22
	v_max_u32_e32 v23, v17, v14
	v_min_u32_e32 v14, v17, v14
	v_max_u32_e32 v17, v20, v10
	v_min_u32_e32 v10, v20, v10
	v_max_u32_e32 v20, v24, v15
	v_min_u32_e32 v15, v24, v15
	v_max_u32_e32 v24, v29, v18
	v_min_u32_e32 v18, v29, v18
	v_min_u32_e32 v29, v25, v30
	v_min_u32_e32 v117, v26, v27
	v_min_u32_e32 v118, v28, v11
	v_min_u32_e32 v119, v9, v13
	v_min_u32_e32 v120, v31, v116
	v_min_u32_e32 v121, v3, v5
	v_min_u32_e32 v122, v7, v4
	v_min_u32_e32 v123, v2, v0
	v_min_u32_e32 v124, v12, v8
	v_min_u32_e32 v125, v19, v1
	v_min_u32_e32 v126, v22, v6
	v_min_u32_e32 v127, v21, v16
	v_min_u32_e32 v142, v10, v14
	v_min_u32_e32 v143, v17, v23
	v_min_u32_e32 v144, v18, v15
	v_min_u32_e32 v145, v24, v20
	v_max3_u32 v25, v25, v30, v124
	v_max3_u32 v8, v29, v12, v8
	v_max3_u32 v12, v26, v27, v125
	v_max3_u32 v1, v117, v19, v1
	v_max3_u32 v11, v28, v11, v126
	v_max3_u32 v6, v118, v22, v6
	v_max3_u32 v9, v9, v13, v127
	v_max3_u32 v13, v119, v21, v16
	v_max3_u32 v16, v31, v116, v142
	v_max3_u32 v10, v120, v10, v14
	v_max3_u32 v3, v3, v5, v143
	v_max3_u32 v5, v121, v17, v23
	v_max3_u32 v4, v7, v4, v144
	v_max3_u32 v7, v122, v18, v15
	v_max3_u32 v0, v2, v0, v145
	v_max3_u32 v2, v123, v24, v20
	v_max_u32_e32 v14, v25, v16
	v_min_u32_e32 v15, v25, v16
	v_max_u32_e32 v16, v8, v10
	v_min_u32_e32 v8, v8, v10
	v_max_u32_e32 v10, v12, v3
	v_min_u32_e32 v3, v12, v3
	v_max_u32_e32 v12, v1, v5
	v_min_u32_e32 v1, v1, v5
	v_max_u32_e32 v5, v11, v4
	v_min_u32_e32 v4, v11, v4
	v_max_u32_e32 v11, v6, v7
	v_min_u32_e32 v6, v6, v7
	v_max_u32_e32 v7, v9, v0
	v_min_u32_e32 v0, v9, v0
	v_max_u32_e32 v9, v13, v2
	v_min_u32_e32 v2, v13, v2
	v_max_u32_e32 v13, v14, v5
	v_min_u32_e32 v5, v14, v5
	v_max_u32_e32 v14, v16, v11
	v_min_u32_e32 v11, v16, v11
	v_max_u32_e32 v16, v10, v7
	v_min_u32_e32 v7, v10, v7
	v_max_u32_e32 v10, v12, v9
	v_min_u32_e32 v9, v12, v9
	v_max_u32_e32 v12, v15, v4
	v_min_u32_e32 v4, v15, v4
	v_max_u32_e32 v15, v8, v6
	v_min_u32_e32 v6, v8, v6
	v_max_u32_e32 v8, v3, v0
	v_min_u32_e32 v0, v3, v0
	v_max_u32_e32 v3, v1, v2
	v_min_u32_e32 v1, v1, v2
	v_max_u32_e32 v2, v13, v16
	v_min_u32_e32 v13, v13, v16
	v_max_u32_e32 v16, v14, v10
	v_min_u32_e32 v10, v14, v10
	v_max_u32_e32 v14, v5, v7
	v_min_u32_e32 v5, v5, v7
	v_max_u32_e32 v7, v11, v9
	v_min_u32_e32 v9, v11, v9
	v_max_u32_e32 v11, v12, v8
	v_min_u32_e32 v8, v12, v8
	v_max_u32_e32 v12, v15, v3
; DI void merge_top16(unsigned (&v)[16], int st) {
;     unsigned x[16];
; #pragma unroll
;     for (int i = 0; i < 16; ++i) x[i] = (unsigned)__shfl_xor((int)v[15 - i], st);
; #pragma unroll
;     for (int i = 0; i < 16; ++i) v[i] = max(v[i], x[i]);
; #pragma unroll
;     for (int j = 8; j > 0; j >>= 1)
; #pragma unroll
;         for (int i = 0; i < 16; ++i) { const int l = i ^ j; if (l > i) cswap(v[i], v[l]); }
; }
; DI void topk_phase(unsigned char* smem_, const bf16_t* __restrict__ qp, const bf16_t* __restrict__ keys, int* __restrict__ eidx, float* __restrict__ gate) {
;     ...
;         merge_top16(t16, 1);
;         merge_top16(t16, 2);
; #pragma unroll
;         for (int i = 0; i < 16; ++i) if ((i >> 2) == q) { const int idx = 127 - (int)(t16[i] & 127u); SI[row * 32 + 16 * p + i] = idx; SV[row * 32 + 16 * p + i] = S[row * LDS_ + idx]; }
	v_min_u32_e32 v3, v15, v3
	v_max_u32_e32 v15, v4, v0
	v_min_u32_e32 v0, v4, v0
	v_max_u32_e32 v4, v6, v1
	v_min_u32_e32 v1, v6, v1
	v_max_u32_e32 v6, v2, v16
	v_min_u32_e32 v2, v2, v16
	v_max_u32_e32 v16, v13, v10
	v_min_u32_e32 v10, v13, v10
	v_max_u32_e32 v13, v14, v7
	v_min_u32_e32 v7, v14, v7
	v_max_u32_e32 v14, v5, v9
	v_min_u32_e32 v5, v5, v9
	v_max_u32_e32 v9, v11, v12
	v_min_u32_e32 v11, v11, v12
	v_max_u32_e32 v12, v8, v3
	v_min_u32_e32 v3, v8, v3
	v_max_u32_e32 v8, v15, v4
	v_min_u32_e32 v4, v15, v4
	v_max_u32_e32 v15, v0, v1
	v_min_u32_e32 v0, v0, v1
	s_nop 1
	v_mov_b32_dpp v1, v0 quad_perm:[1,0,3,2] row_mask:0xf bank_mask:0xf
	v_mov_b32_dpp v17, v15 quad_perm:[1,0,3,2] row_mask:0xf bank_mask:0xf
	v_mov_b32_dpp v18, v4 quad_perm:[1,0,3,2] row_mask:0xf bank_mask:0xf
	v_mov_b32_dpp v19, v8 quad_perm:[1,0,3,2] row_mask:0xf bank_mask:0xf
	v_mov_b32_dpp v20, v3 quad_perm:[1,0,3,2] row_mask:0xf bank_mask:0xf
	v_mov_b32_dpp v21, v12 quad_perm:[1,0,3,2] row_mask:0xf bank_mask:0xf
	v_mov_b32_dpp v22, v11 quad_perm:[1,0,3,2] row_mask:0xf bank_mask:0xf
	v_mov_b32_dpp v23, v9 quad_perm:[1,0,3,2] row_mask:0xf bank_mask:0xf
	v_mov_b32_dpp v24, v5 quad_perm:[1,0,3,2] row_mask:0xf bank_mask:0xf
	v_mov_b32_dpp v25, v14 quad_perm:[1,0,3,2] row_mask:0xf bank_mask:0xf
	v_mov_b32_dpp v26, v7 quad_perm:[1,0,3,2] row_mask:0xf bank_mask:0xf
	v_mov_b32_dpp v27, v13 quad_perm:[1,0,3,2] row_mask:0xf bank_mask:0xf
	v_mov_b32_dpp v28, v10 quad_perm:[1,0,3,2] row_mask:0xf bank_mask:0xf
	v_mov_b32_dpp v29, v16 quad_perm:[1,0,3,2] row_mask:0xf bank_mask:0xf
	v_mov_b32_dpp v30, v2 quad_perm:[1,0,3,2] row_mask:0xf bank_mask:0xf
	v_mov_b32_dpp v31, v6 quad_perm:[1,0,3,2] row_mask:0xf bank_mask:0xf
	s_waitcnt lgkmcnt(0)
	v_max_u32_e32 v1, v6, v1
	v_max_u32_e32 v2, v2, v17
	v_max_u32_e32 v6, v16, v18
	v_max_u32_e32 v10, v10, v19
	v_max_u32_e32 v13, v13, v20
	v_max_u32_e32 v7, v7, v21
	v_max_u32_e32 v14, v14, v22
	v_max_u32_e32 v5, v5, v23
	v_max_u32_e32 v9, v9, v24
	v_max_u32_e32 v11, v11, v25
	v_max_u32_e32 v12, v12, v26
	v_max_u32_e32 v3, v3, v27
	v_max_u32_e32 v8, v8, v28
	v_max_u32_e32 v4, v4, v29
	v_max_u32_e32 v15, v15, v30
	v_max_u32_e32 v0, v0, v31
	v_max_u32_e32 v16, v1, v9
	v_min_u32_e32 v1, v1, v9
	v_max_u32_e32 v9, v2, v11
	v_min_u32_e32 v2, v2, v11
	v_max_u32_e32 v11, v6, v12
	v_min_u32_e32 v6, v6, v12
	v_max_u32_e32 v12, v10, v3
	v_min_u32_e32 v3, v10, v3
	v_max_u32_e32 v10, v13, v8
	v_min_u32_e32 v8, v13, v8
	v_max_u32_e32 v13, v7, v4
	v_min_u32_e32 v4, v7, v4
	v_max_u32_e32 v7, v14, v15
	v_min_u32_e32 v14, v14, v15
	v_max_u32_e32 v15, v5, v0
	v_min_u32_e32 v0, v5, v0
	v_max_u32_e32 v5, v16, v10
	v_min_u32_e32 v10, v16, v10
	v_max_u32_e32 v16, v9, v13
	v_min_u32_e32 v9, v9, v13
	v_max_u32_e32 v13, v11, v7
	v_min_u32_e32 v7, v11, v7
	v_max_u32_e32 v11, v12, v15
	v_min_u32_e32 v12, v12, v15
	v_max_u32_e32 v15, v1, v8
	v_min_u32_e32 v1, v1, v8
	v_max_u32_e32 v8, v2, v4
	v_min_u32_e32 v2, v2, v4
	v_max_u32_e32 v4, v6, v14
	v_min_u32_e32 v6, v6, v14
	v_max_u32_e32 v14, v3, v0
	v_min_u32_e32 v0, v3, v0
	v_max_u32_e32 v3, v5, v13
	v_min_u32_e32 v5, v5, v13
	v_max_u32_e32 v13, v16, v11
	v_min_u32_e32 v11, v16, v11
	v_max_u32_e32 v16, v10, v7
	v_min_u32_e32 v7, v10, v7
	v_max_u32_e32 v10, v9, v12
	v_min_u32_e32 v9, v9, v12
	v_max_u32_e32 v12, v15, v4
	v_min_u32_e32 v4, v15, v4
	v_max_u32_e32 v15, v8, v14
	v_min_u32_e32 v8, v8, v14
	v_max_u32_e32 v14, v1, v6
	v_min_u32_e32 v1, v1, v6
	v_max_u32_e32 v6, v2, v0
	v_min_u32_e32 v0, v2, v0
	v_max_u32_e32 v2, v3, v13
	v_min_u32_e32 v3, v3, v13
	v_max_u32_e32 v13, v5, v11
	v_min_u32_e32 v5, v5, v11
	v_max_u32_e32 v11, v16, v10
	v_min_u32_e32 v10, v16, v10
	v_max_u32_e32 v16, v7, v9
	v_min_u32_e32 v7, v7, v9
	v_max_u32_e32 v9, v12, v15
	v_min_u32_e32 v12, v12, v15
	v_max_u32_e32 v15, v4, v8
	v_min_u32_e32 v17, v4, v8
	v_max_u32_e32 v18, v14, v6
	v_min_u32_e32 v14, v14, v6
	v_max_u32_e32 v19, v1, v0
	v_min_u32_e32 v20, v1, v0
	s_nop 1
	v_mov_b32_dpp v0, v20 quad_perm:[2,3,0,1] row_mask:0xf bank_mask:0xf
	v_mov_b32_dpp v1, v19 quad_perm:[2,3,0,1] row_mask:0xf bank_mask:0xf
	v_mov_b32_dpp v4, v14 quad_perm:[2,3,0,1] row_mask:0xf bank_mask:0xf
	v_mov_b32_dpp v6, v18 quad_perm:[2,3,0,1] row_mask:0xf bank_mask:0xf
	v_mov_b32_dpp v8, v17 quad_perm:[2,3,0,1] row_mask:0xf bank_mask:0xf
	v_mov_b32_dpp v21, v15 quad_perm:[2,3,0,1] row_mask:0xf bank_mask:0xf
	v_mov_b32_dpp v22, v12 quad_perm:[2,3,0,1] row_mask:0xf bank_mask:0xf
	v_mov_b32_dpp v23, v9 quad_perm:[2,3,0,1] row_mask:0xf bank_mask:0xf
	v_mov_b32_dpp v24, v7 quad_perm:[2,3,0,1] row_mask:0xf bank_mask:0xf
	v_mov_b32_dpp v25, v16 quad_perm:[2,3,0,1] row_mask:0xf bank_mask:0xf
	v_mov_b32_dpp v26, v10 quad_perm:[2,3,0,1] row_mask:0xf bank_mask:0xf
	v_mov_b32_dpp v27, v11 quad_perm:[2,3,0,1] row_mask:0xf bank_mask:0xf
	v_mov_b32_dpp v28, v5 quad_perm:[2,3,0,1] row_mask:0xf bank_mask:0xf
	v_mov_b32_dpp v29, v13 quad_perm:[2,3,0,1] row_mask:0xf bank_mask:0xf
	v_mov_b32_dpp v30, v3 quad_perm:[2,3,0,1] row_mask:0xf bank_mask:0xf
	v_mov_b32_dpp v31, v2 quad_perm:[2,3,0,1] row_mask:0xf bank_mask:0xf
	s_waitcnt lgkmcnt(0)
	v_max_u32_e32 v0, v2, v0
	v_max_u32_e32 v1, v3, v1
	v_max_u32_e32 v2, v13, v4
	v_max_u32_e32 v3, v5, v6
	v_max_u32_e32 v4, v11, v8
	v_max_u32_e32 v5, v10, v21
	v_max_u32_e32 v6, v16, v22
	v_max_u32_e32 v7, v7, v23
	v_max_u32_e32 v8, v9, v24
	v_max_u32_e32 v9, v12, v25
	v_max_u32_e32 v10, v15, v26
	v_max_u32_e32 v11, v17, v27
	v_max_u32_e32 v12, v18, v28
	v_max_u32_e32 v13, v14, v29
	v_max_u32_e32 v14, v19, v30
	v_max_u32_e32 v15, v20, v31
	v_max_u32_e32 v16, v0, v8
	v_max_u32_e32 v17, v1, v9
	v_max_u32_e32 v18, v2, v10
	v_max_u32_e32 v19, v3, v11
	v_max_u32_e32 v20, v4, v12
	v_max_u32_e32 v21, v5, v13
	v_max_u32_e32 v22, v6, v14
	v_max_u32_e32 v23, v7, v15
	s_and_saveexec_b64 s[0:1], s[4:5]
	s_cbranch_execz .LBB0_59
	v_max_u32_e32 v24, v16, v20
	v_max_u32_e32 v25, v18, v22
	v_max_u32_e32 v27, v17, v21
	v_max_u32_e32 v28, v19, v23
	v_min_u32_e32 v26, v24, v25
	v_min_u32_e32 v29, v27, v28
	v_max_u32_e32 v24, v24, v25
	v_max_u32_e32 v25, v27, v28
	v_min_u32_e32 v30, v26, v29
	v_max_u32_e32 v29, v26, v29
	v_min_u32_e32 v26, v24, v25
	v_max_u32_e32 v24, v24, v25
	v_xor_b32_e32 v25, -1, v26
	v_xor_b32_e32 v24, -1, v24
	v_and_b32_e32 v25, 0x7f, v25
	v_and_b32_e32 v24, 0x7f, v24
	v_lshl_add_u32 v26, v24, 2, v169
	v_lshl_add_u32 v27, v25, 2, v169
	ds_read_b32 v26, v26 offset:17408
	ds_read_b32 v27, v27 offset:17408
	v_xor_b32_e32 v28, -1, v29
	s_waitcnt lgkmcnt(0)
	ds_write_b64 v175, v[26:27] offset:53248
	v_xor_b32_e32 v26, -1, v30
	v_and_b32_e32 v27, 0x7f, v26
	v_and_b32_e32 v26, 0x7f, v28
	v_lshl_add_u32 v28, v26, 2, v169
	ds_write_b128 v184, v[24:27] offset:61440
	v_lshl_add_u32 v24, v27, 2, v169
	ds_read_b32 v28, v28 offset:17408
	ds_read_b32 v29, v24 offset:17408
	s_waitcnt lgkmcnt(0)
	ds_write_b64 v184, v[28:29] offset:53256

; DI unsigned fkey(float f) { const unsigned u = __float_as_uint(f); return (u & 0x80000000u) ? ~u : (u | 0x80000000u); }
; DI void topk_phase(unsigned char* smem_, const bf16_t* __restrict__ qp, const bf16_t* __restrict__ keys, int* __restrict__ eidx, float* __restrict__ gate) {
;     ...
;     for (int p = 0; p < 2; ++p) {
;     ...
;             const f32x4 sv4 = *(const f32x4*)(S + row * LDS_ + 32 * q + 4 * i);
;             const int ib = 127 - (32 * q + 4 * i);
;             v[4 * i] = (fkey(sv4.x) & ~127u) | (unsigned)ib; v[4 * i + 1] = (fkey(sv4.y) & ~127u) | (unsigned)(ib - 1);
;             v[4 * i + 2] = (fkey(sv4.z) & ~127u) | (unsigned)(ib - 2); v[4 * i + 3] = (fkey(sv4.w) & ~127u) | (unsigned)(ib - 3);
.LBB0_67:
	ds_read_b128 v[0:3], v171 offset:17408
	ds_read_b128 v[4:7], v171 offset:17424
	ds_read_b128 v[8:11], v171 offset:17440
	ds_read_b128 v[12:15], v171 offset:17456
	s_waitcnt lgkmcnt(3)
	v_not_b32_e32 v16, v0
	v_or_b32_e32 v17, 0x80000000, v0
	v_cmp_gt_i32_e32 vcc, 0, v0
	s_nop 1
	v_cndmask_b32_e32 v0, v17, v16, vcc
	v_and_b32_e32 v0, 0xffffff80, v0
	v_sub_u32_e32 v0, v0, v170
	v_add_u32_e32 v16, 0x7f, v0
	v_not_b32_e32 v0, v1
	v_or_b32_e32 v17, 0x80000000, v1
	v_cmp_gt_i32_e32 vcc, 0, v1
	v_or_b32_e32 v1, 0x80000000, v2
	s_nop 0
	v_cndmask_b32_e32 v0, v17, v0, vcc
	v_and_b32_e32 v0, 0xffffff80, v0
	v_sub_u32_e32 v0, v0, v170
	v_add_u32_e32 v17, 0x7e, v0
	v_not_b32_e32 v0, v2
	v_cmp_gt_i32_e32 vcc, 0, v2
	s_nop 1
	v_cndmask_b32_e32 v0, v1, v0, vcc
	v_and_b32_e32 v0, 0xffffff80, v0
	v_sub_u32_e32 v0, v0, v170
	v_add_u32_e32 v18, 0x7d, v0
	v_not_b32_e32 v0, v3
	v_or_b32_e32 v1, 0x80000000, v3
	v_cmp_gt_i32_e32 vcc, 0, v3
	s_nop 1
	v_cndmask_b32_e32 v0, v1, v0, vcc
	v_and_b32_e32 v0, 0xffffff80, v0
	v_sub_u32_e32 v0, v0, v170
	v_add_u32_e32 v19, 0x7c, v0
	s_waitcnt lgkmcnt(2)
	v_not_b32_e32 v0, v4
	v_or_b32_e32 v1, 0x80000000, v4
	v_cmp_gt_i32_e32 vcc, 0, v4
	s_nop 1
	v_cndmask_b32_e32 v0, v1, v0, vcc
	v_and_b32_e32 v0, 0xffffff80, v0
	v_sub_u32_e32 v0, v0, v177
	v_add_u32_e32 v20, 0x7f, v0
	v_not_b32_e32 v0, v5
	v_or_b32_e32 v1, 0x80000000, v5
	v_cmp_gt_i32_e32 vcc, 0, v5
	s_nop 1
	v_cndmask_b32_e32 v0, v1, v0, vcc
	v_and_b32_e32 v0, 0xffffff80, v0
	v_sub_u32_e32 v0, v0, v177
	v_add_u32_e32 v21, 0x7e, v0
	v_not_b32_e32 v0, v6
	v_or_b32_e32 v1, 0x80000000, v6
	v_cmp_gt_i32_e32 vcc, 0, v6
	s_nop 1
	v_cndmask_b32_e32 v0, v1, v0, vcc
	v_and_b32_e32 v0, 0xffffff80, v0
	v_sub_u32_e32 v0, v0, v177
	v_add_u32_e32 v22, 0x7d, v0
	v_not_b32_e32 v0, v7
	v_or_b32_e32 v1, 0x80000000, v7
	v_cmp_gt_i32_e32 vcc, 0, v7
	s_nop 1
	v_cndmask_b32_e32 v0, v1, v0, vcc
	v_and_b32_e32 v0, 0xffffff80, v0
	v_sub_u32_e32 v0, v0, v177
	v_add_u32_e32 v23, 0x7c, v0
	s_waitcnt lgkmcnt(1)
	v_not_b32_e32 v0, v8
	v_or_b32_e32 v1, 0x80000000, v8
	v_cmp_gt_i32_e32 vcc, 0, v8
	s_nop 1
	v_cndmask_b32_e32 v0, v1, v0, vcc
	v_and_b32_e32 v0, 0xffffff80, v0
	v_sub_u32_e32 v0, v0, v178
	v_add_u32_e32 v8, 0x7f, v0
	v_not_b32_e32 v0, v9
	v_or_b32_e32 v1, 0x80000000, v9
	v_cmp_gt_i32_e32 vcc, 0, v9
	s_nop 1
	v_cndmask_b32_e32 v0, v1, v0, vcc
	v_and_b32_e32 v0, 0xffffff80, v0
	v_sub_u32_e32 v0, v0, v178
	v_add_u32_e32 v9, 0x7e, v0
	v_not_b32_e32 v0, v10
	v_or_b32_e32 v1, 0x80000000, v10
	v_cmp_gt_i32_e32 vcc, 0, v10
	s_nop 1
	v_cndmask_b32_e32 v0, v1, v0, vcc
	v_and_b32_e32 v0, 0xffffff80, v0
	v_sub_u32_e32 v0, v0, v178
	v_add_u32_e32 v10, 0x7d, v0
	v_not_b32_e32 v0, v11
	v_or_b32_e32 v1, 0x80000000, v11
	v_cmp_gt_i32_e32 vcc, 0, v11
	s_nop 1
	v_cndmask_b32_e32 v0, v1, v0, vcc
	v_and_b32_e32 v0, 0xffffff80, v0
	v_sub_u32_e32 v0, v0, v178
	v_add_u32_e32 v11, 0x7c, v0
	s_waitcnt lgkmcnt(0)
	v_not_b32_e32 v0, v12
	v_or_b32_e32 v1, 0x80000000, v12
	v_cmp_gt_i32_e32 vcc, 0, v12
	s_nop 1
	v_cndmask_b32_e32 v0, v1, v0, vcc
	v_and_b32_e32 v0, 0xffffff80, v0
	v_sub_u32_e32 v0, v0, v179
	v_add_u32_e32 v12, 0x7f, v0
	v_not_b32_e32 v0, v13
	v_or_b32_e32 v1, 0x80000000, v13
	v_cmp_gt_i32_e32 vcc, 0, v13
	s_nop 1
	v_cndmask_b32_e32 v0, v1, v0, vcc
	v_and_b32_e32 v0, 0xffffff80, v0
	v_sub_u32_e32 v0, v0, v179
	v_add_u32_e32 v13, 0x7e, v0
	v_not_b32_e32 v0, v14
	v_or_b32_e32 v1, 0x80000000, v14
	v_cmp_gt_i32_e32 vcc, 0, v14
	s_nop 1
	v_cndmask_b32_e32 v0, v1, v0, vcc
	v_and_b32_e32 v0, 0xffffff80, v0
	v_sub_u32_e32 v0, v0, v179
	v_add_u32_e32 v14, 0x7d, v0
	v_not_b32_e32 v0, v15
	v_or_b32_e32 v1, 0x80000000, v15
	v_cmp_gt_i32_e32 vcc, 0, v15
	s_nop 1
	v_cndmask_b32_e32 v4, v1, v0, vcc
	ds_read_b128 v[0:3], v171 offset:17472
	v_and_b32_e32 v4, 0xffffff80, v4
	v_sub_u32_e32 v4, v4, v179
	v_add_u32_e32 v15, 0x7c, v4
	ds_read_b128 v[4:7], v171 offset:17488
	s_waitcnt lgkmcnt(1)
	v_not_b32_e32 v24, v0
	v_or_b32_e32 v25, 0x80000000, v0
	v_cmp_gt_i32_e32 vcc, 0, v0
	s_nop 1
	v_cndmask_b32_e32 v0, v25, v24, vcc
	v_and_b32_e32 v0, 0xffffff80, v0
	v_sub_u32_e32 v0, v0, v180
	v_add_u32_e32 v24, 0x7f, v0
	v_not_b32_e32 v0, v1
	v_or_b32_e32 v25, 0x80000000, v1
	v_cmp_gt_i32_e32 vcc, 0, v1
	v_or_b32_e32 v1, 0x80000000, v2
	s_nop 0
	v_cndmask_b32_e32 v0, v25, v0, vcc
	v_and_b32_e32 v0, 0xffffff80, v0
	v_sub_u32_e32 v0, v0, v180
	v_add_u32_e32 v25, 0x7e, v0
	v_not_b32_e32 v0, v2
	v_cmp_gt_i32_e32 vcc, 0, v2
	s_nop 1
	v_cndmask_b32_e32 v0, v1, v0, vcc
	v_and_b32_e32 v0, 0xffffff80, v0
	v_sub_u32_e32 v0, v0, v180
	v_add_u32_e32 v26, 0x7d, v0
	v_not_b32_e32 v0, v3
	v_or_b32_e32 v1, 0x80000000, v3
	v_cmp_gt_i32_e32 vcc, 0, v3
	s_nop 1
	v_cndmask_b32_e32 v0, v1, v0, vcc
	v_and_b32_e32 v0, 0xffffff80, v0
	v_sub_u32_e32 v0, v0, v180
	v_add_u32_e32 v27, 0x7c, v0
	s_waitcnt lgkmcnt(0)
	v_not_b32_e32 v0, v4
	v_or_b32_e32 v1, 0x80000000, v4
	v_cmp_gt_i32_e32 vcc, 0, v4
	s_nop 1
	v_cndmask_b32_e32 v0, v1, v0, vcc
	v_and_b32_e32 v0, 0xffffff80, v0
	v_sub_u32_e32 v0, v0, v181
	v_add_u32_e32 v28, 0x7f, v0
	v_not_b32_e32 v0, v5
	v_or_b32_e32 v1, 0x80000000, v5
	v_cmp_gt_i32_e32 vcc, 0, v5
	s_nop 1
	v_cndmask_b32_e32 v0, v1, v0, vcc
	v_and_b32_e32 v0, 0xffffff80, v0
	v_sub_u32_e32 v0, v0, v181
	v_add_u32_e32 v29, 0x7e, v0
	v_not_b32_e32 v0, v6
	v_or_b32_e32 v1, 0x80000000, v6
	v_cmp_gt_i32_e32 vcc, 0, v6
	s_nop 1
	v_cndmask_b32_e32 v0, v1, v0, vcc
	v_and_b32_e32 v0, 0xffffff80, v0
	v_sub_u32_e32 v0, v0, v181
	v_add_u32_e32 v30, 0x7d, v0
	v_not_b32_e32 v0, v7
	v_or_b32_e32 v1, 0x80000000, v7
	v_cmp_gt_i32_e32 vcc, 0, v7
	s_nop 1
	v_cndmask_b32_e32 v4, v1, v0, vcc
	ds_read_b128 v[0:3], v171 offset:17504
	v_and_b32_e32 v4, 0xffffff80, v4
	v_sub_u32_e32 v4, v4, v181
	v_add_u32_e32 v31, 0x7c, v4
	ds_read_b128 v[4:7], v171 offset:17520
	s_waitcnt lgkmcnt(1)
; DI unsigned fkey(float f) { const unsigned u = __float_as_uint(f); return (u & 0x80000000u) ? ~u : (u | 0x80000000u); }
; template <int N> DI void bitonic_sort_desc(unsigned (&v)[N]) {
; #pragma unroll
;     for (int k = 2; k <= N; k <<= 1)
; #pragma unroll
;         for (int j = k >> 1; j > 0; j >>= 1)
; #pragma unroll
;             for (int i = 0; i < N; ++i) { const int l = i ^ j; if (l > i) { if ((i & k) == 0) cswap(v[i], v[l]); else cswap(v[l], v[i]); } }
; }
; DI void topk_phase(unsigned char* smem_, const bf16_t* __restrict__ qp, const bf16_t* __restrict__ keys, int* __restrict__ eidx, float* __restrict__ gate) {
;     ...
;             const f32x4 sv4 = *(const f32x4*)(S + row * LDS_ + 32 * q + 4 * i);
;             const int ib = 127 - (32 * q + 4 * i);
;             v[4 * i] = (fkey(sv4.x) & ~127u) | (unsigned)ib; v[4 * i + 1] = (fkey(sv4.y) & ~127u) | (unsigned)(ib - 1);
;             v[4 * i + 2] = (fkey(sv4.z) & ~127u) | (unsigned)(ib - 2); v[4 * i + 3] = (fkey(sv4.w) & ~127u) | (unsigned)(ib - 3);
;         }
;         bitonic_sort_desc<32>(v);
	v_not_b32_e32 v117, v0
	v_or_b32_e32 v118, 0x80000000, v0
	v_cmp_gt_i32_e32 vcc, 0, v0
	s_nop 1
	v_cndmask_b32_e32 v0, v118, v117, vcc
	v_not_b32_e32 v117, v1
	v_or_b32_e32 v118, 0x80000000, v1
	v_cmp_gt_i32_e32 vcc, 0, v1
	v_and_b32_e32 v0, 0xffffff80, v0
	v_sub_u32_e32 v0, v0, v182
	v_cndmask_b32_e32 v1, v118, v117, vcc
	v_not_b32_e32 v117, v2
	v_or_b32_e32 v118, 0x80000000, v2
	v_cmp_gt_i32_e32 vcc, 0, v2
	v_and_b32_e32 v1, 0xffffff80, v1
	v_sub_u32_e32 v1, v1, v182
	v_cndmask_b32_e32 v2, v118, v117, vcc
	v_not_b32_e32 v117, v3
	v_or_b32_e32 v118, 0x80000000, v3
	v_cmp_gt_i32_e32 vcc, 0, v3
	v_and_b32_e32 v2, 0xffffff80, v2
	v_sub_u32_e32 v2, v2, v182
	v_cndmask_b32_e32 v3, v118, v117, vcc
	s_waitcnt lgkmcnt(0)
	v_not_b32_e32 v117, v4
	v_or_b32_e32 v118, 0x80000000, v4
	v_cmp_gt_i32_e32 vcc, 0, v4
	v_and_b32_e32 v3, 0xffffff80, v3
	v_sub_u32_e32 v3, v3, v182
	v_cndmask_b32_e32 v4, v118, v117, vcc
	v_not_b32_e32 v117, v5
	v_or_b32_e32 v118, 0x80000000, v5
	v_cmp_gt_i32_e32 vcc, 0, v5
	v_and_b32_e32 v4, 0xffffff80, v4
	v_sub_u32_e32 v4, v4, v183
	v_cndmask_b32_e32 v5, v118, v117, vcc
	v_not_b32_e32 v117, v6
	v_or_b32_e32 v118, 0x80000000, v6
	v_cmp_gt_i32_e32 vcc, 0, v6
	v_and_b32_e32 v5, 0xffffff80, v5
	v_sub_u32_e32 v5, v5, v183
	v_cndmask_b32_e32 v6, v118, v117, vcc
	v_not_b32_e32 v117, v7
	v_or_b32_e32 v118, 0x80000000, v7
	v_cmp_gt_i32_e32 vcc, 0, v7
	v_and_b32_e32 v6, 0xffffff80, v6
	v_sub_u32_e32 v6, v6, v183
	v_cndmask_b32_e32 v7, v118, v117, vcc
	v_and_b32_e32 v7, 0xffffff80, v7
	v_sub_u32_e32 v7, v7, v183
	v_add_u32_e32 v0, 0x7f, v0
	v_add_u32_e32 v1, 0x7e, v1
	v_add_u32_e32 v2, 0x7d, v2
	v_add_u32_e32 v3, 0x7c, v3
	v_add_u32_e32 v4, 0x7f, v4
	v_add_u32_e32 v5, 0x7e, v5
	v_add_u32_e32 v6, 0x7d, v6
	v_add_u32_e32 v7, 0x7c, v7
	v_max_u32_e32 v117, v16, v17
	v_min_u32_e32 v16, v16, v17
	v_max_u32_e32 v17, v19, v18
	v_min_u32_e32 v18, v19, v18
	v_max_u32_e32 v19, v20, v21
	v_min_u32_e32 v20, v20, v21
	v_max_u32_e32 v21, v23, v22
	v_min_u32_e32 v22, v23, v22
	v_max_u32_e32 v23, v8, v9
	v_min_u32_e32 v8, v8, v9
	v_max_u32_e32 v9, v11, v10
	v_min_u32_e32 v10, v11, v10
	v_max_u32_e32 v11, v12, v13
	v_min_u32_e32 v12, v12, v13
	v_max_u32_e32 v13, v15, v14
	v_min_u32_e32 v14, v15, v14
	v_max_u32_e32 v15, v24, v25
	v_min_u32_e32 v24, v24, v25
	v_max_u32_e32 v25, v27, v26
	v_min_u32_e32 v26, v27, v26
	v_max_u32_e32 v27, v28, v29
	v_min_u32_e32 v28, v28, v29
	v_max_u32_e32 v29, v31, v30
	v_min_u32_e32 v30, v31, v30
	v_max_u32_e32 v31, v0, v1
	v_min_u32_e32 v0, v0, v1
	v_max_u32_e32 v1, v3, v2
	v_min_u32_e32 v2, v3, v2
	v_max_u32_e32 v3, v4, v5
	v_min_u32_e32 v4, v4, v5
	v_max_u32_e32 v5, v7, v6
	v_min_u32_e32 v6, v7, v6
	v_max_u32_e32 v7, v117, v18
	v_min_u32_e32 v18, v117, v18
	v_max_u32_e32 v117, v16, v17
	v_min_u32_e32 v16, v16, v17
	v_max_u32_e32 v17, v22, v19
	v_min_u32_e32 v19, v22, v19
	v_max_u32_e32 v22, v21, v20
	v_min_u32_e32 v20, v21, v20
	v_max_u32_e32 v21, v23, v10
	v_min_u32_e32 v10, v23, v10
	v_max_u32_e32 v23, v8, v9
	v_min_u32_e32 v8, v8, v9
	v_max_u32_e32 v9, v14, v11
	v_min_u32_e32 v11, v14, v11
	v_max_u32_e32 v14, v13, v12
	v_min_u32_e32 v12, v13, v12
	v_max_u32_e32 v13, v15, v26
	v_min_u32_e32 v15, v15, v26
	v_max_u32_e32 v26, v24, v25
	v_min_u32_e32 v24, v24, v25
	v_max_u32_e32 v25, v30, v27
	v_min_u32_e32 v27, v30, v27
	v_max_u32_e32 v30, v29, v28
	v_min_u32_e32 v28, v29, v28
	v_max_u32_e32 v29, v31, v2
	v_min_u32_e32 v2, v31, v2
	v_max_u32_e32 v31, v0, v1
	v_min_u32_e32 v0, v0, v1
	v_max_u32_e32 v1, v6, v3
	v_min_u32_e32 v3, v6, v3
	v_max_u32_e32 v6, v5, v4
	v_min_u32_e32 v4, v5, v4
	v_max_u32_e32 v5, v7, v117
	v_min_u32_e32 v7, v7, v117
	v_max_u32_e32 v117, v18, v16
	v_min_u32_e32 v16, v18, v16
	v_max_u32_e32 v18, v20, v19
	v_min_u32_e32 v19, v20, v19
	v_max_u32_e32 v20, v22, v17
	v_min_u32_e32 v17, v22, v17
	v_max_u32_e32 v22, v21, v23
	v_min_u32_e32 v21, v21, v23
	v_max_u32_e32 v23, v10, v8
	v_min_u32_e32 v8, v10, v8
	v_max_u32_e32 v10, v12, v11
	v_min_u32_e32 v11, v12, v11
	v_max_u32_e32 v12, v14, v9
	v_min_u32_e32 v9, v14, v9
	v_max_u32_e32 v14, v13, v26
	v_min_u32_e32 v13, v13, v26
	v_max_u32_e32 v26, v15, v24
	v_min_u32_e32 v15, v15, v24
	v_max_u32_e32 v24, v28, v27
	v_min_u32_e32 v27, v28, v27
	v_max_u32_e32 v28, v30, v25
	v_min_u32_e32 v25, v30, v25
	v_max_u32_e32 v30, v29, v31
	v_min_u32_e32 v29, v29, v31
	v_max_u32_e32 v31, v2, v0
	v_min_u32_e32 v0, v2, v0
	v_max_u32_e32 v2, v4, v3
	v_min_u32_e32 v3, v4, v3
	v_max_u32_e32 v4, v6, v1
	v_min_u32_e32 v1, v6, v1
	v_max_u32_e32 v6, v5, v19
	v_min_u32_e32 v5, v5, v19
	v_max_u32_e32 v19, v7, v18
	v_min_u32_e32 v7, v7, v18
	v_max_u32_e32 v18, v117, v17
	v_min_u32_e32 v17, v117, v17
	v_max_u32_e32 v117, v16, v20
	v_min_u32_e32 v16, v16, v20
	v_max_u32_e32 v20, v11, v22
	v_min_u32_e32 v11, v11, v22
	v_max_u32_e32 v22, v10, v21
	v_min_u32_e32 v10, v10, v21
	v_max_u32_e32 v21, v9, v23
	v_min_u32_e32 v9, v9, v23
	v_max_u32_e32 v23, v12, v8
	v_min_u32_e32 v8, v12, v8
	v_max_u32_e32 v12, v14, v27
	v_min_u32_e32 v14, v14, v27
	v_max_u32_e32 v27, v13, v24
	v_min_u32_e32 v13, v13, v24
	v_max_u32_e32 v24, v26, v25
	v_min_u32_e32 v25, v26, v25
	v_max_u32_e32 v26, v15, v28
	v_min_u32_e32 v15, v15, v28
	v_max_u32_e32 v28, v3, v30
	v_min_u32_e32 v3, v3, v30
	v_max_u32_e32 v30, v2, v29
	v_min_u32_e32 v2, v2, v29
	v_max_u32_e32 v29, v1, v31
	v_min_u32_e32 v1, v1, v31
	v_max_u32_e32 v31, v4, v0
	v_min_u32_e32 v0, v4, v0
	v_max_u32_e32 v4, v6, v18
	v_min_u32_e32 v6, v6, v18
	v_max_u32_e32 v18, v19, v117
	v_min_u32_e32 v19, v19, v117
	v_max_u32_e32 v117, v5, v17
	v_min_u32_e32 v5, v5, v17
	v_max_u32_e32 v17, v7, v16
	v_min_u32_e32 v7, v7, v16
	v_max_u32_e32 v16, v9, v11
; template <int N> DI void bitonic_sort_desc(unsigned (&v)[N]) {
; #pragma unroll
;     for (int k = 2; k <= N; k <<= 1)
; #pragma unroll
;         for (int j = k >> 1; j > 0; j >>= 1)
; #pragma unroll
;             for (int i = 0; i < N; ++i) { const int l = i ^ j; if (l > i) { if ((i & k) == 0) cswap(v[i], v[l]); else cswap(v[l], v[i]); } }
; }
; DI void topk_phase(unsigned char* smem_, const bf16_t* __restrict__ qp, const bf16_t* __restrict__ keys, int* __restrict__ eidx, float* __restrict__ gate) {
;     ...
;         for (int i = 0; i < 16; ++i) t16[i] = v[i];
;         merge_top16(t16, 1);
	v_min_u32_e32 v9, v9, v11
	v_max_u32_e32 v11, v8, v10
	v_min_u32_e32 v8, v8, v10
	v_max_u32_e32 v10, v21, v20
	v_min_u32_e32 v20, v21, v20
	v_max_u32_e32 v21, v23, v22
	v_min_u32_e32 v22, v23, v22
	v_max_u32_e32 v23, v12, v24
	v_min_u32_e32 v12, v12, v24
	v_max_u32_e32 v24, v27, v26
	v_min_u32_e32 v26, v27, v26
	v_max_u32_e32 v27, v14, v25
	v_min_u32_e32 v14, v14, v25
	v_max_u32_e32 v25, v13, v15
	v_min_u32_e32 v13, v13, v15
	v_max_u32_e32 v15, v1, v3
	v_min_u32_e32 v1, v1, v3
	v_max_u32_e32 v3, v0, v2
	v_min_u32_e32 v0, v0, v2
	v_max_u32_e32 v2, v29, v28
	v_min_u32_e32 v28, v29, v28
	v_max_u32_e32 v29, v31, v30
	v_min_u32_e32 v30, v31, v30
	v_max_u32_e32 v31, v4, v18
	v_min_u32_e32 v4, v4, v18
	v_max_u32_e32 v18, v6, v19
	v_min_u32_e32 v6, v6, v19
	v_max_u32_e32 v19, v117, v17
	v_min_u32_e32 v17, v117, v17
	v_max_u32_e32 v117, v5, v7
	v_min_u32_e32 v5, v5, v7
	v_max_u32_e32 v7, v8, v9
	v_min_u32_e32 v8, v8, v9
	v_max_u32_e32 v9, v11, v16
	v_min_u32_e32 v11, v11, v16
	v_max_u32_e32 v16, v22, v20
	v_min_u32_e32 v20, v22, v20
	v_max_u32_e32 v22, v21, v10
	v_min_u32_e32 v10, v21, v10
	v_max_u32_e32 v21, v23, v24
	v_min_u32_e32 v23, v23, v24
	v_max_u32_e32 v24, v12, v26
	v_min_u32_e32 v12, v12, v26
	v_max_u32_e32 v26, v27, v25
	v_min_u32_e32 v25, v27, v25
	v_max_u32_e32 v27, v14, v13
	v_min_u32_e32 v13, v14, v13
	v_max_u32_e32 v14, v0, v1
	v_min_u32_e32 v0, v0, v1
	v_max_u32_e32 v1, v3, v15
	v_min_u32_e32 v3, v3, v15
	v_max_u32_e32 v15, v30, v28
	v_min_u32_e32 v28, v30, v28
	v_max_u32_e32 v30, v29, v2
	v_min_u32_e32 v2, v29, v2
	v_max_u32_e32 v29, v31, v8
	v_min_u32_e32 v8, v31, v8
	v_max_u32_e32 v31, v4, v7
	v_min_u32_e32 v4, v4, v7
	v_max_u32_e32 v7, v18, v11
	v_min_u32_e32 v11, v18, v11
	v_max_u32_e32 v18, v6, v9
	v_min_u32_e32 v6, v6, v9
	v_max_u32_e32 v9, v19, v20
	v_min_u32_e32 v19, v19, v20
	v_max_u32_e32 v20, v17, v16
	v_min_u32_e32 v16, v17, v16
	v_max_u32_e32 v17, v117, v10
	v_min_u32_e32 v10, v117, v10
	v_max_u32_e32 v117, v5, v22
	v_min_u32_e32 v5, v5, v22
	v_max_u32_e32 v22, v0, v21
	v_min_u32_e32 v0, v0, v21
	v_max_u32_e32 v21, v14, v23
	v_min_u32_e32 v14, v14, v23
	v_max_u32_e32 v23, v3, v24
	v_min_u32_e32 v3, v3, v24
	v_max_u32_e32 v24, v1, v12
	v_min_u32_e32 v1, v1, v12
	v_max_u32_e32 v12, v28, v26
	v_min_u32_e32 v26, v28, v26
	v_max_u32_e32 v28, v15, v25
	v_min_u32_e32 v15, v15, v25
	v_max_u32_e32 v25, v2, v27
	v_min_u32_e32 v2, v2, v27
	v_max_u32_e32 v27, v30, v13
	v_min_u32_e32 v13, v30, v13
	v_max_u32_e32 v30, v29, v9
	v_min_u32_e32 v9, v29, v9
	v_max_u32_e32 v29, v31, v20
	v_min_u32_e32 v20, v31, v20
	v_max_u32_e32 v31, v7, v17
	v_min_u32_e32 v7, v7, v17
	v_max_u32_e32 v17, v18, v117
	v_min_u32_e32 v18, v18, v117
	v_max_u32_e32 v117, v8, v19
	v_min_u32_e32 v8, v8, v19
	v_max_u32_e32 v19, v4, v16
	v_min_u32_e32 v4, v4, v16
	v_max_u32_e32 v16, v11, v10
	v_min_u32_e32 v10, v11, v10
	v_max_u32_e32 v11, v6, v5
	v_min_u32_e32 v5, v6, v5
	v_max_u32_e32 v6, v26, v0
	v_min_u32_e32 v0, v26, v0
	v_max_u32_e32 v26, v15, v14
	v_min_u32_e32 v14, v15, v14
	v_max_u32_e32 v15, v2, v3
	v_min_u32_e32 v2, v2, v3
	v_max_u32_e32 v3, v13, v1
	v_min_u32_e32 v1, v13, v1
	v_max_u32_e32 v13, v12, v22
	v_min_u32_e32 v12, v12, v22
	v_max_u32_e32 v22, v28, v21
	v_min_u32_e32 v21, v28, v21
	v_max_u32_e32 v28, v25, v23
	v_min_u32_e32 v23, v25, v23
	v_max_u32_e32 v25, v27, v24
	v_min_u32_e32 v24, v27, v24
	v_max_u32_e32 v27, v30, v31
	v_min_u32_e32 v30, v30, v31
	v_max_u32_e32 v31, v29, v17
	v_min_u32_e32 v17, v29, v17
	v_max_u32_e32 v29, v9, v7
	v_min_u32_e32 v7, v9, v7
	v_max_u32_e32 v9, v20, v18
	v_min_u32_e32 v18, v20, v18
	v_max_u32_e32 v20, v117, v16
	v_min_u32_e32 v16, v117, v16
	v_max_u32_e32 v117, v19, v11
	v_min_u32_e32 v11, v19, v11
	v_max_u32_e32 v19, v8, v10
	v_min_u32_e32 v8, v8, v10
	v_max_u32_e32 v10, v4, v5
	v_min_u32_e32 v4, v4, v5
	v_max_u32_e32 v5, v2, v0
	v_min_u32_e32 v0, v2, v0
	v_max_u32_e32 v2, v1, v14
	v_min_u32_e32 v1, v1, v14
	v_max_u32_e32 v14, v15, v6
	v_min_u32_e32 v6, v15, v6
	v_max_u32_e32 v15, v3, v26
	v_min_u32_e32 v3, v3, v26
	v_max_u32_e32 v26, v23, v12
	v_min_u32_e32 v12, v23, v12
	v_max_u32_e32 v23, v24, v21
	v_min_u32_e32 v21, v24, v21
	v_max_u32_e32 v24, v28, v13
	v_min_u32_e32 v13, v28, v13
	v_max_u32_e32 v28, v25, v22
	v_min_u32_e32 v22, v25, v22
	v_min_u32_e32 v25, v27, v31
	v_min_u32_e32 v118, v30, v17
	v_min_u32_e32 v119, v29, v9
	v_min_u32_e32 v120, v7, v18
	v_min_u32_e32 v121, v20, v117
	v_min_u32_e32 v122, v16, v11
	v_min_u32_e32 v123, v19, v10
	v_min_u32_e32 v124, v8, v4
	v_min_u32_e32 v125, v1, v0
	v_min_u32_e32 v126, v2, v5
	v_min_u32_e32 v127, v3, v6
	v_min_u32_e32 v142, v15, v14
	v_min_u32_e32 v143, v21, v12
	v_min_u32_e32 v144, v23, v26
	v_min_u32_e32 v145, v22, v13
	v_min_u32_e32 v146, v28, v24
	v_max3_u32 v27, v27, v31, v125
	v_max3_u32 v0, v25, v1, v0
	v_max3_u32 v1, v30, v17, v126
	v_max3_u32 v2, v118, v2, v5
	v_max3_u32 v5, v29, v9, v127
	v_max3_u32 v3, v119, v3, v6
	v_max3_u32 v6, v7, v18, v142
	v_max3_u32 v7, v120, v15, v14
	v_max3_u32 v9, v20, v117, v143
	v_max3_u32 v12, v121, v21, v12
	v_max3_u32 v11, v16, v11, v144
	v_max3_u32 v14, v122, v23, v26
	v_max3_u32 v10, v19, v10, v145
	v_max3_u32 v13, v123, v22, v13
	v_max3_u32 v4, v8, v4, v146
	v_max3_u32 v8, v124, v28, v24
	v_max_u32_e32 v15, v27, v9
	v_min_u32_e32 v9, v27, v9
	v_max_u32_e32 v16, v0, v12
	v_min_u32_e32 v0, v0, v12
	v_max_u32_e32 v12, v1, v11
	v_min_u32_e32 v1, v1, v11
	v_max_u32_e32 v11, v2, v14
	v_min_u32_e32 v2, v2, v14
	v_max_u32_e32 v14, v5, v10
	v_min_u32_e32 v5, v5, v10
	v_max_u32_e32 v10, v3, v13
	v_min_u32_e32 v3, v3, v13
	v_max_u32_e32 v13, v6, v4
	v_min_u32_e32 v4, v6, v4
	v_max_u32_e32 v6, v7, v8
	v_min_u32_e32 v7, v7, v8
; DI void merge_top16(unsigned (&v)[16], int st) {
;     unsigned x[16];
; #pragma unroll
;     for (int i = 0; i < 16; ++i) x[i] = (unsigned)__shfl_xor((int)v[15 - i], st);
; #pragma unroll
;     for (int i = 0; i < 16; ++i) v[i] = max(v[i], x[i]);
; #pragma unroll
;     for (int j = 8; j > 0; j >>= 1)
; #pragma unroll
;         for (int i = 0; i < 16; ++i) { const int l = i ^ j; if (l > i) cswap(v[i], v[l]); }
; }
; DI void topk_phase(unsigned char* smem_, const bf16_t* __restrict__ qp, const bf16_t* __restrict__ keys, int* __restrict__ eidx, float* __restrict__ gate) {
;     ...
;         merge_top16(t16, 1);
;         merge_top16(t16, 2);
	v_max_u32_e32 v8, v15, v14
	v_min_u32_e32 v14, v15, v14
	v_max_u32_e32 v15, v16, v10
	v_min_u32_e32 v10, v16, v10
	v_max_u32_e32 v16, v12, v13
	v_min_u32_e32 v12, v12, v13
	v_max_u32_e32 v13, v11, v6
	v_min_u32_e32 v6, v11, v6
	v_max_u32_e32 v11, v9, v5
	v_min_u32_e32 v5, v9, v5
	v_max_u32_e32 v9, v0, v3
	v_min_u32_e32 v0, v0, v3
	v_max_u32_e32 v3, v1, v4
	v_min_u32_e32 v1, v1, v4
	v_max_u32_e32 v4, v2, v7
	v_min_u32_e32 v2, v2, v7
	v_max_u32_e32 v7, v8, v16
	v_min_u32_e32 v8, v8, v16
	v_max_u32_e32 v16, v15, v13
	v_min_u32_e32 v13, v15, v13
	v_max_u32_e32 v15, v14, v12
	v_min_u32_e32 v12, v14, v12
	v_max_u32_e32 v14, v10, v6
	v_min_u32_e32 v6, v10, v6
	v_max_u32_e32 v10, v11, v3
	v_min_u32_e32 v3, v11, v3
	v_max_u32_e32 v11, v9, v4
	v_min_u32_e32 v4, v9, v4
	v_max_u32_e32 v9, v5, v1
	v_min_u32_e32 v1, v5, v1
	v_max_u32_e32 v5, v0, v2
	v_min_u32_e32 v0, v0, v2
	v_max_u32_e32 v2, v7, v16
	v_min_u32_e32 v7, v7, v16
	v_max_u32_e32 v16, v8, v13
	v_min_u32_e32 v8, v8, v13
	v_max_u32_e32 v13, v15, v14
	v_min_u32_e32 v14, v15, v14
	v_max_u32_e32 v15, v12, v6
	v_min_u32_e32 v6, v12, v6
	v_max_u32_e32 v12, v10, v11
	v_min_u32_e32 v10, v10, v11
	v_max_u32_e32 v11, v3, v4
	v_min_u32_e32 v3, v3, v4
	v_max_u32_e32 v4, v9, v5
	v_min_u32_e32 v5, v9, v5
	v_max_u32_e32 v9, v1, v0
	v_min_u32_e32 v0, v1, v0
	s_nop 1
	v_mov_b32_dpp v1, v0 quad_perm:[1,0,3,2] row_mask:0xf bank_mask:0xf
	v_mov_b32_dpp v17, v9 quad_perm:[1,0,3,2] row_mask:0xf bank_mask:0xf
	v_mov_b32_dpp v18, v5 quad_perm:[1,0,3,2] row_mask:0xf bank_mask:0xf
	v_mov_b32_dpp v19, v4 quad_perm:[1,0,3,2] row_mask:0xf bank_mask:0xf
	v_mov_b32_dpp v20, v3 quad_perm:[1,0,3,2] row_mask:0xf bank_mask:0xf
	v_mov_b32_dpp v21, v11 quad_perm:[1,0,3,2] row_mask:0xf bank_mask:0xf
	v_mov_b32_dpp v22, v10 quad_perm:[1,0,3,2] row_mask:0xf bank_mask:0xf
	v_mov_b32_dpp v23, v12 quad_perm:[1,0,3,2] row_mask:0xf bank_mask:0xf
	v_mov_b32_dpp v24, v6 quad_perm:[1,0,3,2] row_mask:0xf bank_mask:0xf
	v_mov_b32_dpp v25, v15 quad_perm:[1,0,3,2] row_mask:0xf bank_mask:0xf
	v_mov_b32_dpp v26, v14 quad_perm:[1,0,3,2] row_mask:0xf bank_mask:0xf
	v_mov_b32_dpp v27, v13 quad_perm:[1,0,3,2] row_mask:0xf bank_mask:0xf
	v_mov_b32_dpp v28, v8 quad_perm:[1,0,3,2] row_mask:0xf bank_mask:0xf
	v_mov_b32_dpp v29, v16 quad_perm:[1,0,3,2] row_mask:0xf bank_mask:0xf
	v_mov_b32_dpp v30, v7 quad_perm:[1,0,3,2] row_mask:0xf bank_mask:0xf
	v_mov_b32_dpp v31, v2 quad_perm:[1,0,3,2] row_mask:0xf bank_mask:0xf
	s_waitcnt lgkmcnt(0)
	v_max_u32_e32 v1, v2, v1
	v_max_u32_e32 v2, v7, v17
	v_max_u32_e32 v7, v16, v18
	v_max_u32_e32 v8, v8, v19
	v_max_u32_e32 v13, v13, v20
	v_max_u32_e32 v14, v14, v21
	v_max_u32_e32 v15, v15, v22
	v_max_u32_e32 v6, v6, v23
	v_max_u32_e32 v12, v12, v24
	v_max_u32_e32 v10, v10, v25
	v_max_u32_e32 v11, v11, v26
	v_max_u32_e32 v3, v3, v27
	v_max_u32_e32 v4, v4, v28
	v_max_u32_e32 v5, v5, v29
	v_max_u32_e32 v9, v9, v30
	v_max_u32_e32 v0, v0, v31
	v_max_u32_e32 v16, v1, v12
	v_min_u32_e32 v1, v1, v12
	v_max_u32_e32 v12, v2, v10
	v_min_u32_e32 v2, v2, v10
	v_max_u32_e32 v10, v7, v11
	v_min_u32_e32 v7, v7, v11
	v_max_u32_e32 v11, v8, v3
	v_min_u32_e32 v3, v8, v3
	v_max_u32_e32 v8, v13, v4
	v_min_u32_e32 v4, v13, v4
	v_max_u32_e32 v13, v14, v5
	v_min_u32_e32 v5, v14, v5
	v_max_u32_e32 v14, v15, v9
	v_min_u32_e32 v9, v15, v9
	v_max_u32_e32 v15, v6, v0
	v_min_u32_e32 v0, v6, v0
	v_max_u32_e32 v6, v16, v8
	v_min_u32_e32 v8, v16, v8
	v_max_u32_e32 v16, v12, v13
	v_min_u32_e32 v12, v12, v13
	v_max_u32_e32 v13, v10, v14
	v_min_u32_e32 v10, v10, v14
	v_max_u32_e32 v14, v11, v15
	v_min_u32_e32 v11, v11, v15
	v_max_u32_e32 v15, v1, v4
	v_min_u32_e32 v1, v1, v4
	v_max_u32_e32 v4, v2, v5
	v_min_u32_e32 v2, v2, v5
	v_max_u32_e32 v5, v7, v9
	v_min_u32_e32 v7, v7, v9
	v_max_u32_e32 v9, v3, v0
	v_min_u32_e32 v0, v3, v0
	v_max_u32_e32 v3, v6, v13
	v_min_u32_e32 v6, v6, v13
	v_max_u32_e32 v13, v16, v14
	v_min_u32_e32 v14, v16, v14
	v_max_u32_e32 v16, v8, v10
	v_min_u32_e32 v8, v8, v10
	v_max_u32_e32 v10, v12, v11
	v_min_u32_e32 v11, v12, v11
	v_max_u32_e32 v12, v15, v5
	v_min_u32_e32 v5, v15, v5
	v_max_u32_e32 v15, v4, v9
	v_min_u32_e32 v4, v4, v9
	v_max_u32_e32 v9, v1, v7
	v_min_u32_e32 v1, v1, v7
	v_max_u32_e32 v7, v2, v0
	v_min_u32_e32 v0, v2, v0
	v_max_u32_e32 v2, v3, v13
	v_min_u32_e32 v3, v3, v13
	v_max_u32_e32 v13, v6, v14
	v_min_u32_e32 v6, v6, v14
	v_max_u32_e32 v14, v16, v10
	v_min_u32_e32 v10, v16, v10
	v_max_u32_e32 v16, v8, v11
	v_min_u32_e32 v8, v8, v11
	v_max_u32_e32 v11, v12, v15
	v_min_u32_e32 v12, v12, v15
	v_max_u32_e32 v15, v5, v4
	v_min_u32_e32 v17, v5, v4
	v_max_u32_e32 v18, v9, v7
	v_min_u32_e32 v19, v9, v7
	v_max_u32_e32 v20, v1, v0
	v_min_u32_e32 v21, v1, v0
	s_nop 1
	v_mov_b32_dpp v0, v21 quad_perm:[2,3,0,1] row_mask:0xf bank_mask:0xf
	v_mov_b32_dpp v1, v20 quad_perm:[2,3,0,1] row_mask:0xf bank_mask:0xf
	v_mov_b32_dpp v4, v19 quad_perm:[2,3,0,1] row_mask:0xf bank_mask:0xf
	v_mov_b32_dpp v5, v18 quad_perm:[2,3,0,1] row_mask:0xf bank_mask:0xf
	v_mov_b32_dpp v7, v17 quad_perm:[2,3,0,1] row_mask:0xf bank_mask:0xf
	v_mov_b32_dpp v9, v15 quad_perm:[2,3,0,1] row_mask:0xf bank_mask:0xf
	v_mov_b32_dpp v22, v12 quad_perm:[2,3,0,1] row_mask:0xf bank_mask:0xf
	v_mov_b32_dpp v23, v11 quad_perm:[2,3,0,1] row_mask:0xf bank_mask:0xf
	v_mov_b32_dpp v24, v8 quad_perm:[2,3,0,1] row_mask:0xf bank_mask:0xf
	v_mov_b32_dpp v25, v16 quad_perm:[2,3,0,1] row_mask:0xf bank_mask:0xf
	v_mov_b32_dpp v26, v10 quad_perm:[2,3,0,1] row_mask:0xf bank_mask:0xf
	v_mov_b32_dpp v27, v14 quad_perm:[2,3,0,1] row_mask:0xf bank_mask:0xf
	v_mov_b32_dpp v28, v6 quad_perm:[2,3,0,1] row_mask:0xf bank_mask:0xf
	v_mov_b32_dpp v29, v13 quad_perm:[2,3,0,1] row_mask:0xf bank_mask:0xf
	v_mov_b32_dpp v30, v3 quad_perm:[2,3,0,1] row_mask:0xf bank_mask:0xf
	v_mov_b32_dpp v31, v2 quad_perm:[2,3,0,1] row_mask:0xf bank_mask:0xf
	s_waitcnt lgkmcnt(0)
	v_max_u32_e32 v0, v2, v0
	v_max_u32_e32 v1, v3, v1
	v_max_u32_e32 v2, v13, v4
	v_max_u32_e32 v3, v6, v5
	v_max_u32_e32 v4, v14, v7
	v_max_u32_e32 v5, v10, v9
	v_max_u32_e32 v6, v16, v22
	v_max_u32_e32 v7, v8, v23
	v_max_u32_e32 v8, v11, v24
	v_max_u32_e32 v9, v12, v25
	v_max_u32_e32 v10, v15, v26
	v_max_u32_e32 v11, v17, v27
	v_max_u32_e32 v12, v18, v28
	v_max_u32_e32 v13, v19, v29
	v_max_u32_e32 v14, v20, v30
	v_max_u32_e32 v15, v21, v31
	v_max_u32_e32 v16, v0, v8
	v_max_u32_e32 v17, v1, v9
	v_max_u32_e32 v18, v2, v10
	v_max_u32_e32 v19, v3, v11
	v_max_u32_e32 v20, v4, v12
	v_max_u32_e32 v21, v5, v13
	v_max_u32_e32 v22, v6, v14
	v_max_u32_e32 v23, v7, v15
	s_and_saveexec_b64 s[16:17], s[4:5]
	s_cbranch_execz .LBB0_69
; DI void topk_phase(unsigned char* smem_, const bf16_t* __restrict__ qp, const bf16_t* __restrict__ keys, int* __restrict__ eidx, float* __restrict__ gate) {
;     ...
;         for (int i = 0; i < 16; ++i) if ((i >> 2) == q) { const int idx = 127 - (int)(t16[i] & 127u); SI[row * 32 + 16 * p + i] = idx; SV[row * 32 + 16 * p + i] = S[row * LDS_ + idx]; }
	v_max_u32_e32 v24, v16, v20
	v_max_u32_e32 v25, v18, v22
	v_max_u32_e32 v27, v17, v21
	v_max_u32_e32 v28, v19, v23
	v_min_u32_e32 v26, v24, v25
	v_min_u32_e32 v29, v27, v28
	v_max_u32_e32 v24, v24, v25
	v_max_u32_e32 v25, v27, v28
	v_min_u32_e32 v30, v26, v29
	v_max_u32_e32 v29, v26, v29
	v_min_u32_e32 v26, v24, v25
	v_max_u32_e32 v24, v24, v25
	v_xor_b32_e32 v25, -1, v26
	v_xor_b32_e32 v24, -1, v24
	v_and_b32_e32 v25, 0x7f, v25
	v_and_b32_e32 v24, 0x7f, v24
	v_lshl_add_u32 v26, v24, 2, v169
	v_lshl_add_u32 v27, v25, 2, v169
	ds_read_b32 v26, v26 offset:17408
	ds_read_b32 v27, v27 offset:17408
	v_xor_b32_e32 v28, -1, v29
	s_waitcnt lgkmcnt(0)
	ds_write_b64 v184, v[26:27] offset:53312
	v_xor_b32_e32 v26, -1, v30
	v_and_b32_e32 v27, 0x7f, v26
	v_and_b32_e32 v26, 0x7f, v28
	v_lshl_add_u32 v28, v26, 2, v169
	ds_write2_b64 v116, v[24:25], v[26:27] offset0:8 offset1:9
	v_lshl_add_u32 v24, v27, 2, v169
	ds_read_b32 v28, v28 offset:17408
	ds_read_b32 v29, v24 offset:17408
	s_waitcnt lgkmcnt(0)
	ds_write_b64 v184, v[28:29] offset:53320

; DI unsigned fkey(float f) { const unsigned u = __float_as_uint(f); return (u & 0x80000000u) ? ~u : (u | 0x80000000u); }
; DI void topk_phase(unsigned char* smem_, const bf16_t* __restrict__ qp, const bf16_t* __restrict__ keys, int* __restrict__ eidx, float* __restrict__ gate) {
;     ...
;     __syncthreads();
;     constexpr unsigned KT[13] = {0x03020100u, 0x07060504u, 0x0b0a0908u, 0x0f0e0d0cu, 0x13121110u, 0x17161514u, 0x23222120u, 0x32313024u, 0x42414033u, 0x61605150u, 0x90807170u, 0xd0c0b0a0u, 0x0000f0e0u};
;     unsigned c16[16];
; #pragma unroll
;     for (int i = 0; i < 13; ++i) {
;         const unsigned ab = (KT[i] >> (8 * q)) & 255u;
;         const float c = SV[row * 32 + (ab >> 4)] + SV[row * 32 + 16 + (ab & 15u)];
;         c16[i] = (fkey(c) & ~255u) | (255u - ab);
;     }
;     if (q >= 2) c16[12] = 0u;
;     c16[13] = 0u; c16[14] = 0u; c16[15] = 0u;
;     bitonic_sort_desc<16>(c16);
.LBB0_75:
	s_or_b64 exec, exec, s[16:17]
	s_waitcnt lgkmcnt(0)
	s_barrier
	ds_read_b96 v[0:2], v175 offset:53248
	ds_read_b32 v5, v186 offset:53312
	ds_read_b32 v3, v188 offset:53312
	ds_read_b32 v4, v175 offset:53312
	s_mov_b32 s16, 0xff61b1e6
	s_waitcnt lgkmcnt(3)
	v_mov_b32_e32 v7, v2
	s_waitcnt lgkmcnt(2)
	v_add_f32_e32 v2, v0, v5
	v_not_b32_e32 v5, v2
	v_or_b32_e32 v8, 0x80000000, v2
	v_cmp_gt_i32_e32 vcc, 0, v2
	v_mov_b32_e32 v6, v1
	v_or_b32_e32 v158, s24, v164
	v_cndmask_b32_e32 v2, v8, v5, vcc
	v_and_b32_e32 v2, 0xffffff00, v2
	v_bitop3_b32 v5, v2, s71, v185 bitop3:0x36
	ds_read_b32 v2, v190 offset:53312
	ds_read_b32 v9, v211 offset:53312
	ds_read_b32 v8, v213 offset:53312
	ds_read_b32 v10, v215 offset:53312
	ds_read_b32 v11, v217 offset:53312
	ds_read_b32 v13, v219 offset:53248
	ds_read_b32 v15, v220 offset:53312
	ds_read_b32 v12, v222 offset:53248
	s_waitcnt lgkmcnt(7)
	v_pk_add_f32 v[2:3], v[0:1], v[2:3] op_sel_hi:[0,1]
	v_not_b32_e32 v14, v3
	v_or_b32_e32 v16, 0x80000000, v3
	v_cmp_gt_i32_e32 vcc, 0, v3
	v_ashrrev_i32_e32 v159, 31, v158
	v_lshlrev_b64 v[158:159], 7, v[158:159]
	v_cndmask_b32_e32 v3, v16, v14, vcc
	v_and_b32_e32 v3, 0xffffff00, v3
	v_bitop3_b32 v16, v3, s71, v187 bitop3:0x36
	v_not_b32_e32 v3, v2
	v_or_b32_e32 v14, 0x80000000, v2
	v_cmp_gt_i32_e32 vcc, 0, v2
	v_lshl_or_b32 v158, s23, 4, v158
	v_lshlrev_b64 v[158:159], 2, v[158:159]
	v_cndmask_b32_e32 v2, v14, v3, vcc
	v_and_b32_e32 v2, 0xffffff00, v2
	v_bitop3_b32 v17, v2, s71, v189 bitop3:0x36
	v_mov_b32_e32 v2, v1
	v_mov_b32_e32 v3, v0
	s_waitcnt lgkmcnt(5)
	v_pk_add_f32 v[0:1], v[2:3], v[8:9]
	s_nop 0
	v_not_b32_e32 v2, v1
	v_or_b32_e32 v3, 0x80000000, v1
	v_cmp_gt_i32_e32 vcc, 0, v1
	s_nop 1
	v_cndmask_b32_e32 v1, v3, v2, vcc
	v_and_b32_e32 v1, 0xffffff00, v1
	v_bitop3_b32 v18, v1, s71, v191 bitop3:0x36
	v_not_b32_e32 v1, v0
	v_or_b32_e32 v2, 0x80000000, v0
	v_cmp_gt_i32_e32 vcc, 0, v0
	s_nop 1
	v_cndmask_b32_e32 v0, v2, v1, vcc
	v_and_b32_e32 v0, 0xffffff00, v0
	v_bitop3_b32 v19, v0, s71, v212 bitop3:0x36
	s_waitcnt lgkmcnt(3)
	v_pk_add_f32 v[0:1], v[6:7], v[10:11]
	s_nop 0
	v_not_b32_e32 v2, v0
	v_or_b32_e32 v3, 0x80000000, v0
	v_cmp_gt_i32_e32 vcc, 0, v0
	s_nop 1
	v_cndmask_b32_e32 v0, v3, v2, vcc
	v_and_b32_e32 v0, 0xffffff00, v0
	v_bitop3_b32 v10, v0, s71, v214 bitop3:0x36
	v_not_b32_e32 v0, v1
	v_or_b32_e32 v2, 0x80000000, v1
	v_cmp_gt_i32_e32 vcc, 0, v1
	s_nop 1
	v_cndmask_b32_e32 v0, v2, v0, vcc
	v_and_b32_e32 v0, 0xffffff00, v0
	v_bitop3_b32 v11, v0, s71, v216 bitop3:0x36
	ds_read_b32 v14, v223 offset:53312
	ds_read_b32 v1, v225 offset:53248
	ds_read_b32 v3, v226 offset:53312
	ds_read_b32 v0, v228 offset:53248
	ds_read_b32 v2, v229 offset:53312
	ds_read_b32 v7, v232 offset:53248
	ds_read_b32 v6, v233 offset:53248
	s_waitcnt lgkmcnt(6)
	v_pk_add_f32 v[8:9], v[12:13], v[14:15]
	s_waitcnt lgkmcnt(2)
	v_pk_add_f32 v[0:1], v[0:1], v[2:3]
	v_not_b32_e32 v12, v9
	v_or_b32_e32 v13, 0x80000000, v9
	v_cmp_gt_i32_e32 vcc, 0, v9
	v_not_b32_e32 v2, v1
	v_or_b32_e32 v3, 0x80000000, v1
	v_cndmask_b32_e32 v9, v13, v12, vcc
	v_not_b32_e32 v12, v8
	v_or_b32_e32 v13, 0x80000000, v8
	v_cmp_gt_i32_e32 vcc, 0, v8
	v_and_b32_e32 v9, 0xffffff00, v9
	v_bitop3_b32 v9, v9, s71, v218 bitop3:0x36
	v_cndmask_b32_e32 v8, v13, v12, vcc
	v_cmp_gt_i32_e32 vcc, 0, v1
	v_and_b32_e32 v8, 0xffffff00, v8
	v_bitop3_b32 v8, v8, s71, v221 bitop3:0x36
	v_cndmask_b32_e32 v1, v3, v2, vcc
	v_and_b32_e32 v1, 0xffffff00, v1
	v_bitop3_b32 v2, v1, s71, v224 bitop3:0x36
	v_not_b32_e32 v1, v0
	v_or_b32_e32 v3, 0x80000000, v0
	v_cmp_gt_i32_e32 vcc, 0, v0
	v_max_u32_e32 v12, v19, v10
	v_min_u32_e32 v10, v19, v10
	v_cndmask_b32_e32 v0, v3, v1, vcc
	v_and_b32_e32 v0, 0xffffff00, v0
	v_bitop3_b32 v3, v0, s71, v227 bitop3:0x36
	s_waitcnt lgkmcnt(0)
	v_pk_add_f32 v[0:1], v[6:7], v[4:5] op_sel_hi:[1,0]
	v_min_u32_e32 v7, v18, v17
	v_not_b32_e32 v4, v1
	v_or_b32_e32 v6, 0x80000000, v1
	v_cmp_gt_i32_e32 vcc, 0, v1
	v_max_u32_e32 v13, v9, v11
	v_min_u32_e32 v9, v9, v11
	v_cndmask_b32_e32 v1, v6, v4, vcc
	v_and_b32_e32 v1, 0xffffff00, v1
	v_not_b32_e32 v4, v0
	v_or_b32_e32 v6, 0x80000000, v0
	v_cmp_gt_i32_e32 vcc, 0, v0
	v_bitop3_b32 v1, v1, s71, v230 bitop3:0x36
	v_max_u32_e32 v11, v8, v2
	v_cndmask_b32_e32 v0, v6, v4, vcc
	v_and_b32_e32 v0, 0xffffff00, v0
	v_max_u32_e32 v4, v5, v16
	v_min_u32_e32 v5, v5, v16
	v_max_u32_e32 v6, v18, v17
	v_min_u32_e32 v2, v8, v2
	v_max_u32_e32 v8, v1, v3
	v_min_u32_e32 v1, v1, v3
	v_bitop3_b32 v0, v0, s71, v231 bitop3:0x36
	v_max_u32_e32 v3, v4, v7
	v_min_u32_e32 v4, v4, v7
	v_max_u32_e32 v7, v5, v6
	v_min_u32_e32 v5, v5, v6
	v_max_u32_e32 v6, v9, v12
	v_min_u32_e32 v9, v9, v12
	v_max_u32_e32 v12, v13, v10
	v_min_u32_e32 v10, v13, v10
	v_max_u32_e32 v13, v11, v1
	v_min_u32_e32 v1, v11, v1
	v_max_u32_e32 v11, v2, v8
	v_min_u32_e32 v2, v2, v8
	v_cndmask_b32_e64 v0, v0, 0, s[2:3]
	v_max_u32_e32 v8, v3, v7
	v_min_u32_e32 v3, v3, v7
	v_max_u32_e32 v7, v4, v5
	v_min_u32_e32 v4, v4, v5
	v_max_u32_e32 v5, v10, v9
	v_min_u32_e32 v9, v10, v9
	v_max_u32_e32 v10, v12, v6
	v_min_u32_e32 v6, v12, v6
	v_max_u32_e32 v12, v13, v11
	v_min_u32_e32 v11, v13, v11
	v_max_u32_e32 v13, v1, v2
	v_min_u32_e32 v1, v1, v2
	v_max_u32_e32 v2, v8, v9
	v_min_u32_e32 v8, v8, v9
	v_max_u32_e32 v9, v3, v5
	v_min_u32_e32 v3, v3, v5
	v_max_u32_e32 v5, v7, v6
	v_min_u32_e32 v6, v7, v6
	v_max_u32_e32 v7, v4, v10
	v_min_u32_e32 v4, v4, v10
	v_max_u32_e32 v10, v0, v1
	v_min_u32_e32 v0, v0, v1
	v_max_u32_e32 v1, v2, v5
	v_min_u32_e32 v2, v2, v5
	v_max_u32_e32 v5, v9, v7
	v_min_u32_e32 v7, v9, v7
	v_max_u32_e32 v9, v8, v6
	v_min_u32_e32 v6, v8, v6
	v_max_u32_e32 v8, v3, v4
	v_min_u32_e32 v3, v3, v4
	v_max_u32_e32 v4, v13, v12
; DI void merge_top16(unsigned (&v)[16], int st) {
;     unsigned x[16];
; #pragma unroll
;     for (int i = 0; i < 16; ++i) x[i] = (unsigned)__shfl_xor((int)v[15 - i], st);
; #pragma unroll
;     for (int i = 0; i < 16; ++i) v[i] = max(v[i], x[i]);
; #pragma unroll
;     for (int j = 8; j > 0; j >>= 1)
; #pragma unroll
;         for (int i = 0; i < 16; ++i) { const int l = i ^ j; if (l > i) cswap(v[i], v[l]); }
; }
; DI void topk_phase(unsigned char* smem_, const bf16_t* __restrict__ qp, const bf16_t* __restrict__ keys, int* __restrict__ eidx, float* __restrict__ gate) {
;     ...
;     bitonic_sort_desc<16>(c16);
;     merge_top16(c16, 1);
;     merge_top16(c16, 2);
	v_min_u32_e32 v12, v13, v12
	v_max_u32_e32 v13, v10, v11
	v_min_u32_e32 v10, v10, v11
	v_max_u32_e32 v11, v1, v5
	v_min_u32_e32 v1, v1, v5
	v_max_u32_e32 v5, v2, v7
	v_min_u32_e32 v2, v2, v7
	v_max_u32_e32 v7, v9, v8
	v_min_u32_e32 v8, v9, v8
	v_max_u32_e32 v9, v6, v3
	v_min_u32_e32 v3, v6, v3
	v_max_u32_e32 v6, v10, v12
	v_min_u32_e32 v10, v10, v12
	v_max_u32_e32 v12, v13, v4
	v_min_u32_e32 v4, v13, v4
	v_max_u32_e32 v13, v2, v0
	v_min_u32_e32 v0, v2, v0
	v_max_u32_e32 v2, v7, v10
	v_min_u32_e32 v7, v7, v10
	v_max_u32_e32 v10, v8, v6
	v_min_u32_e32 v6, v8, v6
	v_max_u32_e32 v8, v9, v4
	v_min_u32_e32 v4, v9, v4
	v_max_u32_e32 v9, v3, v12
	v_min_u32_e32 v3, v3, v12
	v_max_u32_e32 v12, v11, v2
	v_min_u32_e32 v2, v11, v2
	v_max_u32_e32 v11, v1, v10
	v_min_u32_e32 v1, v1, v10
	v_max_u32_e32 v10, v5, v8
	v_min_u32_e32 v5, v5, v8
	v_max_u32_e32 v8, v13, v9
	v_min_u32_e32 v9, v13, v9
	v_max_u32_e32 v13, v0, v3
	v_min_u32_e32 v0, v0, v3
	v_max_u32_e32 v3, v12, v10
	v_min_u32_e32 v10, v12, v10
	v_max_u32_e32 v12, v11, v8
	v_min_u32_e32 v8, v11, v8
	v_max_u32_e32 v11, v2, v5
	v_min_u32_e32 v2, v2, v5
	v_max_u32_e32 v5, v1, v9
	v_min_u32_e32 v1, v1, v9
	v_max_u32_e32 v9, v7, v4
	v_min_u32_e32 v4, v7, v4
	v_max_u32_e32 v7, v6, v13
	v_min_u32_e32 v6, v6, v13
	v_max_u32_e32 v13, v3, v12
	v_min_u32_e32 v3, v3, v12
	v_max_u32_e32 v12, v10, v8
	v_min_u32_e32 v8, v10, v8
	v_max_u32_e32 v10, v11, v5
	v_min_u32_e32 v5, v11, v5
	v_max_u32_e32 v11, v2, v1
	v_min_u32_e32 v1, v2, v1
	v_max_u32_e32 v2, v9, v7
	v_min_u32_e32 v7, v9, v7
	v_max_u32_e32 v9, v4, v6
	v_min_u32_e32 v4, v4, v6
	s_nop 1
	v_mov_b32_dpp v6, v0 quad_perm:[1,0,3,2] row_mask:0xf bank_mask:0xf
	v_mov_b32_dpp v14, v4 quad_perm:[1,0,3,2] row_mask:0xf bank_mask:0xf
	v_mov_b32_dpp v15, v9 quad_perm:[1,0,3,2] row_mask:0xf bank_mask:0xf
	v_mov_b32_dpp v16, v7 quad_perm:[1,0,3,2] row_mask:0xf bank_mask:0xf
	v_mov_b32_dpp v17, v2 quad_perm:[1,0,3,2] row_mask:0xf bank_mask:0xf
	v_mov_b32_dpp v18, v1 quad_perm:[1,0,3,2] row_mask:0xf bank_mask:0xf
	v_mov_b32_dpp v19, v11 quad_perm:[1,0,3,2] row_mask:0xf bank_mask:0xf
	v_mov_b32_dpp v20, v5 quad_perm:[1,0,3,2] row_mask:0xf bank_mask:0xf
	v_mov_b32_dpp v21, v10 quad_perm:[1,0,3,2] row_mask:0xf bank_mask:0xf
	v_mov_b32_dpp v22, v8 quad_perm:[1,0,3,2] row_mask:0xf bank_mask:0xf
	v_mov_b32_dpp v23, v12 quad_perm:[1,0,3,2] row_mask:0xf bank_mask:0xf
	v_mov_b32_dpp v24, v3 quad_perm:[1,0,3,2] row_mask:0xf bank_mask:0xf
	v_mov_b32_dpp v25, v13 quad_perm:[1,0,3,2] row_mask:0xf bank_mask:0xf
	s_waitcnt lgkmcnt(0)
	v_max_u32_e32 v6, v8, v6
	v_max_u32_e32 v8, v10, v14
	v_max_u32_e32 v5, v5, v15
	v_max_u32_e32 v10, v11, v16
	v_max_u32_e32 v1, v1, v17
	v_max_u32_e32 v2, v2, v18
	v_max_u32_e32 v7, v7, v19
	v_max_u32_e32 v9, v9, v20
	v_max_u32_e32 v4, v4, v21
	v_max_u32_e32 v0, v0, v22
	v_max_u32_e32 v11, v13, v2
	v_min_u32_e32 v2, v13, v2
	v_max_u32_e32 v13, v3, v7
	v_min_u32_e32 v3, v3, v7
	v_max_u32_e32 v7, v12, v9
	v_min_u32_e32 v9, v12, v9
	v_max_u32_e32 v12, v6, v4
	v_min_u32_e32 v4, v6, v4
	v_max_u32_e32 v6, v8, v0
	v_min_u32_e32 v0, v8, v0
	v_max_u32_e32 v8, v5, v23
	v_min_u32_e32 v5, v5, v23
	v_max_u32_e32 v14, v10, v24
	v_min_u32_e32 v10, v10, v24
	v_max_u32_e32 v15, v1, v25
	v_min_u32_e32 v1, v1, v25
	v_max_u32_e32 v16, v11, v6
	v_min_u32_e32 v6, v11, v6
	v_max_u32_e32 v11, v13, v8
	v_min_u32_e32 v8, v13, v8
	v_max_u32_e32 v13, v7, v14
	v_min_u32_e32 v7, v7, v14
	v_max_u32_e32 v14, v12, v15
	v_min_u32_e32 v12, v12, v15
	v_max_u32_e32 v15, v2, v0
	v_min_u32_e32 v0, v2, v0
	v_max_u32_e32 v2, v3, v5
	v_min_u32_e32 v3, v3, v5
	v_max_u32_e32 v5, v9, v10
	v_min_u32_e32 v9, v9, v10
	v_max_u32_e32 v10, v4, v1
	v_min_u32_e32 v1, v4, v1
	v_max_u32_e32 v4, v16, v13
	v_min_u32_e32 v13, v16, v13
	v_max_u32_e32 v16, v11, v14
	v_min_u32_e32 v11, v11, v14
	v_max_u32_e32 v14, v6, v7
	v_min_u32_e32 v6, v6, v7
	v_max_u32_e32 v7, v8, v12
	v_min_u32_e32 v8, v8, v12
	v_max_u32_e32 v12, v15, v5
	v_min_u32_e32 v5, v15, v5
	v_max_u32_e32 v15, v2, v10
	v_min_u32_e32 v2, v2, v10
	v_max_u32_e32 v10, v0, v9
	v_min_u32_e32 v0, v0, v9
	v_max_u32_e32 v9, v3, v1
	v_min_u32_e32 v1, v3, v1
	v_max_u32_e32 v3, v4, v16
	v_min_u32_e32 v4, v4, v16
	v_max_u32_e32 v16, v13, v11
	v_min_u32_e32 v11, v13, v11
	v_max_u32_e32 v13, v14, v7
	v_min_u32_e32 v7, v14, v7
	v_max_u32_e32 v14, v6, v8
	v_min_u32_e32 v6, v6, v8
	v_max_u32_e32 v8, v12, v15
	v_min_u32_e32 v12, v12, v15
	v_max_u32_e32 v15, v5, v2
	v_min_u32_e32 v2, v5, v2
	v_max_u32_e32 v5, v10, v9
	v_min_u32_e32 v9, v10, v9
	v_max_u32_e32 v10, v0, v1
	v_min_u32_e32 v0, v0, v1
	s_nop 1
	v_mov_b32_dpp v1, v0 quad_perm:[2,3,0,1] row_mask:0xf bank_mask:0xf
	v_mov_b32_dpp v17, v10 quad_perm:[2,3,0,1] row_mask:0xf bank_mask:0xf
	v_mov_b32_dpp v18, v9 quad_perm:[2,3,0,1] row_mask:0xf bank_mask:0xf
	v_mov_b32_dpp v19, v5 quad_perm:[2,3,0,1] row_mask:0xf bank_mask:0xf
	v_mov_b32_dpp v20, v2 quad_perm:[2,3,0,1] row_mask:0xf bank_mask:0xf
	v_mov_b32_dpp v21, v15 quad_perm:[2,3,0,1] row_mask:0xf bank_mask:0xf
	v_mov_b32_dpp v22, v12 quad_perm:[2,3,0,1] row_mask:0xf bank_mask:0xf
	v_mov_b32_dpp v23, v8 quad_perm:[2,3,0,1] row_mask:0xf bank_mask:0xf
	v_mov_b32_dpp v24, v6 quad_perm:[2,3,0,1] row_mask:0xf bank_mask:0xf
	v_mov_b32_dpp v25, v14 quad_perm:[2,3,0,1] row_mask:0xf bank_mask:0xf
	v_mov_b32_dpp v26, v7 quad_perm:[2,3,0,1] row_mask:0xf bank_mask:0xf
	v_mov_b32_dpp v27, v13 quad_perm:[2,3,0,1] row_mask:0xf bank_mask:0xf
	v_mov_b32_dpp v28, v11 quad_perm:[2,3,0,1] row_mask:0xf bank_mask:0xf
	v_mov_b32_dpp v29, v16 quad_perm:[2,3,0,1] row_mask:0xf bank_mask:0xf
	v_mov_b32_dpp v30, v4 quad_perm:[2,3,0,1] row_mask:0xf bank_mask:0xf
	v_mov_b32_dpp v31, v3 quad_perm:[2,3,0,1] row_mask:0xf bank_mask:0xf
	s_waitcnt lgkmcnt(0)
; DI void merge_top16(unsigned (&v)[16], int st) {
;     unsigned x[16];
; #pragma unroll
;     for (int i = 0; i < 16; ++i) x[i] = (unsigned)__shfl_xor((int)v[15 - i], st);
; #pragma unroll
;     for (int i = 0; i < 16; ++i) v[i] = max(v[i], x[i]);
; #pragma unroll
;     for (int j = 8; j > 0; j >>= 1)
; #pragma unroll
;         for (int i = 0; i < 16; ++i) { const int l = i ^ j; if (l > i) cswap(v[i], v[l]); }
; }
; DI void topk_phase(unsigned char* smem_, const bf16_t* __restrict__ qp, const bf16_t* __restrict__ keys, int* __restrict__ eidx, float* __restrict__ gate) {
;     ...
;     float bv[16]; int be[16]; float mx = -3.0e38f;
; #pragma unroll
;     for (int i = 0; i < 16; ++i) {
;         const int ab = 255 - (int)(c16[i] & 255u), a = ab >> 4, b = ab & 15;
;         bv[i] = SV[row * 32 + a] + SV[row * 32 + 16 + b];
;         be[i] = SI[row * 32 + a] * 128 + SI[row * 32 + 16 + b];
;         mx = fmaxf(mx, bv[i]);
;     }
	v_max_u32_e32 v1, v3, v1
	v_max_u32_e32 v3, v4, v17
	v_max_u32_e32 v4, v16, v18
	v_max_u32_e32 v11, v11, v19
	v_max_u32_e32 v13, v13, v20
	v_max_u32_e32 v7, v7, v21
	v_max_u32_e32 v14, v14, v22
	v_max_u32_e32 v6, v6, v23
	v_max_u32_e32 v8, v8, v24
	v_max_u32_e32 v12, v12, v25
	v_max_u32_e32 v15, v15, v26
	v_max_u32_e32 v2, v2, v27
	v_max_u32_e32 v5, v5, v28
	v_max_u32_e32 v9, v9, v29
	v_max_u32_e32 v10, v10, v30
	v_max_u32_e32 v0, v0, v31
	v_max_u32_e32 v16, v1, v8
	v_min_u32_e32 v1, v1, v8
	v_max_u32_e32 v8, v3, v12
	v_min_u32_e32 v3, v3, v12
	v_max_u32_e32 v12, v4, v15
	v_min_u32_e32 v4, v4, v15
	v_max_u32_e32 v15, v11, v2
	v_min_u32_e32 v2, v11, v2
	v_max_u32_e32 v11, v13, v5
	v_min_u32_e32 v5, v13, v5
	v_max_u32_e32 v13, v7, v9
	v_min_u32_e32 v7, v7, v9
	v_max_u32_e32 v9, v14, v10
	v_min_u32_e32 v10, v14, v10
	v_max_u32_e32 v14, v6, v0
	v_min_u32_e32 v0, v6, v0
	v_max_u32_e32 v6, v16, v11
	v_min_u32_e32 v11, v16, v11
	v_max_u32_e32 v16, v8, v13
	v_min_u32_e32 v8, v8, v13
	v_max_u32_e32 v13, v12, v9
	v_min_u32_e32 v9, v12, v9
	v_max_u32_e32 v12, v15, v14
	v_min_u32_e32 v14, v15, v14
	v_max_u32_e32 v15, v1, v5
	v_min_u32_e32 v1, v1, v5
	v_max_u32_e32 v5, v3, v7
	v_min_u32_e32 v3, v3, v7
	v_max_u32_e32 v7, v4, v10
	v_min_u32_e32 v4, v4, v10
	v_max_u32_e32 v10, v2, v0
	v_min_u32_e32 v0, v2, v0
	v_max_u32_e32 v2, v6, v13
	v_min_u32_e32 v6, v6, v13
	v_max_u32_e32 v13, v16, v12
	v_min_u32_e32 v12, v16, v12
	v_max_u32_e32 v16, v11, v9
	v_min_u32_e32 v9, v11, v9
	v_max_u32_e32 v11, v8, v14
	v_min_u32_e32 v8, v8, v14
	v_max_u32_e32 v14, v15, v7
	v_min_u32_e32 v7, v15, v7
	v_max_u32_e32 v15, v5, v10
	v_min_u32_e32 v5, v5, v10
	v_max_u32_e32 v10, v1, v4
	v_min_u32_e32 v1, v1, v4
	v_max_u32_e32 v4, v3, v0
	v_min_u32_e32 v0, v3, v0
	v_max_u32_e32 v3, v2, v13
	v_not_b32_e32 v17, v3
	v_min_u32_e32 v2, v2, v13
	v_max_u32_e32 v142, v1, v0
	v_min_u32_e32 v144, v1, v0
	v_lshrrev_b32_e32 v0, 4, v17
	v_not_b32_e32 v13, v2
	v_and_or_b32 v0, v0, 15, v174
	v_max_u32_e32 v18, v6, v12
	v_lshl_add_u32 v237, v0, 2, s19
	v_lshrrev_b32_e32 v0, 4, v13
	v_not_b32_e32 v19, v18
	v_and_or_b32 v0, v0, 15, v174
	v_min_u32_e32 v6, v6, v12
	v_bitop3_b32 v1, v3, 15, v3 bitop3:0xc
	v_lshl_add_u32 v239, v0, 2, s19
	v_lshrrev_b32_e32 v0, 4, v19
	v_not_b32_e32 v12, v6
	v_lshl_add_u32 v238, v1, 2, v184
	v_bitop3_b32 v1, v2, 15, v2 bitop3:0xc
	v_and_or_b32 v0, v0, 15, v174
	v_lshl_add_u32 v240, v1, 2, v175
	v_bitop3_b32 v1, v18, 15, v18 bitop3:0xc
	v_lshl_add_u32 v241, v0, 2, s19
	v_lshrrev_b32_e32 v0, 4, v12
	v_lshl_add_u32 v242, v1, 2, v184
	v_bitop3_b32 v1, v6, 15, v6 bitop3:0xc
	v_and_or_b32 v0, v0, 15, v174
	v_max_u32_e32 v30, v7, v5
	v_min_u32_e32 v116, v7, v5
	v_max_u32_e32 v120, v10, v4
	v_min_u32_e32 v124, v10, v4
	v_lshl_add_u32 v243, v0, 2, s19
	v_lshl_add_u32 v244, v1, 2, v175
	ds_read_b32 v0, v237 offset:53248
	ds_read_b32 v1, v238 offset:53312
	ds_read_b32 v2, v239 offset:53248
	ds_read_b32 v3, v240 offset:53312
	ds_read_b32 v4, v241 offset:53248
	ds_read_b32 v5, v242 offset:53312
	ds_read_b32 v6, v243 offset:53248
	ds_read_b32 v7, v244 offset:53312
	v_max_u32_e32 v20, v16, v11
	v_min_u32_e32 v11, v16, v11
	v_not_b32_e32 v16, v11
	s_waitcnt lgkmcnt(2)
	v_add_f32_e32 v148, v4, v5
	v_lshrrev_b32_e32 v5, 4, v16
	v_and_or_b32 v5, v5, 15, v174
	v_bitop3_b32 v10, v11, 15, v11 bitop3:0xc
	v_lshl_add_u32 v5, v5, 2, s19
	v_max_u32_e32 v22, v9, v8
	s_waitcnt lgkmcnt(0)
	v_add_f32_e32 v149, v6, v7
	ds_read2st64_b32 v[6:7], v5 offset0:208 offset1:240
	v_lshl_add_u32 v5, v10, 2, v175
	v_not_b32_e32 v23, v22
	v_add_u32_e32 v5, 64, v5
	ds_read2st64_b32 v[10:11], v5 offset0:208 offset1:240
	v_lshrrev_b32_e32 v5, 4, v23
	v_and_or_b32 v5, v5, 15, v174
	v_bitop3_b32 v12, v22, 15, v22 bitop3:0xc
	v_lshl_add_u32 v5, v5, 2, s19
	v_min_u32_e32 v8, v9, v8
	v_max_u32_e32 v24, v14, v15
	v_min_u32_e32 v26, v14, v15
	v_add_f32_e32 v146, v0, v1
	v_add_f32_e32 v147, v2, v3
	ds_read2st64_b32 v[14:15], v5 offset0:208 offset1:240
	v_lshl_add_u32 v5, v12, 2, v184
	v_not_b32_e32 v21, v20
	v_not_b32_e32 v9, v8
	v_max3_f32 v0, v146, s16, v147
	v_add_u32_e32 v5, 64, v5
	v_max3_f32 v4, v0, v148, v149
	v_lshrrev_b32_e32 v0, 4, v21
	v_bitop3_b32 v2, v20, 15, v20 bitop3:0xc
	ds_read2st64_b32 v[20:21], v5 offset0:208 offset1:240
	v_lshrrev_b32_e32 v5, 4, v9
	v_and_or_b32 v0, v0, 15, v174
	v_lshl_add_u32 v2, v2, 2, v184
	v_and_or_b32 v5, v5, 15, v174
	v_lshl_add_u32 v0, v0, 2, s19
	v_add_u32_e32 v2, 64, v2
	v_bitop3_b32 v8, v8, 15, v8 bitop3:0xc
	v_lshl_add_u32 v5, v5, 2, s19
	ds_read2st64_b32 v[0:1], v0 offset0:208 offset1:240
	ds_read2st64_b32 v[2:3], v2 offset0:208 offset1:240
	ds_read2st64_b32 v[28:29], v5 offset0:208 offset1:240
	v_lshl_add_u32 v5, v8, 2, v175
	v_add_u32_e32 v5, 64, v5
	v_not_b32_e32 v27, v26
	ds_read2st64_b32 v[118:119], v5 offset0:208 offset1:240
	v_lshrrev_b32_e32 v13, 4, v27
	v_and_or_b32 v13, v13, 15, v174
	s_waitcnt lgkmcnt(2)
	v_add_f32_e32 v0, v0, v2
	v_add_f32_e32 v2, v6, v10
	v_add_f32_e32 v6, v14, v20
	v_bitop3_b32 v14, v26, 15, v26 bitop3:0xc
	v_lshl_add_u32 v13, v13, 2, s19
	ds_read2st64_b32 v[16:17], v13 offset0:208 offset1:240
	v_lshl_add_u32 v13, v14, 2, v175
	v_not_b32_e32 v25, v24
	v_not_b32_e32 v31, v30
	v_max3_f32 v4, v4, v0, v2
	s_waitcnt lgkmcnt(1)
; DI void topk_phase(unsigned char* smem_, const bf16_t* __restrict__ qp, const bf16_t* __restrict__ keys, int* __restrict__ eidx, float* __restrict__ gate) {
;     ...
;     float bv[16]; int be[16]; float mx = -3.0e38f;
; #pragma unroll
;     for (int i = 0; i < 16; ++i) {
;         const int ab = 255 - (int)(c16[i] & 255u), a = ab >> 4, b = ab & 15;
;         bv[i] = SV[row * 32 + a] + SV[row * 32 + 16 + b];
;         be[i] = SI[row * 32 + a] * 128 + SI[row * 32 + 16 + b];
;         mx = fmaxf(mx, bv[i]);
;     }
;     float sum = 0.f, ex[16];
; #pragma unroll
;     for (int i = 0; i < 16; ++i) { ex[i] = __expf(bv[i] - mx); sum += ex[i]; }
;     const float inv = 1.f / sum;
;     const size_t ob = (size_t)(tok0 + row) * 128 + h * 16;
; #pragma unroll
;     for (int i = 0; i < 16; ++i) if ((i >> 2) == q) { eidx[ob + i] = be[i]; gate[ob + i] = ex[i] * inv; }
	v_add_f32_e32 v10, v28, v118
	v_add_u32_e32 v13, 64, v13
	v_max3_f32 v12, v4, v6, v10
	v_lshrrev_b32_e32 v4, 4, v25
	v_bitop3_b32 v8, v24, 15, v24 bitop3:0xc
	ds_read2st64_b32 v[22:23], v13 offset0:208 offset1:240
	v_lshrrev_b32_e32 v13, 4, v31
	v_and_or_b32 v4, v4, 15, v174
	v_lshl_add_u32 v8, v8, 2, v184
	v_and_or_b32 v13, v13, 15, v174
	v_lshl_add_u32 v4, v4, 2, s19
	v_add_u32_e32 v8, 64, v8
	v_bitop3_b32 v14, v30, 15, v30 bitop3:0xc
	v_lshl_add_u32 v13, v13, 2, s19
	ds_read2st64_b32 v[4:5], v4 offset0:208 offset1:240
	ds_read2st64_b32 v[8:9], v8 offset0:208 offset1:240
	ds_read2st64_b32 v[24:25], v13 offset0:208 offset1:240
	v_lshl_add_u32 v13, v14, 2, v184
	v_not_b32_e32 v117, v116
	v_add_u32_e32 v13, 64, v13
	ds_read2st64_b32 v[30:31], v13 offset0:208 offset1:240
	v_lshrrev_b32_e32 v13, 4, v117
	v_and_or_b32 v13, v13, 15, v174
	v_not_b32_e32 v125, v124
	v_bitop3_b32 v14, v116, 15, v116 bitop3:0xc
	v_lshl_add_u32 v13, v13, 2, s19
	ds_read2st64_b32 v[122:123], v13 offset0:208 offset1:240
	v_lshl_add_u32 v13, v14, 2, v175
	s_waitcnt lgkmcnt(3)
	v_add_f32_e32 v4, v4, v8
	v_add_f32_e32 v8, v16, v22
	v_lshrrev_b32_e32 v22, 4, v125
	v_add_u32_e32 v13, 64, v13
	v_and_or_b32 v22, v22, 15, v174
	ds_read2st64_b32 v[126:127], v13 offset0:208 offset1:240
	s_waitcnt lgkmcnt(2)
	v_add_f32_e32 v14, v24, v30
	v_bitop3_b32 v24, v124, 15, v124 bitop3:0xc
	v_lshl_add_u32 v22, v22, 2, s19
	ds_read2st64_b32 v[26:27], v22 offset0:208 offset1:240
	v_lshl_add_u32 v22, v24, 2, v175
	v_not_b32_e32 v143, v142
	v_add_u32_e32 v22, 64, v22
	ds_read2st64_b32 v[116:117], v22 offset0:208 offset1:240
	v_lshrrev_b32_e32 v22, 4, v143
	v_and_or_b32 v22, v22, 15, v174
	v_not_b32_e32 v121, v120
	v_max3_f32 v12, v12, v4, v8
	s_waitcnt lgkmcnt(2)
	v_add_f32_e32 v16, v122, v126
	v_bitop3_b32 v24, v142, 15, v142 bitop3:0xc
	v_lshl_add_u32 v22, v22, 2, s19
	v_max3_f32 v20, v12, v14, v16
	v_lshrrev_b32_e32 v12, 4, v121
	v_bitop3_b32 v18, v120, 15, v120 bitop3:0xc
	ds_read2st64_b32 v[120:121], v22 offset0:208 offset1:240
	v_lshl_add_u32 v22, v24, 2, v184
	v_not_b32_e32 v145, v144
	v_add_u32_e32 v22, 64, v22
	ds_read2st64_b32 v[124:125], v22 offset0:208 offset1:240
	v_lshrrev_b32_e32 v22, 4, v145
	v_and_or_b32 v22, v22, 15, v174
	v_and_or_b32 v12, v12, 15, v174
	v_lshl_add_u32 v18, v18, 2, v184
	v_bitop3_b32 v24, v144, 15, v144 bitop3:0xc
	v_lshl_add_u32 v22, v22, 2, s19
	v_lshl_add_u32 v12, v12, 2, s19
	v_add_u32_e32 v18, 64, v18
	ds_read2st64_b32 v[142:143], v22 offset0:208 offset1:240
	v_lshl_add_u32 v22, v24, 2, v175
	ds_read2st64_b32 v[12:13], v12 offset0:208 offset1:240
	ds_read2st64_b32 v[18:19], v18 offset0:208 offset1:240
	v_add_u32_e32 v22, 64, v22
	ds_read2st64_b32 v[144:145], v22 offset0:208 offset1:240
	s_waitcnt lgkmcnt(4)
	v_add_f32_e32 v22, v120, v124
	s_waitcnt lgkmcnt(1)
	v_add_f32_e32 v12, v12, v18
	v_add_f32_e32 v18, v26, v116
	v_max3_f32 v20, v20, v12, v18
	s_waitcnt lgkmcnt(0)
	v_add_f32_e32 v24, v142, v144
	v_max3_f32 v20, v20, v22, v24
	v_sub_f32_e32 v26, v146, v20
	v_mul_f32_e32 v26, 0x3fb8aa3b, v26
	v_exp_f32_e32 v160, v26
	v_sub_f32_e32 v26, v147, v20
	v_sub_f32_e32 v0, v0, v20
	v_mul_f32_e32 v26, 0x3fb8aa3b, v26
	v_mul_f32_e32 v0, 0x3fb8aa3b, v0
	v_exp_f32_e32 v161, v26
	v_sub_f32_e32 v26, v148, v20
	v_exp_f32_e32 v154, v0
	v_sub_f32_e32 v0, v2, v20
	v_sub_f32_e32 v2, v4, v20
	v_mul_f32_e32 v26, 0x3fb8aa3b, v26
	v_mul_f32_e32 v2, 0x3fb8aa3b, v2
	v_exp_f32_e32 v162, v26
	v_sub_f32_e32 v26, v149, v20
	v_exp_f32_e32 v150, v2
	v_sub_f32_e32 v2, v8, v20
	v_mul_f32_e32 v26, 0x3fb8aa3b, v26
	v_mul_f32_e32 v0, 0x3fb8aa3b, v0
	v_mul_f32_e32 v2, 0x3fb8aa3b, v2
	v_exp_f32_e32 v163, v26
	v_exp_f32_e32 v155, v0
	v_sub_f32_e32 v0, v6, v20
	v_exp_f32_e32 v151, v2
	v_sub_f32_e32 v2, v14, v20
	v_add_f32_e32 v26, 0, v160
	v_mul_f32_e32 v0, 0x3fb8aa3b, v0
	v_mul_f32_e32 v2, 0x3fb8aa3b, v2
	v_add_f32_e32 v26, v161, v26
	v_exp_f32_e32 v156, v0
	v_sub_f32_e32 v0, v10, v20
	v_exp_f32_e32 v152, v2
	v_sub_f32_e32 v2, v16, v20
	v_add_f32_e32 v26, v162, v26
	v_mul_f32_e32 v0, 0x3fb8aa3b, v0
	v_mul_f32_e32 v2, 0x3fb8aa3b, v2
	v_add_f32_e32 v26, v163, v26
	v_exp_f32_e32 v157, v0
	v_exp_f32_e32 v153, v2
	v_sub_f32_e32 v2, v12, v20
	v_add_f32_e32 v0, v154, v26
	v_mul_f32_e32 v2, 0x3fb8aa3b, v2
	v_add_f32_e32 v0, v155, v0
	v_exp_f32_e32 v146, v2
	v_sub_f32_e32 v2, v18, v20
	v_add_f32_e32 v0, v156, v0
	v_mul_f32_e32 v2, 0x3fb8aa3b, v2
	v_add_f32_e32 v0, v157, v0
	v_exp_f32_e32 v147, v2
	v_sub_f32_e32 v2, v22, v20
	v_add_f32_e32 v0, v150, v0
	v_mul_f32_e32 v2, 0x3fb8aa3b, v2
	v_add_f32_e32 v0, v151, v0
	v_exp_f32_e32 v148, v2
	v_sub_f32_e32 v2, v24, v20
	v_add_f32_e32 v0, v152, v0
	v_mul_f32_e32 v2, 0x3fb8aa3b, v2
	v_add_f32_e32 v0, v153, v0
	v_exp_f32_e32 v149, v2
	v_add_f32_e32 v0, v146, v0
	v_add_f32_e32 v0, v147, v0
	v_add_f32_e32 v0, v148, v0
	v_add_f32_e32 v0, v149, v0
	v_div_scale_f32 v2, s[16:17], v0, v0, 1.0
	v_rcp_f32_e32 v4, v2
	s_nop 0
	v_fma_f32 v6, -v2, v4, 1.0
	v_fmac_f32_e32 v4, v6, v4
	v_div_scale_f32 v6, vcc, 1.0, v0, 1.0
	v_mul_f32_e32 v8, v6, v4
	v_fma_f32 v10, -v2, v8, v6
	v_fmac_f32_e32 v8, v10, v4
	v_fma_f32 v2, -v2, v8, v6
	v_div_fmas_f32 v2, v2, v4, v8
	v_div_fixup_f32 v0, v2, v0, 1.0
	s_and_saveexec_b64 s[16:17], s[4:5]
	s_cbranch_execnz .LBB0_79
	s_or_b64 exec, exec, s[16:17]
	s_and_saveexec_b64 s[16:17], s[6:7]
	s_cbranch_execnz .LBB0_80
